# GEMM K-loop priority 3 held from DMA issue through the DMA-complete wait (dropped to 0 just before the hand-over barrier)
# baseline (speedup 1.0000x reference)
; template <int MI, bool SWAP, bool F8 = false>
; __device__ __forceinline__ void gemm_core(const bf16_t* __restrict__ A, int lda, const bf16_t* __restrict__ B, int ldb,
;                                           int K, char* smem, f32x4 (&acc)[MI][4]) {
;     ...
;   for (int kt = 0; kt < nk; ++kt) {
;     __syncthreads();
; #pragma unroll
;     for (int i = 0; i < MI; ++i) *(u32x4*)(smem + woff + i * 4096) = ra[i];
; #pragma unroll
;     for (int i = 0; i < 4; ++i) *(u32x4*)(smem + 32768 + woff + i * 4096) = rb[i];
;     __syncthreads();
;     if (kt + 1 < nk) {
; #pragma unroll
;       for (int i = 0; i < MI; ++i) ra[i] = *(const u32x4*)(ap + (size_t)(32 * i) * lda + (kt + 1) * 64);
; #pragma unroll
;       for (int i = 0; i < 4; ++i) rb[i] = *(const u32x4*)(bp + (size_t)(32 * i) * ldb + (kt + 1) * 64);
;     }
;     if (F8) {
;       const int c0 = (g ^ (li & 7)) << 4, c1 = ((4 + g) ^ (li & 7)) << 4;
;       i32x8 wf8[4];
; #pragma unroll
;       for (int j = 0; j < 4; ++j) {
;         const char* rp = smem + wrow + ((j & 1) * 16 + (j >> 1) * 64) * 128;
;         const u32x4 lo = *(const u32x4*)(rp + c0), hi = *(const u32x4*)(rp + c1);
;         wf8[j] = (i32x8){(int)lo.x, (int)lo.y, (int)lo.z, (int)lo.w, (int)hi.x, (int)hi.y, (int)hi.z, (int)hi.w};
;       }
; #pragma unroll
;       for (int i = 0; i < MI; ++i) {
;         const char* rp = smem + xrow + i * 2048;
;         const u32x4 lo = *(const u32x4*)(rp + c0), hi = *(const u32x4*)(rp + c1);
;         const i32x8 xf8 = {(int)lo.x, (int)lo.y, (int)lo.z, (int)lo.w, (int)hi.x, (int)hi.y, (int)hi.z, (int)hi.w};
; #pragma unroll
;         for (int j = 0; j < 4; ++j)
;           acc[i][j] = __builtin_amdgcn_mfma_scale_f32_16x16x128_f8f6f4(wf8[j], xf8, acc[i][j], 0, 0, 0, 0x77777777, 0, 0x7f7f7f7f);
;       }
;     } else {
; #pragma unroll
;     for (int kk = 0; kk < 2; ++kk) {
;       const int ch = ((kk * 4 + g) ^ (li & 7)) << 4;
;       bf16x8 xf[MI], wf[4];
; #pragma unroll
;       for (int j = 0; j < 4; ++j) wf[j] = *(const bf16x8*)(smem + wrow + ((j & 1) * 16 + (j >> 1) * 64) * 128 + ch);
; #pragma unroll
;       for (int i = 0; i < MI; ++i) xf[i] = *(const bf16x8*)(smem + xrow + i * 2048 + ch);
; #pragma unroll
;       for (int i = 0; i < MI; ++i)
; #pragma unroll
;         for (int j = 0; j < 4; ++j) {
.LBB0_120:
	s_barrier
	s_setprio 3
	s_mov_b32 m0, s62
	s_nop 0
	global_load_lds_dwordx4 v252, s[56:57]
	s_add_u32 m0, s62, 0x1000
	s_nop 0
	global_load_lds_dwordx4 v253, s[56:57]
	s_add_u32 s56, s56, 0x20000
	s_addc_u32 s57, s57, 0
	s_add_u32 m0, s62, 0x2000
	s_nop 0
	global_load_lds_dwordx4 v252, s[56:57]
	s_add_u32 m0, s62, 0x3000
	s_nop 0
	global_load_lds_dwordx4 v253, s[56:57]
	s_add_u32 s56, s56, 0x20000
	s_addc_u32 s57, s57, 0
	s_add_u32 m0, s62, 0x4000
	s_nop 0
	global_load_lds_dwordx4 v252, s[56:57]
	s_add_u32 m0, s62, 0x5000
	s_nop 0
	global_load_lds_dwordx4 v253, s[56:57]
	s_add_u32 s56, s56, 0x20000
	s_addc_u32 s57, s57, 0
	s_add_u32 m0, s62, 0x6000
	s_nop 0
	global_load_lds_dwordx4 v252, s[56:57]
	s_add_u32 m0, s62, 0x7000
	s_nop 0
	global_load_lds_dwordx4 v253, s[56:57]
	s_sub_u32 s56, s56, 0x60000
	s_subb_u32 s57, s57, 0
	s_add_u32 m0, s62, 0x8000
	s_nop 0
	global_load_lds_dwordx4 v252, s[58:59]
	s_add_u32 m0, s62, 0x9000
	s_nop 0
	global_load_lds_dwordx4 v253, s[58:59]
	s_add_u32 s58, s58, 0x20000
	s_addc_u32 s59, s59, 0
	s_add_u32 m0, s62, 0xa000
	s_nop 0
	global_load_lds_dwordx4 v252, s[58:59]
	s_add_u32 m0, s62, 0xb000
	s_nop 0
	global_load_lds_dwordx4 v253, s[58:59]
	s_sub_u32 s58, s58, 0x20000
	s_subb_u32 s59, s59, 0
	v_add_u32_e32 v252, 0x80, v252
	v_add_u32_e32 v253, 0x80, v253
	s_waitcnt vmcnt(0)
	s_setprio 0
	s_barrier
	ds_read_b128 v[148:151], v215 offset:32768
	ds_read_b128 v[152:155], v215 offset:34816
	ds_read_b128 v[156:159], v213
	ds_read_b128 v[160:163], v213 offset:2048
	ds_read_b128 v[164:167], v215 offset:40960
	ds_read_b128 v[168:171], v215 offset:43008
	s_waitcnt lgkmcnt(3)
	v_mfma_f32_16x16x32_bf16 v[140:143], v[148:151], v[156:159], v[140:143]
	v_mfma_f32_16x16x32_bf16 v[136:139], v[152:155], v[156:159], v[136:139]
	s_waitcnt lgkmcnt(1)
	v_mfma_f32_16x16x32_bf16 v[132:135], v[164:167], v[156:159], v[132:135]
	s_waitcnt lgkmcnt(0)
	v_mfma_f32_16x16x32_bf16 v[128:131], v[168:171], v[156:159], v[128:131]
	v_mfma_f32_16x16x32_bf16 v[124:127], v[148:151], v[160:163], v[124:127]
	v_mfma_f32_16x16x32_bf16 v[120:123], v[152:155], v[160:163], v[120:123]
	v_mfma_f32_16x16x32_bf16 v[116:119], v[164:167], v[160:163], v[116:119]
	v_mfma_f32_16x16x32_bf16 v[104:107], v[168:171], v[160:163], v[104:107]
	ds_read_b128 v[156:159], v213 offset:4096
	ds_read_b128 v[160:163], v213 offset:6144
	s_waitcnt lgkmcnt(1)
	v_mfma_f32_16x16x32_bf16 v[88:91], v[148:151], v[156:159], v[88:91]
	v_mfma_f32_16x16x32_bf16 v[84:87], v[152:155], v[156:159], v[84:87]
	v_mfma_f32_16x16x32_bf16 v[80:83], v[164:167], v[156:159], v[80:83]
	v_mfma_f32_16x16x32_bf16 v[76:79], v[168:171], v[156:159], v[76:79]
	s_waitcnt lgkmcnt(0)
	v_mfma_f32_16x16x32_bf16 v[72:75], v[148:151], v[160:163], v[72:75]
	v_mfma_f32_16x16x32_bf16 v[68:71], v[152:155], v[160:163], v[68:71]
	v_mfma_f32_16x16x32_bf16 v[64:67], v[164:167], v[160:163], v[64:67]
	v_mfma_f32_16x16x32_bf16 v[60:63], v[168:171], v[160:163], v[60:63]
	ds_read_b128 v[156:159], v213 offset:8192
	ds_read_b128 v[160:163], v213 offset:10240
	s_waitcnt lgkmcnt(1)
	v_mfma_f32_16x16x32_bf16 v[44:47], v[148:151], v[156:159], v[44:47]
	v_mfma_f32_16x16x32_bf16 v[40:43], v[152:155], v[156:159], v[40:43]
	v_mfma_f32_16x16x32_bf16 v[36:39], v[164:167], v[156:159], v[36:39]
	v_mfma_f32_16x16x32_bf16 v[32:35], v[168:171], v[156:159], v[32:35]
	s_waitcnt lgkmcnt(0)
	v_mfma_f32_16x16x32_bf16 v[28:31], v[148:151], v[160:163], v[28:31]
	v_mfma_f32_16x16x32_bf16 v[24:27], v[152:155], v[160:163], v[24:27]
	v_mfma_f32_16x16x32_bf16 v[20:23], v[164:167], v[160:163], v[20:23]
	v_mfma_f32_16x16x32_bf16 v[52:55], v[168:171], v[160:163], v[52:55]
	ds_read_b128 v[156:159], v213 offset:12288
	ds_read_b128 v[160:163], v213 offset:14336
	ds_read_b128 v[172:175], v206 offset:32768
	ds_read_b128 v[180:183], v206 offset:34816
	s_waitcnt lgkmcnt(3)
	v_mfma_f32_16x16x32_bf16 v[48:51], v[148:151], v[156:159], v[48:51]
	v_mfma_f32_16x16x32_bf16 v[56:59], v[152:155], v[156:159], v[56:59]
	s_waitcnt lgkmcnt(2)
	v_mfma_f32_16x16x32_bf16 v[100:103], v[148:151], v[160:163], v[100:103]
	v_mfma_f32_16x16x32_bf16 v[96:99], v[152:155], v[160:163], v[96:99]
	ds_read_b128 v[148:151], v0
	ds_read_b128 v[152:155], v0 offset:2048
	ds_read_b128 v[192:195], v206 offset:40960
	ds_read_b128 v[196:199], v206 offset:43008
	s_waitcnt lgkmcnt(3)
	v_mfma_f32_16x16x32_bf16 v[140:143], v[172:175], v[148:151], v[140:143]
	v_mfma_f32_16x16x32_bf16 v[136:139], v[180:183], v[148:151], v[136:139]
	s_waitcnt lgkmcnt(1)
	v_mfma_f32_16x16x32_bf16 v[132:135], v[192:195], v[148:151], v[132:135]
	s_waitcnt lgkmcnt(0)
	v_mfma_f32_16x16x32_bf16 v[128:131], v[196:199], v[148:151], v[128:131]
	v_mfma_f32_16x16x32_bf16 v[124:127], v[172:175], v[152:155], v[124:127]
	v_mfma_f32_16x16x32_bf16 v[120:123], v[180:183], v[152:155], v[120:123]
	v_mfma_f32_16x16x32_bf16 v[116:119], v[192:195], v[152:155], v[116:119]
	v_mfma_f32_16x16x32_bf16 v[104:107], v[196:199], v[152:155], v[104:107]
	ds_read_b128 v[148:151], v0 offset:4096
	ds_read_b128 v[152:155], v0 offset:6144
	v_mfma_f32_16x16x32_bf16 v[112:115], v[164:167], v[156:159], v[112:115]
	v_mfma_f32_16x16x32_bf16 v[92:95], v[164:167], v[160:163], v[92:95]
	v_mfma_f32_16x16x32_bf16 v[108:111], v[168:171], v[156:159], v[108:111]
	v_mfma_f32_16x16x32_bf16 v[144:147], v[168:171], v[160:163], v[144:147]
	s_waitcnt lgkmcnt(0)
; template <int MI, bool SWAP, bool F8 = false>
; __device__ __forceinline__ void gemm_core(const bf16_t* __restrict__ A, int lda, const bf16_t* __restrict__ B, int ldb,
;                                           int K, char* smem, f32x4 (&acc)[MI][4]) {
;     ...
;   for (int kt = 0; kt < nk; ++kt) {
;     __syncthreads();
; #pragma unroll
;     for (int i = 0; i < MI; ++i) *(u32x4*)(smem + woff + i * 4096) = ra[i];
; #pragma unroll
;     for (int i = 0; i < 4; ++i) *(u32x4*)(smem + 32768 + woff + i * 4096) = rb[i];
;     __syncthreads();
;     if (kt + 1 < nk) {
; #pragma unroll
;       for (int i = 0; i < MI; ++i) ra[i] = *(const u32x4*)(ap + (size_t)(32 * i) * lda + (kt + 1) * 64);
; #pragma unroll
;       for (int i = 0; i < 4; ++i) rb[i] = *(const u32x4*)(bp + (size_t)(32 * i) * ldb + (kt + 1) * 64);
;     }
;     if (F8) {
;       const int c0 = (g ^ (li & 7)) << 4, c1 = ((4 + g) ^ (li & 7)) << 4;
;       i32x8 wf8[4];
; #pragma unroll
;       for (int j = 0; j < 4; ++j) {
;         const char* rp = smem + wrow + ((j & 1) * 16 + (j >> 1) * 64) * 128;
;         const u32x4 lo = *(const u32x4*)(rp + c0), hi = *(const u32x4*)(rp + c1);
;         wf8[j] = (i32x8){(int)lo.x, (int)lo.y, (int)lo.z, (int)lo.w, (int)hi.x, (int)hi.y, (int)hi.z, (int)hi.w};
;       }
; #pragma unroll
;       for (int i = 0; i < MI; ++i) {
;         const char* rp = smem + xrow + i * 2048;
;         const u32x4 lo = *(const u32x4*)(rp + c0), hi = *(const u32x4*)(rp + c1);
;         const i32x8 xf8 = {(int)lo.x, (int)lo.y, (int)lo.z, (int)lo.w, (int)hi.x, (int)hi.y, (int)hi.z, (int)hi.w};
; #pragma unroll
;         for (int j = 0; j < 4; ++j)
;           acc[i][j] = __builtin_amdgcn_mfma_scale_f32_16x16x128_f8f6f4(wf8[j], xf8, acc[i][j], 0, 0, 0, 0x77777777, 0, 0x7f7f7f7f);
;       }
;     } else {
; #pragma unroll
;     for (int kk = 0; kk < 2; ++kk) {
;       const int ch = ((kk * 4 + g) ^ (li & 7)) << 4;
;       bf16x8 xf[MI], wf[4];
; #pragma unroll
;       for (int j = 0; j < 4; ++j) wf[j] = *(const bf16x8*)(smem + wrow + ((j & 1) * 16 + (j >> 1) * 64) * 128 + ch);
; #pragma unroll
;       for (int i = 0; i < MI; ++i) xf[i] = *(const bf16x8*)(smem + xrow + i * 2048 + ch);
; #pragma unroll
;       for (int i = 0; i < MI; ++i)
; #pragma unroll
;         for (int j = 0; j < 4; ++j) {
	v_mfma_f32_16x16x32_bf16 v[72:75], v[172:175], v[152:155], v[72:75]
	v_mfma_f32_16x16x32_bf16 v[68:71], v[180:183], v[152:155], v[68:71]
	v_mfma_f32_16x16x32_bf16 v[64:67], v[192:195], v[152:155], v[64:67]
	v_mfma_f32_16x16x32_bf16 v[60:63], v[196:199], v[152:155], v[60:63]
	v_mfma_f32_16x16x32_bf16 v[88:91], v[172:175], v[148:151], v[88:91]
	v_mfma_f32_16x16x32_bf16 v[84:87], v[180:183], v[148:151], v[84:87]
	v_mfma_f32_16x16x32_bf16 v[80:83], v[192:195], v[148:151], v[80:83]
	v_mfma_f32_16x16x32_bf16 v[76:79], v[196:199], v[148:151], v[76:79]
	ds_read_b128 v[148:151], v0 offset:8192
	ds_read_b128 v[156:159], v0 offset:10240
	ds_read_b128 v[160:163], v0 offset:12288
	ds_read_b128 v[200:203], v0 offset:14336
	s_waitcnt lgkmcnt(3)
	v_mfma_f32_16x16x32_bf16 v[44:47], v[172:175], v[148:151], v[44:47]
	v_mfma_f32_16x16x32_bf16 v[40:43], v[180:183], v[148:151], v[40:43]
	v_mfma_f32_16x16x32_bf16 v[36:39], v[192:195], v[148:151], v[36:39]
	v_mfma_f32_16x16x32_bf16 v[32:35], v[196:199], v[148:151], v[32:35]
	s_waitcnt lgkmcnt(2)
	v_mfma_f32_16x16x32_bf16 v[28:31], v[172:175], v[156:159], v[28:31]
	v_mfma_f32_16x16x32_bf16 v[24:27], v[180:183], v[156:159], v[24:27]
	v_mfma_f32_16x16x32_bf16 v[20:23], v[192:195], v[156:159], v[20:23]
	v_mfma_f32_16x16x32_bf16 v[52:55], v[196:199], v[156:159], v[52:55]
	s_waitcnt lgkmcnt(1)
	v_mfma_f32_16x16x32_bf16 v[48:51], v[172:175], v[160:163], v[48:51]
	v_mfma_f32_16x16x32_bf16 v[56:59], v[180:183], v[160:163], v[56:59]
	v_mfma_f32_16x16x32_bf16 v[112:115], v[192:195], v[160:163], v[112:115]
	v_mfma_f32_16x16x32_bf16 v[108:111], v[196:199], v[160:163], v[108:111]
	s_waitcnt lgkmcnt(0)
	v_mfma_f32_16x16x32_bf16 v[100:103], v[172:175], v[200:203], v[100:103]
	v_mfma_f32_16x16x32_bf16 v[96:99], v[180:183], v[200:203], v[96:99]
	v_mfma_f32_16x16x32_bf16 v[92:95], v[192:195], v[200:203], v[92:95]
	v_mfma_f32_16x16x32_bf16 v[144:147], v[196:199], v[200:203], v[144:147]
	s_add_u32 s22, s22, 0x80
	s_addc_u32 s23, s23, 0
	s_cmpk_lg_i32 s22, 0x780
	s_cbranch_scc1 .LBB0_120
	s_barrier
	s_setprio 3
	s_mov_b32 m0, s62
	s_nop 0
	global_load_lds_dwordx4 v252, s[56:57]
	s_add_u32 m0, s62, 0x1000
	s_nop 0
	global_load_lds_dwordx4 v253, s[56:57]
	s_add_u32 s56, s56, 0x20000
	s_addc_u32 s57, s57, 0
	s_add_u32 m0, s62, 0x2000
	s_nop 0
	global_load_lds_dwordx4 v252, s[56:57]
	s_add_u32 m0, s62, 0x3000
	s_nop 0
	global_load_lds_dwordx4 v253, s[56:57]
	s_add_u32 s56, s56, 0x20000
	s_addc_u32 s57, s57, 0
	s_add_u32 m0, s62, 0x4000
	s_nop 0
	global_load_lds_dwordx4 v252, s[56:57]
	s_add_u32 m0, s62, 0x5000
	s_nop 0
	global_load_lds_dwordx4 v253, s[56:57]
	s_add_u32 s56, s56, 0x20000
	s_addc_u32 s57, s57, 0
	s_add_u32 m0, s62, 0x6000
	s_nop 0
	global_load_lds_dwordx4 v252, s[56:57]
	s_add_u32 m0, s62, 0x7000
	s_nop 0
	global_load_lds_dwordx4 v253, s[56:57]
	s_sub_u32 s56, s56, 0x60000
	s_subb_u32 s57, s57, 0
	s_add_u32 m0, s62, 0x8000
	s_nop 0
	global_load_lds_dwordx4 v252, s[58:59]
	s_add_u32 m0, s62, 0x9000
	s_nop 0
	global_load_lds_dwordx4 v253, s[58:59]
	s_add_u32 s58, s58, 0x20000
	s_addc_u32 s59, s59, 0
	s_add_u32 m0, s62, 0xa000
	s_nop 0
	global_load_lds_dwordx4 v252, s[58:59]
	s_add_u32 m0, s62, 0xb000
	s_nop 0
	global_load_lds_dwordx4 v253, s[58:59]
	s_sub_u32 s58, s58, 0x20000
	s_subb_u32 s59, s59, 0
	s_waitcnt vmcnt(0)
	s_setprio 0
	s_barrier
	v_bfe_u32 v12, v208, 4, 1
	v_mul_u32_u24_e32 v12, 24, v12
	v_mov_b32_e32 v13, 0
	ds_read_b128 v[148:151], v215 offset:32768
	ds_read_b128 v[152:155], v215 offset:34816
	ds_read_b128 v[156:159], v215 offset:40960
	ds_read_b128 v[160:163], v215 offset:43008
	ds_read_b128 v[164:167], v213
	ds_read_b128 v[168:171], v213 offset:2048
	ds_read_b128 v[172:175], v213 offset:4096
	ds_read_b128 v[176:179], v213 offset:6144
	ds_read_b128 v[180:183], v213 offset:8192
	ds_read_b128 v[184:187], v213 offset:10240
	ds_read_b128 v[188:191], v213 offset:12288
	ds_read_b128 v[192:195], v213 offset:14336
	s_waitcnt lgkmcnt(7)
	v_mfma_f32_16x16x32_bf16 v[140:143], v[148:151], v[164:167], v[140:143]
	s_mul_hi_i32 s11, s10, 0x180000
	s_mul_i32 s10, s10, 0x180000
	s_add_u32 s22, s8, s10
	v_mfma_f32_16x16x32_bf16 v[136:139], v[152:155], v[164:167], v[136:139]
	s_addc_u32 s23, s9, s11
	s_lshl_b64 s[10:11], s[20:21], 1
	s_add_u32 s10, s22, s10
	v_mfma_f32_16x16x32_bf16 v[132:135], v[156:159], v[164:167], v[132:135]
	s_addc_u32 s11, s23, s11
	s_movk_i32 s20, 0x1800
	s_add_i32 s28, s28, s78
	v_mfma_f32_16x16x32_bf16 v[128:131], v[160:163], v[164:167], v[128:131]
	s_add_i32 s27, s27, s71
	s_cmpk_gt_i32 s28, 0x5ff
	s_waitcnt lgkmcnt(6)
	v_mfma_f32_16x16x32_bf16 v[124:127], v[148:151], v[168:171], v[124:127]
	v_mfma_f32_16x16x32_bf16 v[120:123], v[152:155], v[168:171], v[120:123]
	v_mfma_f32_16x16x32_bf16 v[116:119], v[156:159], v[168:171], v[116:119]
	v_mfma_f32_16x16x32_bf16 v[104:107], v[160:163], v[168:171], v[104:107]
	s_waitcnt lgkmcnt(5)
	v_mfma_f32_16x16x32_bf16 v[88:91], v[148:151], v[172:175], v[88:91]
	v_mfma_f32_16x16x32_bf16 v[84:87], v[152:155], v[172:175], v[84:87]
	v_mfma_f32_16x16x32_bf16 v[80:83], v[156:159], v[172:175], v[80:83]
	v_mfma_f32_16x16x32_bf16 v[76:79], v[160:163], v[172:175], v[76:79]
	s_waitcnt lgkmcnt(4)
	v_mfma_f32_16x16x32_bf16 v[72:75], v[148:151], v[176:179], v[72:75]
	v_mfma_f32_16x16x32_bf16 v[68:71], v[152:155], v[176:179], v[68:71]
	v_mfma_f32_16x16x32_bf16 v[64:67], v[156:159], v[176:179], v[64:67]
	v_mfma_f32_16x16x32_bf16 v[60:63], v[160:163], v[176:179], v[60:63]
	s_waitcnt lgkmcnt(3)
	v_mfma_f32_16x16x32_bf16 v[44:47], v[148:151], v[180:183], v[44:47]
	v_mfma_f32_16x16x32_bf16 v[40:43], v[152:155], v[180:183], v[40:43]
	v_mfma_f32_16x16x32_bf16 v[36:39], v[156:159], v[180:183], v[36:39]
	v_mfma_f32_16x16x32_bf16 v[32:35], v[160:163], v[180:183], v[32:35]
	s_waitcnt lgkmcnt(2)
; template <int MI, bool SWAP, bool F8 = false>
; __device__ __forceinline__ void gemm_core(const bf16_t* __restrict__ A, int lda, const bf16_t* __restrict__ B, int ldb,
;                                           int K, char* smem, f32x4 (&acc)[MI][4]) {
;     ...
; #pragma unroll
;     for (int kk = 0; kk < 2; ++kk) {
;       const int ch = ((kk * 4 + g) ^ (li & 7)) << 4;
;       bf16x8 xf[MI], wf[4];
; #pragma unroll
;       for (int j = 0; j < 4; ++j) wf[j] = *(const bf16x8*)(smem + wrow + ((j & 1) * 16 + (j >> 1) * 64) * 128 + ch);
; #pragma unroll
;       for (int i = 0; i < MI; ++i) xf[i] = *(const bf16x8*)(smem + xrow + i * 2048 + ch);
; #pragma unroll
;       for (int i = 0; i < MI; ++i)
; #pragma unroll
;         for (int j = 0; j < 4; ++j) {
;           if (SWAP) acc[i][j] = __builtin_amdgcn_mfma_f32_16x16x32_bf16(xf[i], wf[j], acc[i][j], 0, 0, 0);
;           else acc[i][j] = __builtin_amdgcn_mfma_f32_16x16x32_bf16(wf[j], xf[i], acc[i][j], 0, 0, 0);
;         }
; template <int MI, bool F8 = false>
; __device__ void gemm_tile_bf16(const bf16_t* A, int lda, const bf16_t* B, int ldb, int K, bf16_t* C, int ldc, char* smem) {
;   f32x4 acc[MI][4];
;   gemm_core<MI, false, F8>(A, lda, B, ldb, K, smem, acc);
;   EPI_COORDS
; #pragma unroll
;   for (int i = 0; i < MI; ++i)
; #pragma unroll
;     for (int j = 0; j < 4; ++j) {
;       u32x2 v;
;       v.x = pk_bf16(acc[i][j][0], acc[i][j][1]);
;       v.y = pk_bf16(acc[i][j][2], acc[i][j][3]);
;       *(u32x2*)(C + (size_t)MROW(i) * ldc + NCOL(j)) = v;
;     }
	v_mfma_f32_16x16x32_bf16 v[28:31], v[148:151], v[184:187], v[28:31]
	v_mfma_f32_16x16x32_bf16 v[24:27], v[152:155], v[184:187], v[24:27]
	v_mfma_f32_16x16x32_bf16 v[20:23], v[156:159], v[184:187], v[20:23]
	v_mfma_f32_16x16x32_bf16 v[52:55], v[160:163], v[184:187], v[52:55]
	s_waitcnt lgkmcnt(1)
	v_mfma_f32_16x16x32_bf16 v[48:51], v[148:151], v[188:191], v[48:51]
	v_mfma_f32_16x16x32_bf16 v[164:167], v[152:155], v[188:191], v[56:59]
	v_mfma_f32_16x16x32_bf16 v[168:171], v[156:159], v[188:191], v[112:115]
	v_mfma_f32_16x16x32_bf16 v[172:175], v[160:163], v[188:191], v[108:111]
	s_waitcnt lgkmcnt(0)
	v_mfma_f32_16x16x32_bf16 v[148:151], v[148:151], v[192:195], v[100:103]
	v_mfma_f32_16x16x32_bf16 v[152:155], v[152:155], v[192:195], v[96:99]
	v_mfma_f32_16x16x32_bf16 v[156:159], v[156:159], v[192:195], v[92:95]
	v_mfma_f32_16x16x32_bf16 v[144:147], v[160:163], v[192:195], v[144:147]
	ds_read_b128 v[160:163], v206 offset:32768
	ds_read_b128 v[176:179], v206 offset:34816
	ds_read_b128 v[180:183], v206 offset:40960
	ds_read_b128 v[184:187], v206 offset:43008
	ds_read_b128 v[56:59], v0
	ds_read_b128 v[92:95], v0 offset:2048
	ds_read_b128 v[96:99], v0 offset:4096
	ds_read_b128 v[188:191], v0 offset:6144
	ds_read_b128 v[192:195], v0 offset:8192
	ds_read_b128 v[196:199], v0 offset:10240
	ds_read_b128 v[200:203], v0 offset:12288
	ds_read_b128 v[204:207], v0 offset:14336
	s_waitcnt lgkmcnt(7)
	v_mfma_f32_16x16x32_bf16 v[140:143], v[160:163], v[56:59], v[140:143]
	v_mfma_f32_16x16x32_bf16 v[136:139], v[176:179], v[56:59], v[136:139]
	v_mfma_f32_16x16x32_bf16 v[132:135], v[180:183], v[56:59], v[132:135]
	s_nop 5
	v_cvt_pk_bf16_f32 v140, v140, v141
	v_cvt_pk_bf16_f32 v141, v142, v143
	v_cvt_pk_bf16_f32 v136, v136, v137
	v_mfma_f32_16x16x32_bf16 v[128:131], v[184:187], v[56:59], v[128:131]
	v_cvt_pk_bf16_f32 v137, v138, v139
	v_cvt_pk_bf16_f32 v132, v132, v133
	v_cvt_pk_bf16_f32 v133, v134, v135
	s_waitcnt lgkmcnt(2)
	v_mfma_f32_16x16x32_bf16 v[56:59], v[180:183], v[196:199], v[20:23]
	s_waitcnt lgkmcnt(0)
	v_mfma_f32_16x16x32_bf16 v[20:23], v[184:187], v[204:207], v[144:147]
	s_nop 0
	v_cvt_pk_bf16_f32 v128, v128, v129
	v_cvt_pk_bf16_f32 v129, v130, v131
	s_nop 2
	v_cvt_pk_bf16_f32 v56, v56, v57
	v_mov_b32_e32 v146, v208
	v_mfma_f32_16x16x32_bf16 v[124:127], v[160:163], v[92:95], v[124:127]
	v_lshrrev_b32_e32 v0, 1, v146
	v_and_b32_e32 v0, 32, v0
	v_lshrrev_b32_e32 v2, 2, v146
	v_and_b32_e32 v147, 0xffffff8f, v146
	v_and_or_b32 v0, v2, 12, v0
	v_mov_b64_e32 v[2:3], s[10:11]
	v_mfma_f32_16x16x32_bf16 v[216:219], v[180:183], v[92:95], v[116:119]
	v_mad_i64_i32 v[144:145], s[10:11], v147, s20, v[2:3]
	v_lshlrev_b32_e32 v0, 1, v0
	v_mfma_f32_16x16x32_bf16 v[116:119], v[184:187], v[92:95], v[104:107]
	v_lshl_add_u64 v[142:143], v[144:145], 0, v[0:1]
	global_store_dwordx2 v[142:143], v[128:129], off offset:160
	v_or_b32_e32 v128, 16, v147
	v_mfma_f32_16x16x32_bf16 v[112:115], v[160:163], v[96:99], v[88:91]
	v_mad_i64_i32 v[128:129], s[10:11], v128, s20, v[2:3]
	v_cvt_pk_bf16_f32 v124, v124, v125
	v_mfma_f32_16x16x32_bf16 v[100:103], v[184:187], v[96:99], v[76:79]
	v_cvt_pk_bf16_f32 v125, v126, v127
	v_lshl_add_u64 v[126:127], v[128:129], 0, v[0:1]
	v_cvt_pk_bf16_f32 v116, v116, v117
	v_cvt_pk_bf16_f32 v117, v118, v119
	global_store_dwordx2 v[126:127], v[116:117], off offset:160
	v_or_b32_e32 v116, 32, v147
	v_mfma_f32_16x16x32_bf16 v[108:111], v[176:179], v[96:99], v[84:87]
	v_mad_i64_i32 v[116:117], s[10:11], v116, s20, v[2:3]
	v_cvt_pk_bf16_f32 v112, v112, v113
	v_mfma_f32_16x16x32_bf16 v[104:107], v[180:183], v[96:99], v[80:83]
	v_cvt_pk_bf16_f32 v113, v114, v115
	v_lshl_add_u64 v[114:115], v[116:117], 0, v[0:1]
	v_cvt_pk_bf16_f32 v100, v100, v101
	v_mfma_f32_16x16x32_bf16 v[96:99], v[160:163], v[188:191], v[72:75]
	v_cvt_pk_bf16_f32 v101, v102, v103
	global_store_dwordx2 v[114:115], v[100:101], off offset:160
	v_or_b32_e32 v100, 48, v147
	v_mfma_f32_16x16x32_bf16 v[84:87], v[184:187], v[188:191], v[60:63]
	v_mad_i64_i32 v[100:101], s[10:11], v100, s20, v[2:3]
	s_nop 2
	v_cvt_pk_bf16_f32 v96, v96, v97
	v_mfma_f32_16x16x32_bf16 v[120:123], v[176:179], v[92:95], v[120:123]
	v_cvt_pk_bf16_f32 v97, v98, v99
	v_lshl_add_u64 v[98:99], v[100:101], 0, v[0:1]
	v_cvt_pk_bf16_f32 v84, v84, v85
	v_mfma_f32_16x16x32_bf16 v[92:95], v[176:179], v[188:191], v[68:71]
	v_cvt_pk_bf16_f32 v85, v86, v87
	global_store_dwordx2 v[98:99], v[84:85], off offset:160
	v_or_b32_e32 v84, 64, v147
	v_mfma_f32_16x16x32_bf16 v[80:83], v[160:163], v[192:195], v[44:47]
	v_mad_i64_i32 v[84:85], s[10:11], v84, s20, v[2:3]
	v_cvt_pk_bf16_f32 v120, v120, v121
	v_mfma_f32_16x16x32_bf16 v[68:71], v[184:187], v[192:195], v[32:35]
	v_cvt_pk_bf16_f32 v121, v122, v123
	s_nop 3
	v_cvt_pk_bf16_f32 v80, v80, v81
	v_cvt_pk_bf16_f32 v81, v82, v83
	v_mfma_f32_16x16x32_bf16 v[88:91], v[180:183], v[188:191], v[64:67]
	v_lshl_add_u64 v[82:83], v[84:85], 0, v[0:1]
	v_cvt_pk_bf16_f32 v68, v68, v69
	v_cvt_pk_bf16_f32 v69, v70, v71
	v_mfma_f32_16x16x32_bf16 v[64:67], v[160:163], v[196:199], v[28:31]
; template <int MI, bool F8 = false>
; __device__ void gemm_tile_bf16(const bf16_t* A, int lda, const bf16_t* B, int ldb, int K, bf16_t* C, int ldc, char* smem) {
;   f32x4 acc[MI][4];
;   gemm_core<MI, false, F8>(A, lda, B, ldb, K, smem, acc);
;   EPI_COORDS
; #pragma unroll
;   for (int i = 0; i < MI; ++i)
; #pragma unroll
;     for (int j = 0; j < 4; ++j) {
;       u32x2 v;
;       v.x = pk_bf16(acc[i][j][0], acc[i][j][1]);
;       v.y = pk_bf16(acc[i][j][2], acc[i][j][3]);
;       *(u32x2*)(C + (size_t)MROW(i) * ldc + NCOL(j)) = v;
;     }
	global_store_dwordx2 v[82:83], v[68:69], off offset:160
	v_or_b32_e32 v68, 0x50, v147
	v_mad_i64_i32 v[68:69], s[10:11], v68, s20, v[2:3]
	v_mfma_f32_16x16x32_bf16 v[52:55], v[184:187], v[196:199], v[52:55]
	s_nop 3
	v_cvt_pk_bf16_f32 v64, v64, v65
	v_cvt_pk_bf16_f32 v65, v66, v67
	v_lshl_add_u64 v[66:67], v[68:69], 0, v[0:1]
	v_mfma_f32_16x16x32_bf16 v[72:75], v[180:183], v[192:195], v[36:39]
	global_store_dwordx2 v[126:127], v[120:121], off offset:32
	v_cvt_pk_bf16_f32 v52, v52, v53
	v_cvt_pk_bf16_f32 v53, v54, v55
	v_mfma_f32_16x16x32_bf16 v[48:51], v[160:163], v[200:203], v[48:51]
	global_store_dwordx2 v[66:67], v[52:53], off offset:160
	v_or_b32_e32 v52, 0x60, v147
	v_mad_i64_i32 v[52:53], s[10:11], v52, s20, v[2:3]
	v_mfma_f32_16x16x32_bf16 v[36:39], v[184:187], v[200:203], v[172:175]
	s_nop 3
	v_cvt_pk_bf16_f32 v48, v48, v49
	v_cvt_pk_bf16_f32 v49, v50, v51
	v_lshl_add_u64 v[50:51], v[52:53], 0, v[0:1]
	v_mfma_f32_16x16x32_bf16 v[76:79], v[176:179], v[192:195], v[40:43]
	v_cvt_pk_bf16_f32 v120, v216, v217
	v_cvt_pk_bf16_f32 v36, v36, v37
	v_cvt_pk_bf16_f32 v37, v38, v39
	v_mfma_f32_16x16x32_bf16 v[60:63], v[176:179], v[196:199], v[24:27]
	global_store_dwordx2 v[50:51], v[36:37], off offset:160
	v_or_b32_e32 v36, 0x70, v146
	v_mad_i64_i32 v[2:3], s[10:11], v36, s20, v[2:3]
	v_mfma_f32_16x16x32_bf16 v[44:47], v[176:179], v[200:203], v[164:167]
	v_cvt_pk_bf16_f32 v121, v218, v219
	v_cvt_pk_bf16_f32 v108, v108, v109
	v_cvt_pk_bf16_f32 v109, v110, v111
	v_mfma_f32_16x16x32_bf16 v[40:43], v[180:183], v[200:203], v[168:171]
	v_cvt_pk_bf16_f32 v104, v104, v105
	v_cvt_pk_bf16_f32 v105, v106, v107
	v_cvt_pk_bf16_f32 v92, v92, v93
	v_mfma_f32_16x16x32_bf16 v[32:35], v[160:163], v[204:207], v[148:151]
	v_cvt_pk_bf16_f32 v93, v94, v95
	v_cvt_pk_bf16_f32 v88, v88, v89
	v_cvt_pk_bf16_f32 v89, v90, v91
	v_mfma_f32_16x16x32_bf16 v[28:31], v[176:179], v[204:207], v[152:155]
	v_cvt_pk_bf16_f32 v76, v76, v77
	v_cvt_pk_bf16_f32 v77, v78, v79
	v_cvt_pk_bf16_f32 v72, v72, v73
	v_mfma_f32_16x16x32_bf16 v[24:27], v[180:183], v[204:207], v[156:159]
	v_cvt_pk_bf16_f32 v73, v74, v75
	v_cvt_pk_bf16_f32 v60, v60, v61
	v_cvt_pk_bf16_f32 v61, v62, v63
	v_cvt_pk_bf16_f32 v57, v58, v59
	v_cvt_pk_bf16_f32 v44, v44, v45
	v_cvt_pk_bf16_f32 v45, v46, v47
	v_cvt_pk_bf16_f32 v40, v40, v41
	v_cvt_pk_bf16_f32 v41, v42, v43
	v_cvt_pk_bf16_f32 v32, v32, v33
	v_cvt_pk_bf16_f32 v33, v34, v35
	v_lshl_add_u64 v[2:3], v[2:3], 0, v[0:1]
	v_cvt_pk_bf16_f32 v28, v28, v29
	v_cvt_pk_bf16_f32 v29, v30, v31
	v_cvt_pk_bf16_f32 v24, v24, v25
	v_cvt_pk_bf16_f32 v25, v26, v27
	v_cvt_pk_bf16_f32 v20, v20, v21
	v_cvt_pk_bf16_f32 v21, v22, v23
	v_mov_b64_e32 v[4:5], v[140:141]
	v_mov_b64_e32 v[6:7], v[136:137]
	s_nop 1
	v_permlane16_swap_b32_e32 v4, v6
	v_permlane16_swap_b32_e32 v5, v7
	v_lshl_add_u64 v[14:15], v[142:143], 0, v[12:13]
	global_store_dwordx4 v[14:15], v[4:7], off
	global_store_dwordx2 v[142:143], v[132:133], off offset:128
	global_store_dwordx2 v[126:127], v[124:125], off
	global_store_dwordx2 v[126:127], v[120:121], off offset:128
	v_mov_b64_e32 v[8:9], v[112:113]
	v_mov_b64_e32 v[10:11], v[108:109]
	s_nop 1
	v_permlane16_swap_b32_e32 v8, v10
	v_permlane16_swap_b32_e32 v9, v11
	v_lshl_add_u64 v[14:15], v[114:115], 0, v[12:13]
	global_store_dwordx4 v[14:15], v[8:11], off
	global_store_dwordx2 v[114:115], v[104:105], off offset:128
	v_mov_b64_e32 v[4:5], v[96:97]
	v_mov_b64_e32 v[6:7], v[92:93]
	s_nop 1
	v_permlane16_swap_b32_e32 v4, v6
	v_permlane16_swap_b32_e32 v5, v7
	v_lshl_add_u64 v[14:15], v[98:99], 0, v[12:13]
	global_store_dwordx4 v[14:15], v[4:7], off
	global_store_dwordx2 v[98:99], v[88:89], off offset:128
	v_mov_b64_e32 v[8:9], v[80:81]
	v_mov_b64_e32 v[10:11], v[76:77]
	s_nop 1
	v_permlane16_swap_b32_e32 v8, v10
	v_permlane16_swap_b32_e32 v9, v11
	v_lshl_add_u64 v[14:15], v[82:83], 0, v[12:13]
	global_store_dwordx4 v[14:15], v[8:11], off
	global_store_dwordx2 v[82:83], v[72:73], off offset:128
	v_mov_b64_e32 v[4:5], v[64:65]
	v_mov_b64_e32 v[6:7], v[60:61]
	s_nop 1
	v_permlane16_swap_b32_e32 v4, v6
	v_permlane16_swap_b32_e32 v5, v7
	v_lshl_add_u64 v[14:15], v[66:67], 0, v[12:13]
	global_store_dwordx4 v[14:15], v[4:7], off
	global_store_dwordx2 v[66:67], v[56:57], off offset:128
	v_mov_b64_e32 v[8:9], v[48:49]
	v_mov_b64_e32 v[10:11], v[44:45]
	s_nop 1
	v_permlane16_swap_b32_e32 v8, v10
	v_permlane16_swap_b32_e32 v9, v11
	v_lshl_add_u64 v[14:15], v[50:51], 0, v[12:13]
	global_store_dwordx4 v[14:15], v[8:11], off
	global_store_dwordx2 v[50:51], v[40:41], off offset:128
	v_mov_b64_e32 v[4:5], v[32:33]
	v_mov_b64_e32 v[6:7], v[28:29]
	s_nop 1
	v_permlane16_swap_b32_e32 v4, v6
	v_permlane16_swap_b32_e32 v5, v7
	v_lshl_add_u64 v[14:15], v[2:3], 0, v[12:13]
	global_store_dwordx4 v[14:15], v[4:7], off
	v_mov_b64_e32 v[8:9], v[24:25]
	v_mov_b64_e32 v[10:11], v[20:21]
	s_nop 1
	v_permlane16_swap_b32_e32 v8, v10
	v_permlane16_swap_b32_e32 v9, v11
	v_lshl_add_u64 v[14:15], v[2:3], 0, v[12:13]
	global_store_dwordx4 v[14:15], v[8:11], off offset:128
	s_cbranch_scc0 .LBB0_119

; template <int MI, bool SWAP, bool F8 = false>
; __device__ __forceinline__ void gemm_core(const bf16_t* __restrict__ A, int lda, const bf16_t* __restrict__ B, int ldb,
;                                           int K, char* smem, f32x4 (&acc)[MI][4]) {
;     ...
;   for (int kt = 0; kt < nk; ++kt) {
;     __syncthreads();
; #pragma unroll
;     for (int i = 0; i < MI; ++i) *(u32x4*)(smem + woff + i * 4096) = ra[i];
; #pragma unroll
;     for (int i = 0; i < 4; ++i) *(u32x4*)(smem + 32768 + woff + i * 4096) = rb[i];
;     __syncthreads();
;     if (kt + 1 < nk) {
; #pragma unroll
;       for (int i = 0; i < MI; ++i) ra[i] = *(const u32x4*)(ap + (size_t)(32 * i) * lda + (kt + 1) * 64);
; #pragma unroll
;       for (int i = 0; i < 4; ++i) rb[i] = *(const u32x4*)(bp + (size_t)(32 * i) * ldb + (kt + 1) * 64);
;     }
.LBB0_236:
	v_add_u32_e32 v215, v203, v204
	s_barrier
	s_setprio 3
	s_mov_b32 m0, s62
	s_nop 0
	global_load_lds_dwordx4 v252, s[56:57]
	s_add_u32 m0, s62, 0x1000
	s_nop 0
	global_load_lds_dwordx4 v253, s[56:57]
	s_add_u32 s56, s56, 0x20000
	s_addc_u32 s57, s57, 0
	s_add_u32 m0, s62, 0x2000
	s_nop 0
	global_load_lds_dwordx4 v252, s[56:57]
	s_add_u32 m0, s62, 0x3000
	s_nop 0
	global_load_lds_dwordx4 v253, s[56:57]
	s_add_u32 s56, s56, 0x20000
	s_addc_u32 s57, s57, 0
	s_add_u32 m0, s62, 0x4000
	s_nop 0
	global_load_lds_dwordx4 v252, s[56:57]
	s_add_u32 m0, s62, 0x5000
	s_nop 0
	global_load_lds_dwordx4 v253, s[56:57]
	s_add_u32 s56, s56, 0x20000
	s_addc_u32 s57, s57, 0
	s_add_u32 m0, s62, 0x6000
	s_nop 0
	global_load_lds_dwordx4 v252, s[56:57]
	s_add_u32 m0, s62, 0x7000
	s_nop 0
	global_load_lds_dwordx4 v253, s[56:57]
	s_sub_u32 s56, s56, 0x60000
	s_subb_u32 s57, s57, 0
	s_add_u32 m0, s62, 0x8000
	s_nop 0
	global_load_lds_dwordx4 v252, s[58:59]
	s_add_u32 m0, s62, 0x9000
	s_nop 0
	global_load_lds_dwordx4 v253, s[58:59]
	s_add_u32 s58, s58, 0x20000
	s_addc_u32 s59, s59, 0
	s_add_u32 m0, s62, 0xa000
	s_nop 0
	global_load_lds_dwordx4 v252, s[58:59]
	s_add_u32 m0, s62, 0xb000
	s_nop 0
	global_load_lds_dwordx4 v253, s[58:59]
	s_sub_u32 s58, s58, 0x20000
	s_subb_u32 s59, s59, 0
	v_add_u32_e32 v252, 0x80, v252
	v_add_u32_e32 v253, 0x80, v253
	s_waitcnt vmcnt(0)
	s_setprio 0
	s_cmp_gt_u32 s63, 12
	s_cbranch_scc1 .Lcch236_ret
	s_cmp_eq_u32 s63, 0
	s_cbranch_scc1 .Lcch236_h0
	s_cmp_eq_u32 s63, 3
	s_cbranch_scc1 .Lcch236_h1
	s_cmp_eq_u32 s63, 6
	s_cbranch_scc1 .Lcch236_h2
	s_cmp_eq_u32 s63, 9
	s_cbranch_scc1 .Lcch236_h3
	s_cmp_eq_u32 s63, 12
	s_cbranch_scc1 .Lcch236_h4
	s_branch .Lcch236_ret

; template <int MI, bool SWAP, bool F8 = false>
; __device__ __forceinline__ void gemm_core(const bf16_t* __restrict__ A, int lda, const bf16_t* __restrict__ B, int ldb,
;                                           int K, char* smem, f32x4 (&acc)[MI][4]) {
;     ...
; #pragma unroll
;     for (int kk = 0; kk < 2; ++kk) {
;       const int ch = ((kk * 4 + g) ^ (li & 7)) << 4;
;       bf16x8 xf[MI], wf[4];
; #pragma unroll
;       for (int j = 0; j < 4; ++j) wf[j] = *(const bf16x8*)(smem + wrow + ((j & 1) * 16 + (j >> 1) * 64) * 128 + ch);
; #pragma unroll
;       for (int i = 0; i < MI; ++i) xf[i] = *(const bf16x8*)(smem + xrow + i * 2048 + ch);
; #pragma unroll
;       for (int i = 0; i < MI; ++i)
; #pragma unroll
;         for (int j = 0; j < 4; ++j) {
;           if (SWAP) acc[i][j] = __builtin_amdgcn_mfma_f32_16x16x32_bf16(xf[i], wf[j], acc[i][j], 0, 0, 0);
;           else acc[i][j] = __builtin_amdgcn_mfma_f32_16x16x32_bf16(wf[j], xf[i], acc[i][j], 0, 0, 0);
;         }
;     }
.Lcch236_ret:
	s_add_u32 s63, s63, 1
	s_barrier
	v_add_u32_e32 v213, v202, v204
	ds_read_b128 v[148:151], v215 offset:32768
	ds_read_b128 v[152:155], v215 offset:34816
	ds_read_b128 v[156:159], v213
	ds_read_b128 v[160:163], v213 offset:2048
	ds_read_b128 v[164:167], v215 offset:40960
	ds_read_b128 v[168:171], v215 offset:43008
	s_waitcnt lgkmcnt(3)
	v_mfma_f32_16x16x32_bf16 v[140:143], v[148:151], v[156:159], v[140:143]
	v_add_u32_e32 v207, v203, v205
	v_add_u32_e32 v206, v202, v205
	v_mfma_f32_16x16x32_bf16 v[136:139], v[152:155], v[156:159], v[136:139]
	s_waitcnt lgkmcnt(1)
	v_mfma_f32_16x16x32_bf16 v[132:135], v[164:167], v[156:159], v[132:135]
	s_waitcnt lgkmcnt(0)
	v_mfma_f32_16x16x32_bf16 v[124:127], v[168:171], v[156:159], v[124:127]
	v_mfma_f32_16x16x32_bf16 v[108:111], v[148:151], v[160:163], v[108:111]
	v_mfma_f32_16x16x32_bf16 v[104:107], v[152:155], v[160:163], v[104:107]
	v_mfma_f32_16x16x32_bf16 v[96:99], v[164:167], v[160:163], v[96:99]
	v_mfma_f32_16x16x32_bf16 v[92:95], v[168:171], v[160:163], v[92:95]
	ds_read_b128 v[156:159], v213 offset:4096
	ds_read_b128 v[160:163], v213 offset:6144
	s_waitcnt lgkmcnt(1)
	v_mfma_f32_16x16x32_bf16 v[88:91], v[148:151], v[156:159], v[88:91]
	v_mfma_f32_16x16x32_bf16 v[84:87], v[152:155], v[156:159], v[84:87]
	v_mfma_f32_16x16x32_bf16 v[80:83], v[164:167], v[156:159], v[80:83]
	v_mfma_f32_16x16x32_bf16 v[60:63], v[168:171], v[156:159], v[60:63]
	s_waitcnt lgkmcnt(0)
	v_mfma_f32_16x16x32_bf16 v[56:59], v[148:151], v[160:163], v[56:59]
	v_mfma_f32_16x16x32_bf16 v[52:55], v[152:155], v[160:163], v[52:55]
	v_mfma_f32_16x16x32_bf16 v[48:51], v[164:167], v[160:163], v[48:51]
	v_mfma_f32_16x16x32_bf16 v[44:47], v[168:171], v[160:163], v[44:47]
	ds_read_b128 v[156:159], v213 offset:8192
	ds_read_b128 v[160:163], v213 offset:10240
	s_waitcnt lgkmcnt(1)
	v_mfma_f32_16x16x32_bf16 v[40:43], v[148:151], v[156:159], v[40:43]
	v_mfma_f32_16x16x32_bf16 v[36:39], v[152:155], v[156:159], v[36:39]
	v_mfma_f32_16x16x32_bf16 v[32:35], v[164:167], v[156:159], v[32:35]
	v_mfma_f32_16x16x32_bf16 v[28:31], v[168:171], v[156:159], v[28:31]
	s_waitcnt lgkmcnt(0)
	v_mfma_f32_16x16x32_bf16 v[24:27], v[148:151], v[160:163], v[24:27]
	v_mfma_f32_16x16x32_bf16 v[20:23], v[152:155], v[160:163], v[20:23]
	v_mfma_f32_16x16x32_bf16 v[68:71], v[164:167], v[160:163], v[68:71]
	v_mfma_f32_16x16x32_bf16 v[64:67], v[168:171], v[160:163], v[64:67]
	ds_read_b128 v[156:159], v213 offset:12288
	ds_read_b128 v[160:163], v213 offset:14336
	ds_read_b128 v[172:175], v207 offset:32768
	ds_read_b128 v[180:183], v207 offset:34816
	s_waitcnt lgkmcnt(3)
	v_mfma_f32_16x16x32_bf16 v[72:75], v[148:151], v[156:159], v[72:75]
	v_mfma_f32_16x16x32_bf16 v[76:79], v[152:155], v[156:159], v[76:79]
	v_mfma_f32_16x16x32_bf16 v[128:131], v[164:167], v[156:159], v[128:131]
	v_mfma_f32_16x16x32_bf16 v[120:123], v[168:171], v[156:159], v[120:123]
	s_waitcnt lgkmcnt(2)
	v_mfma_f32_16x16x32_bf16 v[116:119], v[148:151], v[160:163], v[116:119]
	v_mfma_f32_16x16x32_bf16 v[112:115], v[152:155], v[160:163], v[112:115]
	ds_read_b128 v[148:151], v206
	ds_read_b128 v[152:155], v206 offset:2048
	ds_read_b128 v[192:195], v207 offset:40960
	ds_read_b128 v[196:199], v207 offset:43008
	v_mfma_f32_16x16x32_bf16 v[100:103], v[164:167], v[160:163], v[100:103]
	v_mfma_f32_16x16x32_bf16 v[144:147], v[168:171], v[160:163], v[144:147]
	s_waitcnt lgkmcnt(3)
	v_mfma_f32_16x16x32_bf16 v[140:143], v[172:175], v[148:151], v[140:143]
	v_mfma_f32_16x16x32_bf16 v[136:139], v[180:183], v[148:151], v[136:139]
	s_waitcnt lgkmcnt(1)
	v_mfma_f32_16x16x32_bf16 v[132:135], v[192:195], v[148:151], v[132:135]
	s_waitcnt lgkmcnt(0)
	v_mfma_f32_16x16x32_bf16 v[124:127], v[196:199], v[148:151], v[124:127]
	v_mfma_f32_16x16x32_bf16 v[108:111], v[172:175], v[152:155], v[108:111]
	v_mfma_f32_16x16x32_bf16 v[104:107], v[180:183], v[152:155], v[104:107]
	v_mfma_f32_16x16x32_bf16 v[96:99], v[192:195], v[152:155], v[96:99]
	v_mfma_f32_16x16x32_bf16 v[92:95], v[196:199], v[152:155], v[92:95]
	ds_read_b128 v[148:151], v206 offset:4096
	ds_read_b128 v[152:155], v206 offset:6144
	s_waitcnt lgkmcnt(1)
	v_mfma_f32_16x16x32_bf16 v[88:91], v[172:175], v[148:151], v[88:91]
	ds_read_b128 v[156:159], v206 offset:12288
	ds_read_b128 v[216:219], v206 offset:14336
	v_mfma_f32_16x16x32_bf16 v[84:87], v[180:183], v[148:151], v[84:87]
	v_mfma_f32_16x16x32_bf16 v[80:83], v[192:195], v[148:151], v[80:83]
	v_mfma_f32_16x16x32_bf16 v[60:63], v[196:199], v[148:151], v[60:63]
	ds_read_b128 v[148:151], v206 offset:8192
	s_waitcnt lgkmcnt(3)
	v_mfma_f32_16x16x32_bf16 v[56:59], v[172:175], v[152:155], v[56:59]
	v_mfma_f32_16x16x32_bf16 v[52:55], v[180:183], v[152:155], v[52:55]
	v_mfma_f32_16x16x32_bf16 v[48:51], v[192:195], v[152:155], v[48:51]
	v_mfma_f32_16x16x32_bf16 v[44:47], v[196:199], v[152:155], v[44:47]
	ds_read_b128 v[152:155], v206 offset:10240
	s_waitcnt lgkmcnt(1)
	v_mfma_f32_16x16x32_bf16 v[40:43], v[172:175], v[148:151], v[40:43]
	v_mfma_f32_16x16x32_bf16 v[36:39], v[180:183], v[148:151], v[36:39]
	v_mfma_f32_16x16x32_bf16 v[32:35], v[192:195], v[148:151], v[32:35]
	v_mfma_f32_16x16x32_bf16 v[28:31], v[196:199], v[148:151], v[28:31]
	s_waitcnt lgkmcnt(0)
	v_mfma_f32_16x16x32_bf16 v[24:27], v[172:175], v[152:155], v[24:27]
	v_mfma_f32_16x16x32_bf16 v[20:23], v[180:183], v[152:155], v[20:23]
	v_mfma_f32_16x16x32_bf16 v[68:71], v[192:195], v[152:155], v[68:71]
	v_mfma_f32_16x16x32_bf16 v[64:67], v[196:199], v[152:155], v[64:67]
	v_mfma_f32_16x16x32_bf16 v[72:75], v[172:175], v[156:159], v[72:75]
	v_mfma_f32_16x16x32_bf16 v[76:79], v[180:183], v[156:159], v[76:79]
	v_mfma_f32_16x16x32_bf16 v[128:131], v[192:195], v[156:159], v[128:131]
	v_mfma_f32_16x16x32_bf16 v[120:123], v[196:199], v[156:159], v[120:123]
	v_mfma_f32_16x16x32_bf16 v[116:119], v[172:175], v[216:219], v[116:119]
	v_mfma_f32_16x16x32_bf16 v[112:115], v[180:183], v[216:219], v[112:115]
	v_mfma_f32_16x16x32_bf16 v[100:103], v[192:195], v[216:219], v[100:103]
	v_mfma_f32_16x16x32_bf16 v[144:147], v[196:199], v[216:219], v[144:147]
	s_add_u32 s20, s20, 0x80
	s_addc_u32 s21, s21, 0
	s_cmpk_lg_i32 s20, 0x780
	s_cbranch_scc1 .LBB0_236
; template <int MI, bool SWAP, bool F8 = false>
; __device__ __forceinline__ void gemm_core(const bf16_t* __restrict__ A, int lda, const bf16_t* __restrict__ B, int ldb,
;                                           int K, char* smem, f32x4 (&acc)[MI][4]) {
;     ...
;   for (int kt = 0; kt < nk; ++kt) {
;     __syncthreads();
; #pragma unroll
;     for (int i = 0; i < MI; ++i) *(u32x4*)(smem + woff + i * 4096) = ra[i];
; #pragma unroll
;     for (int i = 0; i < 4; ++i) *(u32x4*)(smem + 32768 + woff + i * 4096) = rb[i];
;     __syncthreads();
;     if (kt + 1 < nk) {
; #pragma unroll
;       for (int i = 0; i < MI; ++i) ra[i] = *(const u32x4*)(ap + (size_t)(32 * i) * lda + (kt + 1) * 64);
; #pragma unroll
;       for (int i = 0; i < 4; ++i) rb[i] = *(const u32x4*)(bp + (size_t)(32 * i) * ldb + (kt + 1) * 64);
;     }
;     if (F8) {
;       const int c0 = (g ^ (li & 7)) << 4, c1 = ((4 + g) ^ (li & 7)) << 4;
;       i32x8 wf8[4];
; #pragma unroll
;       for (int j = 0; j < 4; ++j) {
;         const char* rp = smem + wrow + ((j & 1) * 16 + (j >> 1) * 64) * 128;
;         const u32x4 lo = *(const u32x4*)(rp + c0), hi = *(const u32x4*)(rp + c1);
;         wf8[j] = (i32x8){(int)lo.x, (int)lo.y, (int)lo.z, (int)lo.w, (int)hi.x, (int)hi.y, (int)hi.z, (int)hi.w};
;       }
; #pragma unroll
;       for (int i = 0; i < MI; ++i) {
;         const char* rp = smem + xrow + i * 2048;
;         const u32x4 lo = *(const u32x4*)(rp + c0), hi = *(const u32x4*)(rp + c1);
;         const i32x8 xf8 = {(int)lo.x, (int)lo.y, (int)lo.z, (int)lo.w, (int)hi.x, (int)hi.y, (int)hi.z, (int)hi.w};
; #pragma unroll
;         for (int j = 0; j < 4; ++j)
;           acc[i][j] = __builtin_amdgcn_mfma_scale_f32_16x16x128_f8f6f4(wf8[j], xf8, acc[i][j], 0, 0, 0, 0x77777777, 0, 0x7f7f7f7f);
;       }
;     } else {
; #pragma unroll
;     for (int kk = 0; kk < 2; ++kk) {
;       const int ch = ((kk * 4 + g) ^ (li & 7)) << 4;
;       bf16x8 xf[MI], wf[4];
; #pragma unroll
;       for (int j = 0; j < 4; ++j) wf[j] = *(const bf16x8*)(smem + wrow + ((j & 1) * 16 + (j >> 1) * 64) * 128 + ch);
; #pragma unroll
;       for (int i = 0; i < MI; ++i) xf[i] = *(const bf16x8*)(smem + xrow + i * 2048 + ch);
; #pragma unroll
;       for (int i = 0; i < MI; ++i)
; #pragma unroll
;         for (int j = 0; j < 4; ++j) {
	s_barrier
	s_setprio 3
	s_mov_b32 m0, s62
	s_nop 0
	global_load_lds_dwordx4 v252, s[56:57]
	s_add_u32 m0, s62, 0x1000
	s_nop 0
	global_load_lds_dwordx4 v253, s[56:57]
	s_add_u32 s56, s56, 0x20000
	s_addc_u32 s57, s57, 0
	s_add_u32 m0, s62, 0x2000
	s_nop 0
	global_load_lds_dwordx4 v252, s[56:57]
	s_add_u32 m0, s62, 0x3000
	s_nop 0
	global_load_lds_dwordx4 v253, s[56:57]
	s_add_u32 s56, s56, 0x20000
	s_addc_u32 s57, s57, 0
	s_add_u32 m0, s62, 0x4000
	s_nop 0
	global_load_lds_dwordx4 v252, s[56:57]
	s_add_u32 m0, s62, 0x5000
	s_nop 0
	global_load_lds_dwordx4 v253, s[56:57]
	s_add_u32 s56, s56, 0x20000
	s_addc_u32 s57, s57, 0
	s_add_u32 m0, s62, 0x6000
	s_nop 0
	global_load_lds_dwordx4 v252, s[56:57]
	s_add_u32 m0, s62, 0x7000
	s_nop 0
	global_load_lds_dwordx4 v253, s[56:57]
	s_sub_u32 s56, s56, 0x60000
	s_subb_u32 s57, s57, 0
	s_add_u32 m0, s62, 0x8000
	s_nop 0
	global_load_lds_dwordx4 v252, s[58:59]
	s_add_u32 m0, s62, 0x9000
	s_nop 0
	global_load_lds_dwordx4 v253, s[58:59]
	s_add_u32 s58, s58, 0x20000
	s_addc_u32 s59, s59, 0
	s_add_u32 m0, s62, 0xa000
	s_nop 0
	global_load_lds_dwordx4 v252, s[58:59]
	s_add_u32 m0, s62, 0xb000
	s_nop 0
	global_load_lds_dwordx4 v253, s[58:59]
	s_sub_u32 s58, s58, 0x20000
	s_subb_u32 s59, s59, 0
	s_waitcnt vmcnt(0)
	s_setprio 0
	s_barrier
	ds_read_b128 v[148:151], v215 offset:32768
	ds_read_b128 v[152:155], v215 offset:34816
	ds_read_b128 v[156:159], v215 offset:40960
	ds_read_b128 v[160:163], v215 offset:43008
	ds_read_b128 v[164:167], v213
	ds_read_b128 v[168:171], v213 offset:2048
	ds_read_b128 v[172:175], v213 offset:4096
	ds_read_b128 v[176:179], v213 offset:6144
	ds_read_b128 v[180:183], v213 offset:8192
	ds_read_b128 v[184:187], v213 offset:10240
	ds_read_b128 v[188:191], v213 offset:12288
	ds_read_b128 v[192:195], v213 offset:14336
	s_waitcnt lgkmcnt(7)
	v_mfma_f32_16x16x32_bf16 v[132:135], v[156:159], v[164:167], v[132:135]
	s_lshl_b64 s[10:11], s[10:11], 2
	s_add_u32 s10, s16, s10
	s_addc_u32 s11, s17, s11
	v_mfma_f32_16x16x32_bf16 v[140:143], v[148:151], v[164:167], v[140:143]
	s_lshl_b32 s20, s26, 2
	s_add_u32 s10, s10, s20
	s_addc_u32 s11, s11, 0
	v_mfma_f32_16x16x32_bf16 v[136:139], v[152:155], v[164:167], v[136:139]
	s_add_i32 s25, s25, s78
	s_add_i32 s24, s24, s71
	s_add_i32 s23, s23, s76
	v_mfma_f32_16x16x32_bf16 v[124:127], v[160:163], v[164:167], v[124:127]
	s_cmpk_gt_i32 s25, 0x1ff
	s_waitcnt lgkmcnt(6)
	v_mfma_f32_16x16x32_bf16 v[108:111], v[148:151], v[168:171], v[108:111]
	v_mfma_f32_16x16x32_bf16 v[104:107], v[152:155], v[168:171], v[104:107]
	v_mfma_f32_16x16x32_bf16 v[96:99], v[156:159], v[168:171], v[96:99]
	v_mfma_f32_16x16x32_bf16 v[92:95], v[160:163], v[168:171], v[92:95]
	s_waitcnt lgkmcnt(5)
	v_mfma_f32_16x16x32_bf16 v[88:91], v[148:151], v[172:175], v[88:91]
	v_mfma_f32_16x16x32_bf16 v[84:87], v[152:155], v[172:175], v[84:87]
	v_mfma_f32_16x16x32_bf16 v[80:83], v[156:159], v[172:175], v[80:83]
	v_mfma_f32_16x16x32_bf16 v[60:63], v[160:163], v[172:175], v[60:63]
	s_waitcnt lgkmcnt(4)
	v_mfma_f32_16x16x32_bf16 v[56:59], v[148:151], v[176:179], v[56:59]
	v_mfma_f32_16x16x32_bf16 v[52:55], v[152:155], v[176:179], v[52:55]
	v_mfma_f32_16x16x32_bf16 v[48:51], v[156:159], v[176:179], v[48:51]
	v_mfma_f32_16x16x32_bf16 v[44:47], v[160:163], v[176:179], v[44:47]
	s_waitcnt lgkmcnt(3)
	v_mfma_f32_16x16x32_bf16 v[40:43], v[148:151], v[180:183], v[40:43]
	v_mfma_f32_16x16x32_bf16 v[36:39], v[152:155], v[180:183], v[36:39]
	v_mfma_f32_16x16x32_bf16 v[32:35], v[156:159], v[180:183], v[32:35]
	v_mfma_f32_16x16x32_bf16 v[28:31], v[160:163], v[180:183], v[28:31]
	s_waitcnt lgkmcnt(2)
	v_mfma_f32_16x16x32_bf16 v[24:27], v[148:151], v[184:187], v[24:27]
	v_mfma_f32_16x16x32_bf16 v[20:23], v[152:155], v[184:187], v[20:23]
	v_mfma_f32_16x16x32_bf16 v[164:167], v[156:159], v[184:187], v[68:71]
	v_mfma_f32_16x16x32_bf16 v[168:171], v[160:163], v[184:187], v[64:67]
	s_waitcnt lgkmcnt(1)
	v_mfma_f32_16x16x32_bf16 v[172:175], v[148:151], v[188:191], v[72:75]
	v_mfma_f32_16x16x32_bf16 v[176:179], v[152:155], v[188:191], v[76:79]
	v_mfma_f32_16x16x32_bf16 v[180:183], v[156:159], v[188:191], v[128:131]
	v_mfma_f32_16x16x32_bf16 v[184:187], v[160:163], v[188:191], v[120:123]
	s_waitcnt lgkmcnt(0)
	v_mfma_f32_16x16x32_bf16 v[148:151], v[148:151], v[192:195], v[116:119]
	v_mfma_f32_16x16x32_bf16 v[152:155], v[152:155], v[192:195], v[112:115]
	v_mfma_f32_16x16x32_bf16 v[156:159], v[156:159], v[192:195], v[100:103]
	v_mfma_f32_16x16x32_bf16 v[144:147], v[160:163], v[192:195], v[144:147]
	ds_read_b128 v[160:163], v207 offset:32768
	ds_read_b128 v[188:191], v207 offset:34816
	ds_read_b128 v[192:195], v207 offset:40960
	ds_read_b128 v[196:199], v207 offset:43008
	ds_read_b128 v[64:67], v206
	ds_read_b128 v[68:71], v206 offset:2048
	ds_read_b128 v[72:75], v206 offset:4096
	ds_read_b128 v[76:79], v206 offset:6144
	ds_read_b128 v[200:203], v206 offset:8192
	ds_read_b128 v[216:219], v206 offset:10240
	ds_read_b128 v[220:223], v206 offset:12288
	ds_read_b128 v[204:207], v206 offset:14336
	s_waitcnt lgkmcnt(7)
; template <int MI, bool SWAP, bool F8 = false>
; __device__ __forceinline__ void gemm_core(const bf16_t* __restrict__ A, int lda, const bf16_t* __restrict__ B, int ldb,
;                                           int K, char* smem, f32x4 (&acc)[MI][4]) {
;     ...
; #pragma unroll
;     for (int kk = 0; kk < 2; ++kk) {
;       const int ch = ((kk * 4 + g) ^ (li & 7)) << 4;
;       bf16x8 xf[MI], wf[4];
; #pragma unroll
;       for (int j = 0; j < 4; ++j) wf[j] = *(const bf16x8*)(smem + wrow + ((j & 1) * 16 + (j >> 1) * 64) * 128 + ch);
; #pragma unroll
;       for (int i = 0; i < MI; ++i) xf[i] = *(const bf16x8*)(smem + xrow + i * 2048 + ch);
; #pragma unroll
;       for (int i = 0; i < MI; ++i)
; #pragma unroll
;         for (int j = 0; j < 4; ++j) {
;           if (SWAP) acc[i][j] = __builtin_amdgcn_mfma_f32_16x16x32_bf16(xf[i], wf[j], acc[i][j], 0, 0, 0);
;           else acc[i][j] = __builtin_amdgcn_mfma_f32_16x16x32_bf16(wf[j], xf[i], acc[i][j], 0, 0, 0);
;         }
; template <bool ACCUM, int MI>
; __device__ void gemm_tile_f32(const bf16_t* A, int lda, const bf16_t* B, int ldb, int K, float* C, int ldc, char* smem) {
;     ...
; #pragma unroll
;   for (int i = 0; i < MI; ++i)
; #pragma unroll
;     for (int j = 0; j < 4; ++j) {
;       f32x4* cp = (f32x4*)(C + (size_t)MROW(i) * ldc + NCOL(j));
;       f32x4 v = acc[i][j];
;       if (ACCUM) v += *cp;
;       *cp = v;
;     }
	v_mfma_f32_16x16x32_bf16 v[224:227], v[192:195], v[64:67], v[132:135]
	v_mfma_f32_16x16x32_bf16 v[228:231], v[196:199], v[64:67], v[124:127]
	s_waitcnt lgkmcnt(6)
	v_mfma_f32_16x16x32_bf16 v[128:131], v[160:163], v[68:71], v[108:111]
	v_mfma_f32_16x16x32_bf16 v[124:127], v[188:191], v[68:71], v[104:107]
	s_waitcnt lgkmcnt(5)
	v_mfma_f32_16x16x32_bf16 v[112:115], v[160:163], v[72:75], v[88:91]
	v_mfma_f32_16x16x32_bf16 v[108:111], v[188:191], v[72:75], v[84:87]
	v_mfma_f32_16x16x32_bf16 v[104:107], v[192:195], v[72:75], v[80:83]
	v_mfma_f32_16x16x32_bf16 v[100:103], v[196:199], v[72:75], v[60:63]
	s_waitcnt lgkmcnt(3)
	v_mfma_f32_16x16x32_bf16 v[72:75], v[192:195], v[200:203], v[32:35]
	s_waitcnt lgkmcnt(0)
	v_mfma_f32_16x16x32_bf16 v[32:35], v[160:163], v[204:207], v[148:151]
	v_mfma_f32_16x16x32_bf16 v[60:63], v[188:191], v[216:219], v[20:23]
	v_mfma_f32_16x16x32_bf16 v[20:23], v[196:199], v[204:207], v[144:147]
	v_mfma_f32_16x16x32_bf16 v[140:143], v[160:163], v[64:67], v[140:143]
	v_mfma_f32_16x16x32_bf16 v[136:139], v[188:191], v[64:67], v[136:139]
	v_mfma_f32_16x16x32_bf16 v[120:123], v[192:195], v[68:71], v[96:99]
	v_mfma_f32_16x16x32_bf16 v[116:119], v[196:199], v[68:71], v[92:95]
	v_mfma_f32_16x16x32_bf16 v[96:99], v[160:163], v[76:79], v[56:59]
	v_mfma_f32_16x16x32_bf16 v[92:95], v[188:191], v[76:79], v[52:55]
	v_mfma_f32_16x16x32_bf16 v[88:91], v[192:195], v[76:79], v[48:51]
	v_mfma_f32_16x16x32_bf16 v[84:87], v[196:199], v[76:79], v[44:47]
	v_mfma_f32_16x16x32_bf16 v[80:83], v[160:163], v[200:203], v[40:43]
	v_mfma_f32_16x16x32_bf16 v[76:79], v[188:191], v[200:203], v[36:39]
	v_mfma_f32_16x16x32_bf16 v[68:71], v[196:199], v[200:203], v[28:31]
	v_mfma_f32_16x16x32_bf16 v[64:67], v[160:163], v[216:219], v[24:27]
	v_mfma_f32_16x16x32_bf16 v[56:59], v[192:195], v[216:219], v[164:167]
	v_mfma_f32_16x16x32_bf16 v[52:55], v[196:199], v[216:219], v[168:171]
	v_mfma_f32_16x16x32_bf16 v[48:51], v[160:163], v[220:223], v[172:175]
	v_mfma_f32_16x16x32_bf16 v[44:47], v[188:191], v[220:223], v[176:179]
	v_mfma_f32_16x16x32_bf16 v[40:43], v[192:195], v[220:223], v[180:183]
	v_mfma_f32_16x16x32_bf16 v[36:39], v[196:199], v[220:223], v[184:187]
	v_mfma_f32_16x16x32_bf16 v[28:31], v[188:191], v[204:207], v[152:155]
	v_mfma_f32_16x16x32_bf16 v[24:27], v[192:195], v[204:207], v[156:159]
	s_nop 7
	s_nop 7
	s_nop 7
	global_store_dwordx4 v237, v[140:143], s[98:99]
	global_store_dwordx4 v237, v[136:139], s[98:99] offset:64
	global_store_dwordx4 v237, v[224:227], s[98:99] offset:256
	global_store_dwordx4 v237, v[228:231], s[98:99] offset:320
	v_add_u32_e32 v237, 0x10000, v237
	global_store_dwordx4 v237, v[128:131], s[98:99]
	global_store_dwordx4 v237, v[124:127], s[98:99] offset:64
	global_store_dwordx4 v237, v[120:123], s[98:99] offset:256
	global_store_dwordx4 v237, v[116:119], s[98:99] offset:320
	v_add_u32_e32 v237, 0x10000, v237
	global_store_dwordx4 v237, v[112:115], s[98:99]
	global_store_dwordx4 v237, v[108:111], s[98:99] offset:64
	global_store_dwordx4 v237, v[104:107], s[98:99] offset:256
	global_store_dwordx4 v237, v[100:103], s[98:99] offset:320
	v_add_u32_e32 v237, 0x10000, v237
	global_store_dwordx4 v237, v[96:99], s[98:99]
	global_store_dwordx4 v237, v[92:95], s[98:99] offset:64
	global_store_dwordx4 v237, v[88:91], s[98:99] offset:256
	global_store_dwordx4 v237, v[84:87], s[98:99] offset:320
	v_add_u32_e32 v237, 0x10000, v237
	global_store_dwordx4 v237, v[80:83], s[98:99]
	global_store_dwordx4 v237, v[76:79], s[98:99] offset:64
	global_store_dwordx4 v237, v[72:75], s[98:99] offset:256
	global_store_dwordx4 v237, v[68:71], s[98:99] offset:320
	v_add_u32_e32 v237, 0x10000, v237
	global_store_dwordx4 v237, v[64:67], s[98:99]
	global_store_dwordx4 v237, v[60:63], s[98:99] offset:64
	global_store_dwordx4 v237, v[56:59], s[98:99] offset:256
	global_store_dwordx4 v237, v[52:55], s[98:99] offset:320
	v_add_u32_e32 v237, 0x10000, v237
	global_store_dwordx4 v237, v[48:51], s[98:99]
	global_store_dwordx4 v237, v[44:47], s[98:99] offset:64
	global_store_dwordx4 v237, v[40:43], s[98:99] offset:256
	global_store_dwordx4 v237, v[36:39], s[98:99] offset:320
	v_add_u32_e32 v237, 0x10000, v237
	global_store_dwordx4 v237, v[32:35], s[98:99]
	global_store_dwordx4 v237, v[28:31], s[98:99] offset:64
	global_store_dwordx4 v237, v[24:27], s[98:99] offset:256
	global_store_dwordx4 v237, v[20:23], s[98:99] offset:320
	s_cbranch_scc0 .LBB0_235

; template <int MI, bool SWAP, bool F8 = false>
; __device__ __forceinline__ void gemm_core(const bf16_t* __restrict__ A, int lda, const bf16_t* __restrict__ B, int ldb,
;                                           int K, char* smem, f32x4 (&acc)[MI][4]) {
;     ...
;   for (int kt = 0; kt < nk; ++kt) {
;     __syncthreads();
; #pragma unroll
;     for (int i = 0; i < MI; ++i) *(u32x4*)(smem + woff + i * 4096) = ra[i];
; #pragma unroll
;     for (int i = 0; i < 4; ++i) *(u32x4*)(smem + 32768 + woff + i * 4096) = rb[i];
;     __syncthreads();
;     if (kt + 1 < nk) {
; #pragma unroll
;       for (int i = 0; i < MI; ++i) ra[i] = *(const u32x4*)(ap + (size_t)(32 * i) * lda + (kt + 1) * 64);
; #pragma unroll
;       for (int i = 0; i < 4; ++i) rb[i] = *(const u32x4*)(bp + (size_t)(32 * i) * ldb + (kt + 1) * 64);
;     }
;     if (F8) {
;       const int c0 = (g ^ (li & 7)) << 4, c1 = ((4 + g) ^ (li & 7)) << 4;
;       i32x8 wf8[4];
; #pragma unroll
;       for (int j = 0; j < 4; ++j) {
;         const char* rp = smem + wrow + ((j & 1) * 16 + (j >> 1) * 64) * 128;
;         const u32x4 lo = *(const u32x4*)(rp + c0), hi = *(const u32x4*)(rp + c1);
;         wf8[j] = (i32x8){(int)lo.x, (int)lo.y, (int)lo.z, (int)lo.w, (int)hi.x, (int)hi.y, (int)hi.z, (int)hi.w};
;       }
; #pragma unroll
;       for (int i = 0; i < MI; ++i) {
;         const char* rp = smem + xrow + i * 2048;
;         const u32x4 lo = *(const u32x4*)(rp + c0), hi = *(const u32x4*)(rp + c1);
;         const i32x8 xf8 = {(int)lo.x, (int)lo.y, (int)lo.z, (int)lo.w, (int)hi.x, (int)hi.y, (int)hi.z, (int)hi.w};
; #pragma unroll
;         for (int j = 0; j < 4; ++j)
;           acc[i][j] = __builtin_amdgcn_mfma_scale_f32_16x16x128_f8f6f4(wf8[j], xf8, acc[i][j], 0, 0, 0, 0x77777777, 0, 0x7f7f7f7f);
;       }
;     } else {
; #pragma unroll
;     for (int kk = 0; kk < 2; ++kk) {
;       const int ch = ((kk * 4 + g) ^ (li & 7)) << 4;
;       bf16x8 xf[MI], wf[4];
; #pragma unroll
;       for (int j = 0; j < 4; ++j) wf[j] = *(const bf16x8*)(smem + wrow + ((j & 1) * 16 + (j >> 1) * 64) * 128 + ch);
; #pragma unroll
;       for (int i = 0; i < MI; ++i) xf[i] = *(const bf16x8*)(smem + xrow + i * 2048 + ch);
; #pragma unroll
;       for (int i = 0; i < MI; ++i)
; #pragma unroll
;         for (int j = 0; j < 4; ++j) {
.LBB0_301:
	v_add_u32_e32 v213, v204, v205
	s_barrier
	s_setprio 3
	s_mov_b32 m0, s62
	s_nop 0
	global_load_lds_dwordx4 v252, s[56:57]
	s_add_u32 m0, s62, 0x1000
	s_nop 0
	global_load_lds_dwordx4 v253, s[56:57]
	s_add_u32 s56, s56, 0x20000
	s_addc_u32 s57, s57, 0
	s_add_u32 m0, s62, 0x2000
	s_nop 0
	global_load_lds_dwordx4 v252, s[56:57]
	s_add_u32 m0, s62, 0x3000
	s_nop 0
	global_load_lds_dwordx4 v253, s[56:57]
	s_add_u32 s56, s56, 0x20000
	s_addc_u32 s57, s57, 0
	s_add_u32 m0, s62, 0x4000
	s_nop 0
	global_load_lds_dwordx4 v252, s[56:57]
	s_add_u32 m0, s62, 0x5000
	s_nop 0
	global_load_lds_dwordx4 v253, s[56:57]
	s_add_u32 s56, s56, 0x20000
	s_addc_u32 s57, s57, 0
	s_add_u32 m0, s62, 0x6000
	s_nop 0
	global_load_lds_dwordx4 v252, s[56:57]
	s_add_u32 m0, s62, 0x7000
	s_nop 0
	global_load_lds_dwordx4 v253, s[56:57]
	s_sub_u32 s56, s56, 0x60000
	s_subb_u32 s57, s57, 0
	s_add_u32 m0, s62, 0x8000
	s_nop 0
	global_load_lds_dwordx4 v252, s[58:59]
	s_add_u32 m0, s62, 0x9000
	s_nop 0
	global_load_lds_dwordx4 v253, s[58:59]
	s_add_u32 s58, s58, 0x20000
	s_addc_u32 s59, s59, 0
	s_add_u32 m0, s62, 0xa000
	s_nop 0
	global_load_lds_dwordx4 v252, s[58:59]
	s_add_u32 m0, s62, 0xb000
	s_nop 0
	global_load_lds_dwordx4 v253, s[58:59]
	s_sub_u32 s58, s58, 0x20000
	s_subb_u32 s59, s59, 0
	v_add_u32_e32 v252, 0x80, v252
	v_add_u32_e32 v253, 0x80, v253
	s_waitcnt vmcnt(0)
	s_setprio 0
	s_barrier
	v_add_u32_e32 v0, v203, v205
	ds_read_b128 v[136:139], v213 offset:32768
	ds_read_b128 v[144:147], v213 offset:34816
	ds_read_b128 v[152:155], v0
	ds_read_b128 v[156:159], v0 offset:2048
	ds_read_b128 v[164:167], v213 offset:40960
	ds_read_b128 v[168:171], v213 offset:43008
	s_waitcnt lgkmcnt(3)
	v_mfma_f32_16x16x32_bf16 v[148:151], v[136:139], v[152:155], v[148:151]
	v_add_u32_e32 v215, v204, v206
	v_add_u32_e32 v207, v203, v206
	v_mfma_f32_16x16x32_bf16 v[140:143], v[144:147], v[152:155], v[140:143]
	s_waitcnt lgkmcnt(1)
	v_mfma_f32_16x16x32_bf16 v[132:135], v[164:167], v[152:155], v[132:135]
	s_waitcnt lgkmcnt(0)
	v_mfma_f32_16x16x32_bf16 v[128:131], v[168:171], v[152:155], v[128:131]
	v_mfma_f32_16x16x32_bf16 v[124:127], v[136:139], v[156:159], v[124:127]
	v_mfma_f32_16x16x32_bf16 v[120:123], v[144:147], v[156:159], v[120:123]
	v_mfma_f32_16x16x32_bf16 v[116:119], v[164:167], v[156:159], v[116:119]
	v_mfma_f32_16x16x32_bf16 v[112:115], v[168:171], v[156:159], v[112:115]
	ds_read_b128 v[152:155], v0 offset:4096
	ds_read_b128 v[156:159], v0 offset:6144
	s_waitcnt lgkmcnt(1)
	v_mfma_f32_16x16x32_bf16 v[108:111], v[136:139], v[152:155], v[108:111]
	v_mfma_f32_16x16x32_bf16 v[104:107], v[144:147], v[152:155], v[104:107]
	v_mfma_f32_16x16x32_bf16 v[100:103], v[164:167], v[152:155], v[100:103]
	v_mfma_f32_16x16x32_bf16 v[96:99], v[168:171], v[152:155], v[96:99]
	s_waitcnt lgkmcnt(0)
	v_mfma_f32_16x16x32_bf16 v[92:95], v[136:139], v[156:159], v[92:95]
	v_mfma_f32_16x16x32_bf16 v[88:91], v[144:147], v[156:159], v[88:91]
	v_mfma_f32_16x16x32_bf16 v[84:87], v[164:167], v[156:159], v[84:87]
	v_mfma_f32_16x16x32_bf16 v[80:83], v[168:171], v[156:159], v[80:83]
	ds_read_b128 v[152:155], v0 offset:8192
	ds_read_b128 v[156:159], v0 offset:10240
	s_waitcnt lgkmcnt(1)
	v_mfma_f32_16x16x32_bf16 v[68:71], v[136:139], v[152:155], v[68:71]
	v_mfma_f32_16x16x32_bf16 v[64:67], v[144:147], v[152:155], v[64:67]
	v_mfma_f32_16x16x32_bf16 v[60:63], v[164:167], v[152:155], v[60:63]
	v_mfma_f32_16x16x32_bf16 v[56:59], v[168:171], v[152:155], v[56:59]
	s_waitcnt lgkmcnt(0)
	v_mfma_f32_16x16x32_bf16 v[48:51], v[136:139], v[156:159], v[48:51]
	v_mfma_f32_16x16x32_bf16 v[44:47], v[144:147], v[156:159], v[44:47]
	v_mfma_f32_16x16x32_bf16 v[40:43], v[164:167], v[156:159], v[40:43]
	v_mfma_f32_16x16x32_bf16 v[36:39], v[168:171], v[156:159], v[36:39]
	ds_read_b128 v[152:155], v0 offset:12288
	ds_read_b128 v[156:159], v0 offset:14336
	ds_read_b128 v[172:175], v215 offset:32768
	ds_read_b128 v[180:183], v215 offset:34816
	s_waitcnt lgkmcnt(3)
	v_mfma_f32_16x16x32_bf16 v[28:31], v[136:139], v[152:155], v[28:31]
	v_mfma_f32_16x16x32_bf16 v[24:27], v[144:147], v[152:155], v[24:27]
	v_mfma_f32_16x16x32_bf16 v[76:79], v[164:167], v[152:155], v[76:79]
	v_mfma_f32_16x16x32_bf16 v[72:75], v[168:171], v[152:155], v[72:75]
	s_waitcnt lgkmcnt(2)
	v_mfma_f32_16x16x32_bf16 v[52:55], v[136:139], v[156:159], v[52:55]
	v_mfma_f32_16x16x32_bf16 v[32:35], v[144:147], v[156:159], v[32:35]
	ds_read_b128 v[136:139], v207
	ds_read_b128 v[144:147], v207 offset:2048
	ds_read_b128 v[192:195], v215 offset:40960
	ds_read_b128 v[196:199], v215 offset:43008
	v_mfma_f32_16x16x32_bf16 v[20:23], v[164:167], v[156:159], v[20:23]
	v_mfma_f32_16x16x32_bf16 v[160:163], v[168:171], v[156:159], v[160:163]
	s_waitcnt lgkmcnt(3)
	v_mfma_f32_16x16x32_bf16 v[148:151], v[172:175], v[136:139], v[148:151]
	v_mfma_f32_16x16x32_bf16 v[140:143], v[180:183], v[136:139], v[140:143]
	s_waitcnt lgkmcnt(1)
	v_mfma_f32_16x16x32_bf16 v[132:135], v[192:195], v[136:139], v[132:135]
	s_waitcnt lgkmcnt(0)
	v_mfma_f32_16x16x32_bf16 v[128:131], v[196:199], v[136:139], v[128:131]
	v_mfma_f32_16x16x32_bf16 v[124:127], v[172:175], v[144:147], v[124:127]
	v_mfma_f32_16x16x32_bf16 v[120:123], v[180:183], v[144:147], v[120:123]
	v_mfma_f32_16x16x32_bf16 v[116:119], v[192:195], v[144:147], v[116:119]
	v_mfma_f32_16x16x32_bf16 v[112:115], v[196:199], v[144:147], v[112:115]
	ds_read_b128 v[136:139], v207 offset:4096
	ds_read_b128 v[144:147], v207 offset:6144
	s_waitcnt lgkmcnt(1)
; template <int MI, bool SWAP, bool F8 = false>
; __device__ __forceinline__ void gemm_core(const bf16_t* __restrict__ A, int lda, const bf16_t* __restrict__ B, int ldb,
;                                           int K, char* smem, f32x4 (&acc)[MI][4]) {
;     ...
;   for (int kt = 0; kt < nk; ++kt) {
;     __syncthreads();
; #pragma unroll
;     for (int i = 0; i < MI; ++i) *(u32x4*)(smem + woff + i * 4096) = ra[i];
; #pragma unroll
;     for (int i = 0; i < 4; ++i) *(u32x4*)(smem + 32768 + woff + i * 4096) = rb[i];
;     __syncthreads();
;     if (kt + 1 < nk) {
; #pragma unroll
;       for (int i = 0; i < MI; ++i) ra[i] = *(const u32x4*)(ap + (size_t)(32 * i) * lda + (kt + 1) * 64);
; #pragma unroll
;       for (int i = 0; i < 4; ++i) rb[i] = *(const u32x4*)(bp + (size_t)(32 * i) * ldb + (kt + 1) * 64);
;     }
;     if (F8) {
;       const int c0 = (g ^ (li & 7)) << 4, c1 = ((4 + g) ^ (li & 7)) << 4;
;       i32x8 wf8[4];
; #pragma unroll
;       for (int j = 0; j < 4; ++j) {
;         const char* rp = smem + wrow + ((j & 1) * 16 + (j >> 1) * 64) * 128;
;         const u32x4 lo = *(const u32x4*)(rp + c0), hi = *(const u32x4*)(rp + c1);
;         wf8[j] = (i32x8){(int)lo.x, (int)lo.y, (int)lo.z, (int)lo.w, (int)hi.x, (int)hi.y, (int)hi.z, (int)hi.w};
;       }
; #pragma unroll
;       for (int i = 0; i < MI; ++i) {
;         const char* rp = smem + xrow + i * 2048;
;         const u32x4 lo = *(const u32x4*)(rp + c0), hi = *(const u32x4*)(rp + c1);
;         const i32x8 xf8 = {(int)lo.x, (int)lo.y, (int)lo.z, (int)lo.w, (int)hi.x, (int)hi.y, (int)hi.z, (int)hi.w};
; #pragma unroll
;         for (int j = 0; j < 4; ++j)
;           acc[i][j] = __builtin_amdgcn_mfma_scale_f32_16x16x128_f8f6f4(wf8[j], xf8, acc[i][j], 0, 0, 0, 0x77777777, 0, 0x7f7f7f7f);
;       }
;     } else {
; #pragma unroll
;     for (int kk = 0; kk < 2; ++kk) {
;       const int ch = ((kk * 4 + g) ^ (li & 7)) << 4;
;       bf16x8 xf[MI], wf[4];
; #pragma unroll
;       for (int j = 0; j < 4; ++j) wf[j] = *(const bf16x8*)(smem + wrow + ((j & 1) * 16 + (j >> 1) * 64) * 128 + ch);
; #pragma unroll
;       for (int i = 0; i < MI; ++i) xf[i] = *(const bf16x8*)(smem + xrow + i * 2048 + ch);
; #pragma unroll
;       for (int i = 0; i < MI; ++i)
; #pragma unroll
;         for (int j = 0; j < 4; ++j) {
	v_mfma_f32_16x16x32_bf16 v[108:111], v[172:175], v[136:139], v[108:111]
	ds_read_b128 v[152:155], v207 offset:12288
	ds_read_b128 v[216:219], v207 offset:14336
	v_mfma_f32_16x16x32_bf16 v[104:107], v[180:183], v[136:139], v[104:107]
	v_mfma_f32_16x16x32_bf16 v[100:103], v[192:195], v[136:139], v[100:103]
	v_mfma_f32_16x16x32_bf16 v[96:99], v[196:199], v[136:139], v[96:99]
	ds_read_b128 v[136:139], v207 offset:8192
	s_waitcnt lgkmcnt(3)
	v_mfma_f32_16x16x32_bf16 v[92:95], v[172:175], v[144:147], v[92:95]
	v_mfma_f32_16x16x32_bf16 v[88:91], v[180:183], v[144:147], v[88:91]
	v_mfma_f32_16x16x32_bf16 v[84:87], v[192:195], v[144:147], v[84:87]
	v_mfma_f32_16x16x32_bf16 v[80:83], v[196:199], v[144:147], v[80:83]
	ds_read_b128 v[144:147], v207 offset:10240
	s_waitcnt lgkmcnt(1)
	v_mfma_f32_16x16x32_bf16 v[68:71], v[172:175], v[136:139], v[68:71]
	v_mfma_f32_16x16x32_bf16 v[64:67], v[180:183], v[136:139], v[64:67]
	v_mfma_f32_16x16x32_bf16 v[60:63], v[192:195], v[136:139], v[60:63]
	v_mfma_f32_16x16x32_bf16 v[56:59], v[196:199], v[136:139], v[56:59]
	s_waitcnt lgkmcnt(0)
	v_mfma_f32_16x16x32_bf16 v[48:51], v[172:175], v[144:147], v[48:51]
	v_mfma_f32_16x16x32_bf16 v[44:47], v[180:183], v[144:147], v[44:47]
	v_mfma_f32_16x16x32_bf16 v[40:43], v[192:195], v[144:147], v[40:43]
	v_mfma_f32_16x16x32_bf16 v[36:39], v[196:199], v[144:147], v[36:39]
	v_mfma_f32_16x16x32_bf16 v[28:31], v[172:175], v[152:155], v[28:31]
	v_mfma_f32_16x16x32_bf16 v[24:27], v[180:183], v[152:155], v[24:27]
	v_mfma_f32_16x16x32_bf16 v[76:79], v[192:195], v[152:155], v[76:79]
	v_mfma_f32_16x16x32_bf16 v[72:75], v[196:199], v[152:155], v[72:75]
	v_mfma_f32_16x16x32_bf16 v[52:55], v[172:175], v[216:219], v[52:55]
	v_mfma_f32_16x16x32_bf16 v[32:35], v[180:183], v[216:219], v[32:35]
	v_mfma_f32_16x16x32_bf16 v[20:23], v[192:195], v[216:219], v[20:23]
	v_mfma_f32_16x16x32_bf16 v[160:163], v[196:199], v[216:219], v[160:163]
	s_add_u32 s26, s26, 0x80
	s_addc_u32 s27, s27, 0
	s_cmpk_lg_i32 s26, 0x780
	s_cbranch_scc1 .LBB0_301
	s_barrier
	s_setprio 3
	s_mov_b32 m0, s62
	s_nop 0
	global_load_lds_dwordx4 v252, s[56:57]
	s_add_u32 m0, s62, 0x1000
	s_nop 0
	global_load_lds_dwordx4 v253, s[56:57]
	s_add_u32 s56, s56, 0x20000
	s_addc_u32 s57, s57, 0
	s_add_u32 m0, s62, 0x2000
	s_nop 0
	global_load_lds_dwordx4 v252, s[56:57]
	s_add_u32 m0, s62, 0x3000
	s_nop 0
	global_load_lds_dwordx4 v253, s[56:57]
	s_add_u32 s56, s56, 0x20000
	s_addc_u32 s57, s57, 0
	s_add_u32 m0, s62, 0x4000
	s_nop 0
	global_load_lds_dwordx4 v252, s[56:57]
	s_add_u32 m0, s62, 0x5000
	s_nop 0
	global_load_lds_dwordx4 v253, s[56:57]
	s_add_u32 s56, s56, 0x20000
	s_addc_u32 s57, s57, 0
	s_add_u32 m0, s62, 0x6000
	s_nop 0
	global_load_lds_dwordx4 v252, s[56:57]
	s_add_u32 m0, s62, 0x7000
	s_nop 0
	global_load_lds_dwordx4 v253, s[56:57]
	s_sub_u32 s56, s56, 0x60000
	s_subb_u32 s57, s57, 0
	s_add_u32 m0, s62, 0x8000
	s_nop 0
	global_load_lds_dwordx4 v252, s[58:59]
	s_add_u32 m0, s62, 0x9000
	s_nop 0
	global_load_lds_dwordx4 v253, s[58:59]
	s_add_u32 s58, s58, 0x20000
	s_addc_u32 s59, s59, 0
	s_add_u32 m0, s62, 0xa000
	s_nop 0
	global_load_lds_dwordx4 v252, s[58:59]
	s_add_u32 m0, s62, 0xb000
	s_nop 0
	global_load_lds_dwordx4 v253, s[58:59]
	s_sub_u32 s58, s58, 0x20000
	s_subb_u32 s59, s59, 0
	s_waitcnt vmcnt(0)
	s_setprio 0
	s_barrier
	v_bfe_u32 v12, v208, 4, 1
	v_mul_u32_u24_e32 v12, 24, v12
	v_mov_b32_e32 v13, 0
	ds_read_b128 v[136:139], v213 offset:32768
	ds_read_b128 v[144:147], v213 offset:34816
	ds_read_b128 v[152:155], v0
	ds_read_b128 v[156:159], v0 offset:2048
	ds_read_b128 v[164:167], v213 offset:40960
	ds_read_b128 v[168:171], v213 offset:43008
	s_waitcnt lgkmcnt(3)
	v_mfma_f32_16x16x32_bf16 v[148:151], v[136:139], v[152:155], v[148:151]
	s_cmp_eq_u32 s42, 6
	s_cselect_b64 s[26:27], -1, 0
	s_cmp_lg_u32 s42, 6
	v_mfma_f32_16x16x32_bf16 v[140:143], v[144:147], v[152:155], v[140:143]
	s_cselect_b64 s[30:31], -1, 0
	s_and_b64 vcc, exec, s[26:27]
	s_waitcnt lgkmcnt(1)
	v_mfma_f32_16x16x32_bf16 v[132:135], v[164:167], v[152:155], v[132:135]
	s_waitcnt lgkmcnt(0)
	v_mfma_f32_16x16x32_bf16 v[128:131], v[168:171], v[152:155], v[128:131]
	v_mfma_f32_16x16x32_bf16 v[172:175], v[136:139], v[156:159], v[124:127]
	s_nop 2
	ds_read_b128 v[124:127], v0 offset:4096
	ds_read_b128 v[152:155], v0 offset:6144
	s_waitcnt lgkmcnt(0)
	v_mfma_f32_16x16x32_bf16 v[176:179], v[164:167], v[152:155], v[84:87]
	v_mfma_f32_16x16x32_bf16 v[180:183], v[168:171], v[152:155], v[80:83]
	s_nop 2
	ds_read_b128 v[80:83], v0 offset:8192
	ds_read_b128 v[84:87], v0 offset:10240
	s_waitcnt lgkmcnt(1)
	v_mfma_f32_16x16x32_bf16 v[196:199], v[168:171], v[80:83], v[56:59]
	s_waitcnt lgkmcnt(0)
	v_mfma_f32_16x16x32_bf16 v[200:203], v[136:139], v[84:87], v[48:51]
	s_nop 2
	ds_read_b128 v[48:51], v0 offset:12288
	ds_read_b128 v[56:59], v0 offset:14336
	v_mfma_f32_16x16x32_bf16 v[116:119], v[164:167], v[156:159], v[116:119]
	v_mfma_f32_16x16x32_bf16 v[112:115], v[168:171], v[156:159], v[112:115]
	v_mfma_f32_16x16x32_bf16 v[100:103], v[164:167], v[124:127], v[100:103]
	v_mfma_f32_16x16x32_bf16 v[96:99], v[168:171], v[124:127], v[96:99]
	v_mfma_f32_16x16x32_bf16 v[192:195], v[164:167], v[80:83], v[60:63]
	v_mfma_f32_16x16x32_bf16 v[40:43], v[164:167], v[84:87], v[40:43]
	v_mfma_f32_16x16x32_bf16 v[36:39], v[168:171], v[84:87], v[36:39]
	s_waitcnt lgkmcnt(1)
	v_mfma_f32_16x16x32_bf16 v[28:31], v[136:139], v[48:51], v[28:31]
	v_mfma_f32_16x16x32_bf16 v[24:27], v[144:147], v[48:51], v[24:27]
	v_mfma_f32_16x16x32_bf16 v[76:79], v[164:167], v[48:51], v[76:79]
	v_mfma_f32_16x16x32_bf16 v[216:219], v[168:171], v[48:51], v[72:75]
	s_waitcnt lgkmcnt(0)
; template <int MI, bool SWAP, bool F8 = false>
; __device__ __forceinline__ void gemm_core(const bf16_t* __restrict__ A, int lda, const bf16_t* __restrict__ B, int ldb,
;                                           int K, char* smem, f32x4 (&acc)[MI][4]) {
;     ...
; #pragma unroll
;     for (int kk = 0; kk < 2; ++kk) {
;       const int ch = ((kk * 4 + g) ^ (li & 7)) << 4;
;       bf16x8 xf[MI], wf[4];
; #pragma unroll
;       for (int j = 0; j < 4; ++j) wf[j] = *(const bf16x8*)(smem + wrow + ((j & 1) * 16 + (j >> 1) * 64) * 128 + ch);
; #pragma unroll
;       for (int i = 0; i < MI; ++i) xf[i] = *(const bf16x8*)(smem + xrow + i * 2048 + ch);
; #pragma unroll
;       for (int i = 0; i < MI; ++i)
; #pragma unroll
;         for (int j = 0; j < 4; ++j) {
;           if (SWAP) acc[i][j] = __builtin_amdgcn_mfma_f32_16x16x32_bf16(xf[i], wf[j], acc[i][j], 0, 0, 0);
;           else acc[i][j] = __builtin_amdgcn_mfma_f32_16x16x32_bf16(wf[j], xf[i], acc[i][j], 0, 0, 0);
;         }
;     }
; __device__ void even_in_tile(const P& p, int li_even, int tm, int tn, char* smem) {
;     ...
;   if (seg != 6) {
;     const float* ctab = (const float*)(ws + OFF_COS);
;     const float* stab = (const float*)(ws + OFF_SIN);
; #pragma unroll
;     for (int i = 0; i < MI; ++i) {
;       const int s = s0 + MROW(i);
; #pragma unroll
;       for (int jj = 0; jj < 2; ++jj) {
;         const int d = wn * 32 + jj * 16 + g * 4;
;         const f32x4 c = *(const f32x4*)(ctab + s * 64 + d);
;         const f32x4 sn = *(const f32x4*)(stab + s * 64 + d);
	v_mfma_f32_16x16x32_bf16 v[224:227], v[144:147], v[56:59], v[32:35]
	v_mfma_f32_16x16x32_bf16 v[20:23], v[164:167], v[56:59], v[20:23]
	ds_read_b128 v[164:167], v215 offset:32768
	v_mfma_f32_16x16x32_bf16 v[160:163], v[168:171], v[56:59], v[160:163]
	ds_read_b128 v[168:171], v215 offset:34816
	ds_read_b128 v[32:35], v207
	ds_read_b128 v[48:51], v207 offset:2048
	ds_read_b128 v[228:231], v215 offset:40960
	ds_read_b128 v[232:235], v215 offset:43008
	v_mfma_f32_16x16x32_bf16 v[120:123], v[144:147], v[156:159], v[120:123]
	v_mov_b32_e32 v215, v208
	v_mfma_f32_16x16x32_bf16 v[108:111], v[136:139], v[124:127], v[108:111]
	v_mfma_f32_16x16x32_bf16 v[104:107], v[144:147], v[124:127], v[104:107]
	v_mfma_f32_16x16x32_bf16 v[92:95], v[136:139], v[152:155], v[92:95]
	v_mfma_f32_16x16x32_bf16 v[156:159], v[144:147], v[152:155], v[88:91]
	v_mfma_f32_16x16x32_bf16 v[184:187], v[136:139], v[80:83], v[68:71]
	v_mfma_f32_16x16x32_bf16 v[188:191], v[144:147], v[80:83], v[64:67]
	v_mfma_f32_16x16x32_bf16 v[44:47], v[144:147], v[84:87], v[44:47]
	v_mfma_f32_16x16x32_bf16 v[220:223], v[136:139], v[56:59], v[52:55]
	s_waitcnt lgkmcnt(3)
	v_mfma_f32_16x16x32_bf16 v[124:127], v[164:167], v[32:35], v[148:151]
	v_mfma_f32_16x16x32_bf16 v[150:153], v[168:171], v[32:35], v[140:143]
	s_waitcnt lgkmcnt(1)
	v_mfma_f32_16x16x32_bf16 v[88:91], v[228:231], v[32:35], v[132:135]
	s_waitcnt lgkmcnt(0)
	v_mfma_f32_16x16x32_bf16 v[84:87], v[232:235], v[32:35], v[128:131]
	v_mfma_f32_16x16x32_bf16 v[134:137], v[164:167], v[48:51], v[172:175]
	v_mfma_f32_16x16x32_bf16 v[138:141], v[168:171], v[48:51], v[120:123]
	v_mfma_f32_16x16x32_bf16 v[80:83], v[228:231], v[48:51], v[116:119]
	v_mfma_f32_16x16x32_bf16 v[72:75], v[232:235], v[48:51], v[112:115]
	ds_read_b128 v[32:35], v207 offset:4096
	ds_read_b128 v[48:51], v207 offset:6144
	s_waitcnt lgkmcnt(1)
	v_mfma_f32_16x16x32_bf16 v[142:145], v[164:167], v[32:35], v[108:111]
	v_mfma_f32_16x16x32_bf16 v[146:149], v[168:171], v[32:35], v[104:107]
	v_mfma_f32_16x16x32_bf16 v[68:71], v[228:231], v[32:35], v[100:103]
	v_mfma_f32_16x16x32_bf16 v[64:67], v[232:235], v[32:35], v[96:99]
	s_waitcnt lgkmcnt(0)
	v_mfma_f32_16x16x32_bf16 v[128:131], v[164:167], v[48:51], v[92:95]
	ds_read_b128 v[32:35], v207 offset:8192
	s_nop 1
	ds_read_b128 v[92:95], v207 offset:10240
	v_mfma_f32_16x16x32_bf16 v[120:123], v[168:171], v[48:51], v[156:159]
	v_mfma_f32_16x16x32_bf16 v[60:63], v[228:231], v[48:51], v[176:179]
	v_mfma_f32_16x16x32_bf16 v[56:59], v[232:235], v[48:51], v[180:183]
	s_waitcnt lgkmcnt(1)
	v_mfma_f32_16x16x32_bf16 v[112:115], v[164:167], v[32:35], v[184:187]
	v_mfma_f32_16x16x32_bf16 v[108:111], v[168:171], v[32:35], v[188:191]
	v_mfma_f32_16x16x32_bf16 v[52:55], v[228:231], v[32:35], v[192:195]
	v_mfma_f32_16x16x32_bf16 v[48:51], v[232:235], v[32:35], v[196:199]
	ds_read_b128 v[32:35], v207 offset:12288
	ds_read_b128 v[116:119], v207 offset:14336
	s_waitcnt lgkmcnt(2)
	v_mfma_f32_16x16x32_bf16 v[104:107], v[164:167], v[92:95], v[200:203]
	v_and_b32_e32 v213, 15, v215
	v_mfma_f32_16x16x32_bf16 v[100:103], v[168:171], v[92:95], v[44:47]
	v_mfma_f32_16x16x32_bf16 v[44:47], v[228:231], v[92:95], v[40:43]
	v_mfma_f32_16x16x32_bf16 v[40:43], v[232:235], v[92:95], v[36:39]
	s_waitcnt lgkmcnt(1)
	v_mfma_f32_16x16x32_bf16 v[96:99], v[164:167], v[32:35], v[28:31]
	v_mfma_f32_16x16x32_bf16 v[92:95], v[168:171], v[32:35], v[24:27]
	v_mfma_f32_16x16x32_bf16 v[36:39], v[228:231], v[32:35], v[76:79]
	v_mfma_f32_16x16x32_bf16 v[32:35], v[232:235], v[32:35], v[216:219]
	s_waitcnt lgkmcnt(0)
	v_mfma_f32_16x16x32_bf16 v[76:79], v[164:167], v[116:119], v[220:223]
	s_nop 0
	v_bfe_u32 v218, v215, 6, 1
	v_bfe_u32 v219, v215, 4, 2
	v_mfma_f32_16x16x32_bf16 v[28:31], v[168:171], v[116:119], v[224:227]
	v_mfma_f32_16x16x32_bf16 v[24:27], v[228:231], v[116:119], v[20:23]
	v_mfma_f32_16x16x32_bf16 v[20:23], v[232:235], v[116:119], v[160:163]
	s_cbranch_vccnz .LBB0_315
	v_and_b32_e32 v0, 0x3ffff80, v215
	v_add_u32_e32 v0, s41, v0
	s_add_u32 s34, s45, 0x4000
	v_or_b32_e32 v0, v0, v213
	s_addc_u32 s35, s48, 0
	v_lshlrev_b32_e32 v2, 6, v0
	s_add_u32 s36, s45, 0x104000
	v_ashrrev_i32_e32 v3, 31, v2
	s_addc_u32 s37, s48, 0
	v_lshlrev_b64 v[116:117], 2, v[2:3]
	v_lshlrev_b32_e32 v0, 4, v219
	v_lshl_add_u64 v[118:119], s[34:35], 0, v[116:117]
	v_lshl_add_u64 v[116:117], s[36:37], 0, v[116:117]
	v_lshl_or_b32 v0, v218, 7, v0
	v_lshl_add_u64 v[132:133], v[118:119], 0, v[0:1]
	v_lshl_add_u64 v[162:163], v[116:117], 0, v[0:1]
	v_lshl_add_u32 v236, v2, 2, v0
	global_load_dwordx4 v[164:167], v236, s[34:35]
	global_load_dwordx4 v[168:171], v236, s[36:37]
	global_load_dwordx4 v[172:175], v236, s[34:35] offset:64
	global_load_dwordx4 v[176:179], v236, s[36:37] offset:64
	v_add_u32_e32 v236, 0x1000, v236
	global_load_dwordx4 v[180:183], v236, s[34:35]
	global_load_dwordx4 v[184:187], v236, s[36:37]
	global_load_dwordx4 v[188:191], v236, s[34:35] offset:64
	global_load_dwordx4 v[192:195], v236, s[36:37] offset:64
	v_add_u32_e32 v236, 0x1000, v236
	global_load_dwordx4 v[196:199], v236, s[34:35]
	global_load_dwordx4 v[200:203], v236, s[36:37]
	global_load_dwordx4 v[204:207], v236, s[34:35] offset:64
	global_load_dwordx4 v[220:223], v236, s[36:37] offset:64
	v_add_u32_e32 v236, 0x1000, v236
	global_load_dwordx4 v[224:227], v236, s[34:35]
	global_load_dwordx4 v[228:231], v236, s[36:37]
	global_load_dwordx4 v[232:235], v236, s[34:35] offset:64
	global_load_dwordx4 v[4:7], v236, s[36:37] offset:64
	v_add_u32_e32 v236, 0x1000, v236
	s_waitcnt vmcnt(14)
; __device__ void even_in_tile(const P& p, int li_even, int tm, int tn, char* smem) {
;     ...
; #pragma unroll
;     for (int i = 0; i < MI; ++i) {
;       const int s = s0 + MROW(i);
; #pragma unroll
;       for (int jj = 0; jj < 2; ++jj) {
;         const int d = wn * 32 + jj * 16 + g * 4;
;         const f32x4 c = *(const f32x4*)(ctab + s * 64 + d);
;         const f32x4 sn = *(const f32x4*)(stab + s * 64 + d);
; #pragma unroll
;         for (int r = 0; r < 4; ++r) {
;           const float a = acc[i][jj][r], bb = acc[i][jj + 2][r];
;           acc[i][jj][r] = a * c[r] - bb * sn[r];
;           acc[i][jj + 2][r] = bb * c[r] + a * sn[r];
;         }
;       }
;     }
	v_mov_b32_e32 v154, v164
	v_mov_b32_e32 v155, v165
	v_mov_b32_e32 v156, v166
	v_mov_b32_e32 v157, v167
	v_mov_b32_e32 v158, v168
	v_mov_b32_e32 v159, v169
	v_mov_b32_e32 v160, v170
	v_mov_b32_e32 v161, v171
	global_load_dwordx4 v[164:167], v236, s[34:35]
	global_load_dwordx4 v[168:171], v236, s[36:37]
	v_pk_mul_f32 v[116:117], v[88:89], v[158:159]
	v_pk_mul_f32 v[118:119], v[124:125], v[158:159]
	v_pk_fma_f32 v[116:117], v[124:125], v[154:155], v[116:117] neg_lo:[0,0,1] neg_hi:[0,0,1]
	v_pk_fma_f32 v[88:89], v[88:89], v[154:155], v[118:119]
	v_mul_f32_e32 v118, v126, v156
	v_mul_f32_e32 v124, v90, v160
	v_mul_f32_e32 v154, v90, v156
	v_mul_f32_e32 v156, v126, v160
	v_mov_b32_e32 v90, v127
	v_mov_b32_e32 v160, v157
	v_mov_b32_e32 v126, v91
	v_pk_mul_f32 v[158:159], v[90:91], v[160:161]
	v_pk_mul_f32 v[90:91], v[126:127], v[160:161]
	v_mov_b32_e32 v119, v158
	v_mov_b32_e32 v155, v90
	v_mov_b32_e32 v157, v91
	v_mov_b32_e32 v125, v159
	v_pk_add_f32 v[90:91], v[154:155], v[156:157]
	v_pk_add_f32 v[118:119], v[118:119], v[124:125] neg_lo:[0,1] neg_hi:[0,1]
	s_waitcnt vmcnt(14)
	v_mov_b32_e32 v154, v172
	v_mov_b32_e32 v155, v173
	v_mov_b32_e32 v156, v174
	v_mov_b32_e32 v157, v175
	v_mov_b32_e32 v158, v176
	v_mov_b32_e32 v159, v177
	v_mov_b32_e32 v160, v178
	v_mov_b32_e32 v161, v179
	global_load_dwordx4 v[172:175], v236, s[34:35] offset:64
	global_load_dwordx4 v[176:179], v236, s[36:37] offset:64
	v_add_u32_e32 v236, 0x1000, v236
	v_pk_mul_f32 v[124:125], v[84:85], v[158:159]
	v_pk_mul_f32 v[126:127], v[150:151], v[158:159]
	v_pk_fma_f32 v[124:125], v[150:151], v[154:155], v[124:125] neg_lo:[0,0,1] neg_hi:[0,0,1]
	v_pk_fma_f32 v[84:85], v[84:85], v[154:155], v[126:127]
	v_mul_f32_e32 v132, v86, v160
	v_mul_f32_e32 v150, v86, v156
	v_mul_f32_e32 v154, v152, v160
	v_mov_b32_e32 v86, v153
	v_mov_b32_e32 v160, v157
	v_mul_f32_e32 v126, v152, v156
	v_pk_mul_f32 v[156:157], v[86:87], v[160:161]
	v_mov_b32_e32 v152, v87
	v_mov_b32_e32 v127, v156
	v_mov_b32_e32 v133, v157
	v_pk_add_f32 v[126:127], v[126:127], v[132:133] neg_lo:[0,1] neg_hi:[0,1]
	v_or_b32_e32 v132, 0x400, v2
	v_pk_mul_f32 v[86:87], v[152:153], v[160:161]
	v_ashrrev_i32_e32 v133, 31, v132
	v_mov_b32_e32 v151, v86
	v_mov_b32_e32 v155, v87
	v_lshlrev_b64 v[132:133], 2, v[132:133]
	v_pk_add_f32 v[86:87], v[150:151], v[154:155]
	v_lshl_add_u64 v[150:151], s[34:35], 0, v[132:133]
	v_lshl_add_u64 v[132:133], s[36:37], 0, v[132:133]
	v_lshl_add_u64 v[158:159], v[150:151], 0, v[0:1]
	v_lshl_add_u64 v[160:161], v[132:133], 0, v[0:1]
	s_waitcnt vmcnt(14)
	v_mov_b32_e32 v150, v180
	v_mov_b32_e32 v151, v181
	v_mov_b32_e32 v152, v182
	v_mov_b32_e32 v153, v183
	v_mov_b32_e32 v154, v184
	v_mov_b32_e32 v155, v185
	v_mov_b32_e32 v156, v186
	v_mov_b32_e32 v157, v187
	global_load_dwordx4 v[180:183], v236, s[34:35]
	global_load_dwordx4 v[184:187], v236, s[36:37]
	v_pk_mul_f32 v[132:133], v[80:81], v[154:155]
	s_nop 0
	v_pk_fma_f32 v[132:133], v[134:135], v[150:151], v[132:133] neg_lo:[0,0,1] neg_hi:[0,0,1]
	v_pk_mul_f32 v[134:135], v[134:135], v[154:155]
	v_mul_f32_e32 v154, v136, v156
	v_pk_fma_f32 v[80:81], v[80:81], v[150:151], v[134:135]
	v_mul_f32_e32 v134, v136, v152
	v_mul_f32_e32 v150, v82, v156
	v_mul_f32_e32 v152, v82, v152
	v_mov_b32_e32 v82, v137
	v_mov_b32_e32 v156, v153
	v_mov_b32_e32 v136, v83
	v_pk_mul_f32 v[162:163], v[82:83], v[156:157]
	v_pk_mul_f32 v[82:83], v[136:137], v[156:157]
	v_mov_b32_e32 v135, v162
	v_mov_b32_e32 v151, v163
	v_mov_b32_e32 v153, v82
	v_mov_b32_e32 v155, v83
	v_pk_add_f32 v[134:135], v[134:135], v[150:151] neg_lo:[0,1] neg_hi:[0,1]
	v_pk_add_f32 v[82:83], v[152:153], v[154:155]
	s_waitcnt vmcnt(14)
	v_mov_b32_e32 v150, v188
	v_mov_b32_e32 v151, v189
	v_mov_b32_e32 v152, v190
	v_mov_b32_e32 v153, v191
	v_mov_b32_e32 v154, v192
	v_mov_b32_e32 v155, v193
	v_mov_b32_e32 v156, v194
	v_mov_b32_e32 v157, v195
	global_load_dwordx4 v[188:191], v236, s[34:35] offset:64
	global_load_dwordx4 v[192:195], v236, s[36:37] offset:64
	v_add_u32_e32 v236, 0x1000, v236
	v_pk_mul_f32 v[136:137], v[72:73], v[154:155]
	s_nop 0
	v_pk_fma_f32 v[136:137], v[138:139], v[150:151], v[136:137] neg_lo:[0,0,1] neg_hi:[0,0,1]
	v_pk_mul_f32 v[138:139], v[138:139], v[154:155]
	v_mul_f32_e32 v154, v140, v156
	v_pk_fma_f32 v[72:73], v[72:73], v[150:151], v[138:139]
	v_mul_f32_e32 v138, v140, v152
	v_mul_f32_e32 v150, v74, v156
	v_mul_f32_e32 v152, v74, v152
	v_mov_b32_e32 v74, v141
	v_mov_b32_e32 v156, v153
	v_mov_b32_e32 v140, v75
	v_pk_mul_f32 v[158:159], v[74:75], v[156:157]
	v_pk_mul_f32 v[74:75], v[140:141], v[156:157]
	v_or_b32_e32 v140, 0x800, v2
	v_ashrrev_i32_e32 v141, 31, v140
	v_mov_b32_e32 v139, v158
	v_mov_b32_e32 v151, v159
	v_lshlrev_b64 v[140:141], 2, v[140:141]
	v_pk_add_f32 v[138:139], v[138:139], v[150:151] neg_lo:[0,1] neg_hi:[0,1]
	v_lshl_add_u64 v[150:151], s[34:35], 0, v[140:141]
	v_lshl_add_u64 v[140:141], s[36:37], 0, v[140:141]
	v_mov_b32_e32 v153, v74
	v_mov_b32_e32 v155, v75
	v_lshl_add_u64 v[158:159], v[150:151], 0, v[0:1]
	v_lshl_add_u64 v[160:161], v[140:141], 0, v[0:1]
	v_pk_add_f32 v[74:75], v[152:153], v[154:155]
	s_waitcnt vmcnt(14)
; __device__ void even_in_tile(const P& p, int li_even, int tm, int tn, char* smem) {
;     ...
; #pragma unroll
;     for (int i = 0; i < MI; ++i) {
;       const int s = s0 + MROW(i);
; #pragma unroll
;       for (int jj = 0; jj < 2; ++jj) {
;         const int d = wn * 32 + jj * 16 + g * 4;
;         const f32x4 c = *(const f32x4*)(ctab + s * 64 + d);
;         const f32x4 sn = *(const f32x4*)(stab + s * 64 + d);
; #pragma unroll
;         for (int r = 0; r < 4; ++r) {
;           const float a = acc[i][jj][r], bb = acc[i][jj + 2][r];
;           acc[i][jj][r] = a * c[r] - bb * sn[r];
;           acc[i][jj + 2][r] = bb * c[r] + a * sn[r];
;         }
;       }
;     }
	v_mov_b32_e32 v150, v196
	v_mov_b32_e32 v151, v197
	v_mov_b32_e32 v152, v198
	v_mov_b32_e32 v153, v199
	v_mov_b32_e32 v154, v200
	v_mov_b32_e32 v155, v201
	v_mov_b32_e32 v156, v202
	v_mov_b32_e32 v157, v203
	global_load_dwordx4 v[196:199], v236, s[34:35]
	global_load_dwordx4 v[200:203], v236, s[36:37]
	v_pk_mul_f32 v[140:141], v[68:69], v[154:155]
	s_nop 0
	v_pk_fma_f32 v[140:141], v[142:143], v[150:151], v[140:141] neg_lo:[0,0,1] neg_hi:[0,0,1]
	v_pk_mul_f32 v[142:143], v[142:143], v[154:155]
	v_mul_f32_e32 v154, v144, v156
	v_pk_fma_f32 v[68:69], v[68:69], v[150:151], v[142:143]
	v_mul_f32_e32 v142, v144, v152
	v_mul_f32_e32 v150, v70, v156
	v_mul_f32_e32 v152, v70, v152
	v_mov_b32_e32 v70, v145
	v_mov_b32_e32 v156, v153
	v_mov_b32_e32 v144, v71
	v_pk_mul_f32 v[162:163], v[70:71], v[156:157]
	v_pk_mul_f32 v[70:71], v[144:145], v[156:157]
	v_mov_b32_e32 v143, v162
	v_mov_b32_e32 v151, v163
	v_mov_b32_e32 v153, v70
	v_mov_b32_e32 v155, v71
	v_pk_add_f32 v[142:143], v[142:143], v[150:151] neg_lo:[0,1] neg_hi:[0,1]
	v_pk_add_f32 v[70:71], v[152:153], v[154:155]
	s_waitcnt vmcnt(14)
	v_mov_b32_e32 v150, v204
	v_mov_b32_e32 v151, v205
	v_mov_b32_e32 v152, v206
	v_mov_b32_e32 v153, v207
	v_mov_b32_e32 v154, v220
	v_mov_b32_e32 v155, v221
	v_mov_b32_e32 v156, v222
	v_mov_b32_e32 v157, v223
	global_load_dwordx4 v[204:207], v236, s[34:35] offset:64
	global_load_dwordx4 v[220:223], v236, s[36:37] offset:64
	v_add_u32_e32 v236, 0x1000, v236
	v_pk_mul_f32 v[144:145], v[64:65], v[154:155]
	s_nop 0
	v_pk_fma_f32 v[144:145], v[146:147], v[150:151], v[144:145] neg_lo:[0,0,1] neg_hi:[0,0,1]
	v_pk_mul_f32 v[146:147], v[146:147], v[154:155]
	v_mul_f32_e32 v154, v148, v156
	v_pk_fma_f32 v[64:65], v[64:65], v[150:151], v[146:147]
	v_mul_f32_e32 v146, v148, v152
	v_mul_f32_e32 v150, v66, v156
	v_mul_f32_e32 v152, v66, v152
	v_mov_b32_e32 v66, v149
	v_mov_b32_e32 v156, v153
	v_mov_b32_e32 v148, v67
	v_pk_mul_f32 v[158:159], v[66:67], v[156:157]
	v_pk_mul_f32 v[66:67], v[148:149], v[156:157]
	v_or_b32_e32 v148, 0xc00, v2
	v_ashrrev_i32_e32 v149, 31, v148
	v_mov_b32_e32 v147, v158
	v_mov_b32_e32 v151, v159
	v_lshlrev_b64 v[148:149], 2, v[148:149]
	v_pk_add_f32 v[146:147], v[146:147], v[150:151] neg_lo:[0,1] neg_hi:[0,1]
	v_lshl_add_u64 v[150:151], s[34:35], 0, v[148:149]
	v_lshl_add_u64 v[148:149], s[36:37], 0, v[148:149]
	v_mov_b32_e32 v153, v66
	v_mov_b32_e32 v155, v67
	v_lshl_add_u64 v[158:159], v[150:151], 0, v[0:1]
	v_lshl_add_u64 v[160:161], v[148:149], 0, v[0:1]
	v_pk_add_f32 v[66:67], v[152:153], v[154:155]
	s_waitcnt vmcnt(14)
	v_mov_b32_e32 v150, v224
	v_mov_b32_e32 v151, v225
	v_mov_b32_e32 v152, v226
	v_mov_b32_e32 v153, v227
	v_mov_b32_e32 v154, v228
	v_mov_b32_e32 v155, v229
	v_mov_b32_e32 v156, v230
	v_mov_b32_e32 v157, v231
	global_load_dwordx4 v[224:227], v236, s[34:35]
	global_load_dwordx4 v[228:231], v236, s[36:37]
	v_pk_mul_f32 v[148:149], v[60:61], v[154:155]
	s_nop 0
	v_pk_fma_f32 v[148:149], v[128:129], v[150:151], v[148:149] neg_lo:[0,0,1] neg_hi:[0,0,1]
	v_pk_mul_f32 v[128:129], v[128:129], v[154:155]
	v_mul_f32_e32 v154, v130, v156
	v_pk_fma_f32 v[60:61], v[60:61], v[150:151], v[128:129]
	v_mul_f32_e32 v128, v130, v152
	v_mul_f32_e32 v150, v62, v156
	v_mul_f32_e32 v152, v62, v152
	v_mov_b32_e32 v62, v131
	v_mov_b32_e32 v156, v153
	v_mov_b32_e32 v130, v63
	v_pk_mul_f32 v[162:163], v[62:63], v[156:157]
	v_pk_mul_f32 v[62:63], v[130:131], v[156:157]
	v_mov_b32_e32 v129, v162
	v_mov_b32_e32 v153, v62
	v_mov_b32_e32 v155, v63
	v_pk_add_f32 v[62:63], v[152:153], v[154:155]
	s_nop 0
	v_mov_b32_e32 v151, v163
	v_pk_add_f32 v[150:151], v[128:129], v[150:151] neg_lo:[0,1] neg_hi:[0,1]
	s_waitcnt vmcnt(14)
	v_mov_b32_e32 v152, v232
	v_mov_b32_e32 v153, v233
	v_mov_b32_e32 v154, v234
	v_mov_b32_e32 v155, v235
	v_mov_b32_e32 v156, v4
	v_mov_b32_e32 v157, v5
	v_mov_b32_e32 v158, v6
	v_mov_b32_e32 v159, v7
	global_load_dwordx4 v[232:235], v236, s[34:35] offset:64
	global_load_dwordx4 v[4:7], v236, s[36:37] offset:64
	v_pk_mul_f32 v[128:129], v[56:57], v[156:157]
	s_nop 0
	v_pk_fma_f32 v[128:129], v[120:121], v[152:153], v[128:129] neg_lo:[0,0,1] neg_hi:[0,0,1]
	v_pk_mul_f32 v[120:121], v[120:121], v[156:157]
	v_mul_f32_e32 v130, v58, v158
	v_pk_fma_f32 v[56:57], v[56:57], v[152:153], v[120:121]
	v_mul_f32_e32 v120, v122, v154
	v_mul_f32_e32 v152, v58, v154
	v_mul_f32_e32 v154, v122, v158
	v_mov_b32_e32 v58, v123
	v_mov_b32_e32 v158, v155
	v_pk_mul_f32 v[156:157], v[58:59], v[158:159]
	v_mov_b32_e32 v122, v59
	v_mov_b32_e32 v121, v156
	v_mov_b32_e32 v131, v157
	v_pk_add_f32 v[130:131], v[120:121], v[130:131] neg_lo:[0,1] neg_hi:[0,1]
	v_or_b32_e32 v120, 0x1000, v2
	v_ashrrev_i32_e32 v121, 31, v120
	v_lshlrev_b64 v[120:121], 2, v[120:121]
	v_pk_mul_f32 v[58:59], v[122:123], v[158:159]
	v_lshl_add_u64 v[122:123], s[34:35], 0, v[120:121]
	v_lshl_add_u64 v[120:121], s[36:37], 0, v[120:121]
	v_mov_b32_e32 v153, v58
	v_mov_b32_e32 v155, v59
	v_lshl_add_u64 v[160:161], v[122:123], 0, v[0:1]
	v_lshl_add_u64 v[162:163], v[120:121], 0, v[0:1]
	v_pk_add_f32 v[58:59], v[152:153], v[154:155]
	s_waitcnt vmcnt(14)
	v_mov_b32_e32 v152, v164
	v_mov_b32_e32 v153, v165
	v_mov_b32_e32 v154, v166
	v_mov_b32_e32 v155, v167
	v_mov_b32_e32 v156, v168
	v_mov_b32_e32 v157, v169
	v_mov_b32_e32 v158, v170
	v_mov_b32_e32 v159, v171
	v_pk_mul_f32 v[120:121], v[52:53], v[156:157]
	s_nop 0
	v_pk_fma_f32 v[120:121], v[112:113], v[152:153], v[120:121] neg_lo:[0,0,1] neg_hi:[0,0,1]
	v_pk_mul_f32 v[112:113], v[112:113], v[156:157]
	v_mul_f32_e32 v122, v54, v158
	v_pk_fma_f32 v[52:53], v[52:53], v[152:153], v[112:113]
	v_mul_f32_e32 v112, v114, v154
	v_mul_f32_e32 v152, v54, v154
	v_mul_f32_e32 v154, v114, v158
	v_mov_b32_e32 v54, v115
	v_mov_b32_e32 v158, v155
	v_mov_b32_e32 v114, v55
	v_pk_mul_f32 v[156:157], v[54:55], v[158:159]
	v_pk_mul_f32 v[54:55], v[114:115], v[158:159]
	v_mov_b32_e32 v113, v156
	v_mov_b32_e32 v153, v54
	v_mov_b32_e32 v155, v55
	v_mov_b32_e32 v123, v157
	v_pk_add_f32 v[54:55], v[152:153], v[154:155]
	v_pk_add_f32 v[122:123], v[112:113], v[122:123] neg_lo:[0,1] neg_hi:[0,1]
	s_waitcnt vmcnt(12)
; __device__ void even_in_tile(const P& p, int li_even, int tm, int tn, char* smem) {
;     ...
; #pragma unroll
;     for (int i = 0; i < MI; ++i) {
;       const int s = s0 + MROW(i);
; #pragma unroll
;       for (int jj = 0; jj < 2; ++jj) {
;         const int d = wn * 32 + jj * 16 + g * 4;
;         const f32x4 c = *(const f32x4*)(ctab + s * 64 + d);
;         const f32x4 sn = *(const f32x4*)(stab + s * 64 + d);
; #pragma unroll
;         for (int r = 0; r < 4; ++r) {
;           const float a = acc[i][jj][r], bb = acc[i][jj + 2][r];
;           acc[i][jj][r] = a * c[r] - bb * sn[r];
;           acc[i][jj + 2][r] = bb * c[r] + a * sn[r];
;         }
;       }
;     }
	v_mov_b32_e32 v152, v172
	v_mov_b32_e32 v153, v173
	v_mov_b32_e32 v154, v174
	v_mov_b32_e32 v155, v175
	v_mov_b32_e32 v156, v176
	v_mov_b32_e32 v157, v177
	v_mov_b32_e32 v158, v178
	v_mov_b32_e32 v159, v179
	v_pk_mul_f32 v[112:113], v[48:49], v[156:157]
	s_nop 0
	v_pk_fma_f32 v[112:113], v[108:109], v[152:153], v[112:113] neg_lo:[0,0,1] neg_hi:[0,0,1]
	v_pk_mul_f32 v[108:109], v[108:109], v[156:157]
	v_mul_f32_e32 v114, v50, v158
	v_pk_fma_f32 v[48:49], v[48:49], v[152:153], v[108:109]
	v_mul_f32_e32 v108, v110, v154
	v_mul_f32_e32 v152, v50, v154
	v_mul_f32_e32 v154, v110, v158
	v_mov_b32_e32 v50, v111
	v_mov_b32_e32 v158, v155
	v_pk_mul_f32 v[156:157], v[50:51], v[158:159]
	v_mov_b32_e32 v110, v51
	v_mov_b32_e32 v109, v156
	v_mov_b32_e32 v115, v157
	v_pk_add_f32 v[114:115], v[108:109], v[114:115] neg_lo:[0,1] neg_hi:[0,1]
	v_or_b32_e32 v108, 0x1400, v2
	v_ashrrev_i32_e32 v109, 31, v108
	v_lshlrev_b64 v[108:109], 2, v[108:109]
	v_pk_mul_f32 v[50:51], v[110:111], v[158:159]
	v_lshl_add_u64 v[110:111], s[34:35], 0, v[108:109]
	v_lshl_add_u64 v[108:109], s[36:37], 0, v[108:109]
	v_mov_b32_e32 v153, v50
	v_mov_b32_e32 v155, v51
	v_lshl_add_u64 v[160:161], v[110:111], 0, v[0:1]
	v_lshl_add_u64 v[162:163], v[108:109], 0, v[0:1]
	v_pk_add_f32 v[50:51], v[152:153], v[154:155]
	s_waitcnt vmcnt(10)
	v_mov_b32_e32 v152, v180
	v_mov_b32_e32 v153, v181
	v_mov_b32_e32 v154, v182
	v_mov_b32_e32 v155, v183
	v_mov_b32_e32 v156, v184
	v_mov_b32_e32 v157, v185
	v_mov_b32_e32 v158, v186
	v_mov_b32_e32 v159, v187
	v_pk_mul_f32 v[108:109], v[44:45], v[156:157]
	s_nop 0
	v_pk_fma_f32 v[108:109], v[104:105], v[152:153], v[108:109] neg_lo:[0,0,1] neg_hi:[0,0,1]
	v_pk_mul_f32 v[104:105], v[104:105], v[156:157]
	v_mul_f32_e32 v110, v46, v158
	v_pk_fma_f32 v[44:45], v[44:45], v[152:153], v[104:105]
	v_mul_f32_e32 v104, v106, v154
	v_mul_f32_e32 v152, v46, v154
	v_mul_f32_e32 v154, v106, v158
	v_mov_b32_e32 v46, v107
	v_mov_b32_e32 v158, v155
	v_mov_b32_e32 v106, v47
	v_pk_mul_f32 v[156:157], v[46:47], v[158:159]
	v_pk_mul_f32 v[46:47], v[106:107], v[158:159]
	v_mov_b32_e32 v105, v156
	v_mov_b32_e32 v153, v46
	v_mov_b32_e32 v155, v47
	v_mov_b32_e32 v111, v157
	v_pk_add_f32 v[46:47], v[152:153], v[154:155]
	v_pk_add_f32 v[110:111], v[104:105], v[110:111] neg_lo:[0,1] neg_hi:[0,1]
	s_waitcnt vmcnt(8)
	v_mov_b32_e32 v152, v188
	v_mov_b32_e32 v153, v189
	v_mov_b32_e32 v154, v190
	v_mov_b32_e32 v155, v191
	v_mov_b32_e32 v156, v192
	v_mov_b32_e32 v157, v193
	v_mov_b32_e32 v158, v194
	v_mov_b32_e32 v159, v195
	v_pk_mul_f32 v[104:105], v[40:41], v[156:157]
	s_nop 0
	v_pk_fma_f32 v[104:105], v[100:101], v[152:153], v[104:105] neg_lo:[0,0,1] neg_hi:[0,0,1]
	v_pk_mul_f32 v[100:101], v[100:101], v[156:157]
	v_mul_f32_e32 v106, v42, v158
	v_pk_fma_f32 v[40:41], v[40:41], v[152:153], v[100:101]
	v_mul_f32_e32 v100, v102, v154
	v_mul_f32_e32 v152, v42, v154
	v_mul_f32_e32 v154, v102, v158
	v_mov_b32_e32 v42, v103
	v_mov_b32_e32 v158, v155
	v_pk_mul_f32 v[156:157], v[42:43], v[158:159]
	v_mov_b32_e32 v102, v43
	v_mov_b32_e32 v101, v156
	v_mov_b32_e32 v107, v157
	v_pk_add_f32 v[106:107], v[100:101], v[106:107] neg_lo:[0,1] neg_hi:[0,1]
	v_or_b32_e32 v100, 0x1800, v2
	v_ashrrev_i32_e32 v101, 31, v100
	v_lshlrev_b64 v[100:101], 2, v[100:101]
	v_pk_mul_f32 v[42:43], v[102:103], v[158:159]
	v_lshl_add_u64 v[102:103], s[34:35], 0, v[100:101]
	v_lshl_add_u64 v[100:101], s[36:37], 0, v[100:101]
	v_mov_b32_e32 v153, v42
	v_mov_b32_e32 v155, v43
	v_lshl_add_u64 v[160:161], v[102:103], 0, v[0:1]
	v_lshl_add_u64 v[162:163], v[100:101], 0, v[0:1]
	v_pk_add_f32 v[42:43], v[152:153], v[154:155]
	v_or_b32_e32 v2, 0x1c00, v2
	v_ashrrev_i32_e32 v3, 31, v2
	v_lshlrev_b64 v[2:3], 2, v[2:3]
	s_waitcnt vmcnt(6)
	v_mov_b32_e32 v152, v196
	v_mov_b32_e32 v153, v197
	v_mov_b32_e32 v154, v198
	v_mov_b32_e32 v155, v199
	v_mov_b32_e32 v156, v200
	v_mov_b32_e32 v157, v201
	v_mov_b32_e32 v158, v202
	v_mov_b32_e32 v159, v203
	v_pk_mul_f32 v[100:101], v[36:37], v[156:157]
	s_nop 0
	v_pk_fma_f32 v[100:101], v[96:97], v[152:153], v[100:101] neg_lo:[0,0,1] neg_hi:[0,0,1]
	v_pk_mul_f32 v[96:97], v[96:97], v[156:157]
	v_mul_f32_e32 v102, v38, v158
	v_pk_fma_f32 v[36:37], v[36:37], v[152:153], v[96:97]
	v_mul_f32_e32 v96, v98, v154
	v_mul_f32_e32 v152, v38, v154
	v_mul_f32_e32 v154, v98, v158
	v_mov_b32_e32 v38, v99
	v_mov_b32_e32 v158, v155
	v_mov_b32_e32 v98, v39
	v_pk_mul_f32 v[156:157], v[38:39], v[158:159]
	v_pk_mul_f32 v[38:39], v[98:99], v[158:159]
	v_mov_b32_e32 v97, v156
	v_mov_b32_e32 v153, v38
	v_mov_b32_e32 v155, v39
	v_mov_b32_e32 v103, v157
	v_pk_add_f32 v[38:39], v[152:153], v[154:155]
	v_pk_add_f32 v[102:103], v[96:97], v[102:103] neg_lo:[0,1] neg_hi:[0,1]
	s_waitcnt vmcnt(4)
; __device__ void even_in_tile(const P& p, int li_even, int tm, int tn, char* smem) {
;     ...
; #pragma unroll
;     for (int i = 0; i < MI; ++i) {
;       const int s = s0 + MROW(i);
; #pragma unroll
;       for (int jj = 0; jj < 2; ++jj) {
;         const int d = wn * 32 + jj * 16 + g * 4;
;         const f32x4 c = *(const f32x4*)(ctab + s * 64 + d);
;         const f32x4 sn = *(const f32x4*)(stab + s * 64 + d);
; #pragma unroll
;         for (int r = 0; r < 4; ++r) {
;           const float a = acc[i][jj][r], bb = acc[i][jj + 2][r];
;           acc[i][jj][r] = a * c[r] - bb * sn[r];
;           acc[i][jj + 2][r] = bb * c[r] + a * sn[r];
;         }
;       }
;     }
;   }
;   if (seg == 1) {
	v_mov_b32_e32 v152, v204
	v_mov_b32_e32 v153, v205
	v_mov_b32_e32 v154, v206
	v_mov_b32_e32 v155, v207
	v_mov_b32_e32 v156, v220
	v_mov_b32_e32 v157, v221
	v_mov_b32_e32 v158, v222
	v_mov_b32_e32 v159, v223
	v_pk_mul_f32 v[96:97], v[32:33], v[156:157]
	s_nop 0
	v_pk_fma_f32 v[96:97], v[92:93], v[152:153], v[96:97] neg_lo:[0,0,1] neg_hi:[0,0,1]
	v_pk_mul_f32 v[92:93], v[92:93], v[156:157]
	v_mul_f32_e32 v98, v34, v158
	v_pk_fma_f32 v[32:33], v[32:33], v[152:153], v[92:93]
	v_mul_f32_e32 v92, v94, v154
	v_mul_f32_e32 v152, v34, v154
	v_mul_f32_e32 v154, v94, v158
	v_mov_b32_e32 v34, v95
	v_mov_b32_e32 v158, v155
	v_pk_mul_f32 v[156:157], v[34:35], v[158:159]
	v_mov_b32_e32 v94, v35
	v_mov_b32_e32 v93, v156
	v_mov_b32_e32 v99, v157
	v_pk_add_f32 v[98:99], v[92:93], v[98:99] neg_lo:[0,1] neg_hi:[0,1]
	v_pk_mul_f32 v[34:35], v[94:95], v[158:159]
	v_lshl_add_u64 v[92:93], s[34:35], 0, v[2:3]
	v_lshl_add_u64 v[2:3], s[36:37], 0, v[2:3]
	v_mov_b32_e32 v153, v34
	v_mov_b32_e32 v155, v35
	v_lshl_add_u64 v[160:161], v[92:93], 0, v[0:1]
	v_lshl_add_u64 v[2:3], v[2:3], 0, v[0:1]
	v_pk_add_f32 v[34:35], v[152:153], v[154:155]
	s_waitcnt vmcnt(2)
	v_mov_b32_e32 v152, v224
	v_mov_b32_e32 v153, v225
	v_mov_b32_e32 v154, v226
	v_mov_b32_e32 v155, v227
	v_mov_b32_e32 v156, v228
	v_mov_b32_e32 v157, v229
	v_mov_b32_e32 v158, v230
	v_mov_b32_e32 v159, v231
	v_pk_mul_f32 v[92:93], v[24:25], v[156:157]
	s_nop 0
	v_pk_fma_f32 v[92:93], v[76:77], v[152:153], v[92:93] neg_lo:[0,0,1] neg_hi:[0,0,1]
	v_pk_mul_f32 v[76:77], v[76:77], v[156:157]
	v_mul_f32_e32 v94, v26, v158
	v_pk_fma_f32 v[24:25], v[24:25], v[152:153], v[76:77]
	v_mul_f32_e32 v76, v78, v154
	v_mul_f32_e32 v152, v26, v154
	v_mul_f32_e32 v154, v78, v158
	v_mov_b32_e32 v26, v79
	v_mov_b32_e32 v158, v155
	v_mov_b32_e32 v78, v27
	v_pk_mul_f32 v[156:157], v[26:27], v[158:159]
	v_pk_mul_f32 v[26:27], v[78:79], v[158:159]
	v_mov_b32_e32 v77, v156
	v_mov_b32_e32 v95, v157
	v_mov_b32_e32 v153, v26
	v_mov_b32_e32 v155, v27
	v_pk_add_f32 v[94:95], v[76:77], v[94:95] neg_lo:[0,1] neg_hi:[0,1]
	v_pk_add_f32 v[26:27], v[152:153], v[154:155]
	s_waitcnt vmcnt(0)
	v_mov_b32_e32 v76, v232
	v_mov_b32_e32 v77, v233
	v_mov_b32_e32 v78, v234
	v_mov_b32_e32 v79, v235
	v_mov_b32_e32 v152, v4
	v_mov_b32_e32 v153, v5
	v_mov_b32_e32 v154, v6
	v_mov_b32_e32 v155, v7
	v_pk_mul_f32 v[2:3], v[20:21], v[152:153]
	s_nop 0
	v_pk_fma_f32 v[156:157], v[28:29], v[76:77], v[2:3] neg_lo:[0,0,1] neg_hi:[0,0,1]
	v_pk_mul_f32 v[2:3], v[28:29], v[152:153]
	v_mul_f32_e32 v28, v22, v154
	v_pk_fma_f32 v[20:21], v[20:21], v[76:77], v[2:3]
	v_mul_f32_e32 v2, v30, v78
	v_mul_f32_e32 v76, v22, v78
	v_mul_f32_e32 v78, v30, v154
	v_mov_b32_e32 v22, v31
	v_mov_b32_e32 v154, v79
	v_pk_mul_f32 v[152:153], v[22:23], v[154:155]
	v_mov_b32_e32 v30, v23
	v_mov_b32_e32 v3, v152
	v_mov_b32_e32 v29, v153
	v_pk_add_f32 v[158:159], v[2:3], v[28:29] neg_lo:[0,1] neg_hi:[0,1]
	v_pk_mul_f32 v[2:3], v[30:31], v[154:155]
	v_mov_b64_e32 v[28:29], v[156:157]
	v_mov_b32_e32 v77, v2
	v_mov_b32_e32 v79, v3
	v_pk_add_f32 v[22:23], v[76:77], v[78:79]
	v_mov_b64_e32 v[76:77], v[92:93]
	v_mov_b64_e32 v[78:79], v[94:95]
	v_mov_b64_e32 v[92:93], v[96:97]
	v_mov_b64_e32 v[94:95], v[98:99]
	v_mov_b64_e32 v[96:97], v[100:101]
	v_mov_b64_e32 v[98:99], v[102:103]
	v_mov_b64_e32 v[100:101], v[104:105]
	v_mov_b64_e32 v[102:103], v[106:107]
	v_mov_b64_e32 v[104:105], v[108:109]
	v_mov_b64_e32 v[106:107], v[110:111]
	v_mov_b64_e32 v[108:109], v[112:113]
	v_mov_b64_e32 v[110:111], v[114:115]
	v_mov_b64_e32 v[112:113], v[120:121]
	v_mov_b64_e32 v[114:115], v[122:123]
	v_mov_b64_e32 v[120:121], v[128:129]
	v_mov_b64_e32 v[122:123], v[130:131]
	v_mov_b64_e32 v[128:129], v[148:149]
	v_mov_b64_e32 v[130:131], v[150:151]
	v_mov_b64_e32 v[148:149], v[146:147]
	v_mov_b64_e32 v[146:147], v[144:145]
	v_mov_b64_e32 v[144:145], v[142:143]
	v_mov_b64_e32 v[142:143], v[140:141]
	v_mov_b64_e32 v[140:141], v[138:139]
	v_mov_b64_e32 v[152:153], v[126:127]
	v_mov_b64_e32 v[138:139], v[136:137]
	v_mov_b64_e32 v[136:137], v[134:135]
	v_mov_b64_e32 v[150:151], v[124:125]
	v_mov_b64_e32 v[126:127], v[118:119]
	v_mov_b64_e32 v[30:31], v[158:159]
	v_mov_b64_e32 v[134:135], v[132:133]
	v_mov_b64_e32 v[124:125], v[116:117]
	s_cmp_eq_u32 s42, 1
	s_cselect_b64 s[34:35], -1, 0
	s_cmp_lg_u32 s42, 1
	s_cbranch_scc0 .LBB0_316

; template <int MI, bool SWAP, bool F8 = false>
; __device__ __forceinline__ void gemm_core(const bf16_t* __restrict__ A, int lda, const bf16_t* __restrict__ B, int ldb,
;                                           int K, char* smem, f32x4 (&acc)[MI][4]) {
;     ...
;   for (int kt = 0; kt < nk; ++kt) {
;     __syncthreads();
; #pragma unroll
;     for (int i = 0; i < MI; ++i) *(u32x4*)(smem + woff + i * 4096) = ra[i];
; #pragma unroll
;     for (int i = 0; i < 4; ++i) *(u32x4*)(smem + 32768 + woff + i * 4096) = rb[i];
;     __syncthreads();
;     if (kt + 1 < nk) {
; #pragma unroll
;       for (int i = 0; i < MI; ++i) ra[i] = *(const u32x4*)(ap + (size_t)(32 * i) * lda + (kt + 1) * 64);
; #pragma unroll
;       for (int i = 0; i < 4; ++i) rb[i] = *(const u32x4*)(bp + (size_t)(32 * i) * ldb + (kt + 1) * 64);
;     }
;     if (F8) {
;       const int c0 = (g ^ (li & 7)) << 4, c1 = ((4 + g) ^ (li & 7)) << 4;
;       i32x8 wf8[4];
; #pragma unroll
;       for (int j = 0; j < 4; ++j) {
;         const char* rp = smem + wrow + ((j & 1) * 16 + (j >> 1) * 64) * 128;
;         const u32x4 lo = *(const u32x4*)(rp + c0), hi = *(const u32x4*)(rp + c1);
;         wf8[j] = (i32x8){(int)lo.x, (int)lo.y, (int)lo.z, (int)lo.w, (int)hi.x, (int)hi.y, (int)hi.z, (int)hi.w};
;       }
; #pragma unroll
;       for (int i = 0; i < MI; ++i) {
;         const char* rp = smem + xrow + i * 2048;
;         const u32x4 lo = *(const u32x4*)(rp + c0), hi = *(const u32x4*)(rp + c1);
;         const i32x8 xf8 = {(int)lo.x, (int)lo.y, (int)lo.z, (int)lo.w, (int)hi.x, (int)hi.y, (int)hi.z, (int)hi.w};
; #pragma unroll
;         for (int j = 0; j < 4; ++j)
;           acc[i][j] = __builtin_amdgcn_mfma_scale_f32_16x16x128_f8f6f4(wf8[j], xf8, acc[i][j], 0, 0, 0, 0x77777777, 0, 0x7f7f7f7f);
;       }
;     } else {
; #pragma unroll
;     for (int kk = 0; kk < 2; ++kk) {
;       const int ch = ((kk * 4 + g) ^ (li & 7)) << 4;
;       bf16x8 xf[MI], wf[4];
; #pragma unroll
;       for (int j = 0; j < 4; ++j) wf[j] = *(const bf16x8*)(smem + wrow + ((j & 1) * 16 + (j >> 1) * 64) * 128 + ch);
; #pragma unroll
;       for (int i = 0; i < MI; ++i) xf[i] = *(const bf16x8*)(smem + xrow + i * 2048 + ch);
; #pragma unroll
;       for (int i = 0; i < MI; ++i)
; #pragma unroll
;         for (int j = 0; j < 4; ++j) {
.LBB0_313:
	v_add_u32_e32 v215, v204, v205
	v_add_u32_e32 v213, v203, v205
	s_waitcnt vmcnt(63) expcnt(7) lgkmcnt(15)
	s_barrier
	s_setprio 3
	s_mov_b32 m0, s62
	s_nop 0
	global_load_lds_dwordx4 v252, s[56:57]
	s_add_u32 m0, s62, 0x1000
	s_nop 0
	global_load_lds_dwordx4 v253, s[56:57]
	s_add_u32 s56, s56, 0x20000
	s_addc_u32 s57, s57, 0
	s_add_u32 m0, s62, 0x2000
	s_nop 0
	global_load_lds_dwordx4 v252, s[56:57]
	s_add_u32 m0, s62, 0x3000
	s_nop 0
	global_load_lds_dwordx4 v253, s[56:57]
	s_add_u32 s56, s56, 0x20000
	s_addc_u32 s57, s57, 0
	s_add_u32 m0, s62, 0x4000
	s_nop 0
	global_load_lds_dwordx4 v252, s[56:57]
	s_add_u32 m0, s62, 0x5000
	s_nop 0
	global_load_lds_dwordx4 v253, s[56:57]
	s_add_u32 s56, s56, 0x20000
	s_addc_u32 s57, s57, 0
	s_add_u32 m0, s62, 0x6000
	s_nop 0
	global_load_lds_dwordx4 v252, s[56:57]
	s_add_u32 m0, s62, 0x7000
	s_nop 0
	global_load_lds_dwordx4 v253, s[56:57]
	s_sub_u32 s56, s56, 0x60000
	s_subb_u32 s57, s57, 0
	s_add_u32 m0, s62, 0x8000
	s_nop 0
	global_load_lds_dwordx4 v252, s[58:59]
	s_add_u32 m0, s62, 0x9000
	s_nop 0
	global_load_lds_dwordx4 v253, s[58:59]
	s_add_u32 s58, s58, 0x20000
	s_addc_u32 s59, s59, 0
	s_add_u32 m0, s62, 0xa000
	s_nop 0
	global_load_lds_dwordx4 v252, s[58:59]
	s_add_u32 m0, s62, 0xb000
	s_nop 0
	global_load_lds_dwordx4 v253, s[58:59]
	s_sub_u32 s58, s58, 0x20000
	s_subb_u32 s59, s59, 0
	v_add_u32_e32 v252, 0x80, v252
	v_add_u32_e32 v253, 0x80, v253
	s_waitcnt vmcnt(0)
	s_setprio 0
	s_barrier
	ds_read_b128 v[148:151], v213
	ds_read_b128 v[152:155], v215 offset:32768
	ds_read_b128 v[156:159], v215 offset:34816
	ds_read_b128 v[160:163], v213 offset:2048
	ds_read_b128 v[164:167], v215 offset:40960
	ds_read_b128 v[168:171], v215 offset:43008
	s_waitcnt lgkmcnt(4)
	v_mfma_f32_16x16x32_bf16 v[140:143], v[148:151], v[152:155], v[140:143]
	v_add_u32_e32 v0, v203, v206
	v_add_u32_e32 v207, v204, v206
	s_waitcnt lgkmcnt(3)
	v_mfma_f32_16x16x32_bf16 v[136:139], v[148:151], v[156:159], v[136:139]
	s_waitcnt lgkmcnt(1)
	v_mfma_f32_16x16x32_bf16 v[132:135], v[148:151], v[164:167], v[132:135]
	s_waitcnt lgkmcnt(0)
	v_mfma_f32_16x16x32_bf16 v[128:131], v[148:151], v[168:171], v[128:131]
	v_mfma_f32_16x16x32_bf16 v[124:127], v[160:163], v[152:155], v[124:127]
	v_mfma_f32_16x16x32_bf16 v[120:123], v[160:163], v[156:159], v[120:123]
	v_mfma_f32_16x16x32_bf16 v[116:119], v[160:163], v[164:167], v[116:119]
	v_mfma_f32_16x16x32_bf16 v[112:115], v[160:163], v[168:171], v[112:115]
	ds_read_b128 v[148:151], v213 offset:4096
	ds_read_b128 v[160:163], v213 offset:6144
	s_waitcnt lgkmcnt(1)
	v_mfma_f32_16x16x32_bf16 v[108:111], v[148:151], v[152:155], v[108:111]
	v_mfma_f32_16x16x32_bf16 v[104:107], v[148:151], v[156:159], v[104:107]
	v_mfma_f32_16x16x32_bf16 v[100:103], v[148:151], v[164:167], v[100:103]
	v_mfma_f32_16x16x32_bf16 v[96:99], v[148:151], v[168:171], v[96:99]
	s_waitcnt lgkmcnt(0)
	v_mfma_f32_16x16x32_bf16 v[92:95], v[160:163], v[152:155], v[92:95]
	v_mfma_f32_16x16x32_bf16 v[88:91], v[160:163], v[156:159], v[88:91]
	v_mfma_f32_16x16x32_bf16 v[80:83], v[160:163], v[164:167], v[80:83]
	v_mfma_f32_16x16x32_bf16 v[72:75], v[160:163], v[168:171], v[72:75]
	ds_read_b128 v[148:151], v213 offset:8192
	ds_read_b128 v[160:163], v213 offset:10240
	s_waitcnt lgkmcnt(1)
	v_mfma_f32_16x16x32_bf16 v[64:67], v[148:151], v[152:155], v[64:67]
	v_mfma_f32_16x16x32_bf16 v[60:63], v[148:151], v[156:159], v[60:63]
	v_mfma_f32_16x16x32_bf16 v[52:55], v[148:151], v[164:167], v[52:55]
	v_mfma_f32_16x16x32_bf16 v[48:51], v[148:151], v[168:171], v[48:51]
	s_waitcnt lgkmcnt(0)
	v_mfma_f32_16x16x32_bf16 v[44:47], v[160:163], v[152:155], v[44:47]
	v_mfma_f32_16x16x32_bf16 v[40:43], v[160:163], v[156:159], v[40:43]
	v_mfma_f32_16x16x32_bf16 v[36:39], v[160:163], v[164:167], v[36:39]
	v_mfma_f32_16x16x32_bf16 v[32:35], v[160:163], v[168:171], v[32:35]
	ds_read_b128 v[148:151], v213 offset:12288
	ds_read_b128 v[160:163], v213 offset:14336
	s_waitcnt lgkmcnt(1)
	v_mfma_f32_16x16x32_bf16 v[24:27], v[148:151], v[156:159], v[24:27]
	s_waitcnt lgkmcnt(0)
	v_mfma_f32_16x16x32_bf16 v[56:59], v[160:163], v[156:159], v[56:59]
	v_mfma_f32_16x16x32_bf16 v[68:71], v[160:163], v[152:155], v[68:71]
	v_mfma_f32_16x16x32_bf16 v[20:23], v[160:163], v[164:167], v[20:23]
	v_mfma_f32_16x16x32_bf16 v[144:147], v[160:163], v[168:171], v[144:147]
	v_mfma_f32_16x16x32_bf16 v[28:31], v[148:151], v[152:155], v[28:31]
	v_mfma_f32_16x16x32_bf16 v[84:87], v[148:151], v[164:167], v[84:87]
	v_mfma_f32_16x16x32_bf16 v[76:79], v[148:151], v[168:171], v[76:79]
	ds_read_b128 v[148:151], v0
	ds_read_b128 v[168:171], v207 offset:32768
	ds_read_b128 v[180:183], v207 offset:34816
	ds_read_b128 v[152:155], v0 offset:2048
	ds_read_b128 v[192:195], v207 offset:40960
	ds_read_b128 v[196:199], v207 offset:43008
	s_waitcnt lgkmcnt(4)
	v_mfma_f32_16x16x32_bf16 v[140:143], v[148:151], v[168:171], v[140:143]
	s_waitcnt lgkmcnt(3)
	v_mfma_f32_16x16x32_bf16 v[136:139], v[148:151], v[180:183], v[136:139]
	s_waitcnt lgkmcnt(1)
	v_mfma_f32_16x16x32_bf16 v[132:135], v[148:151], v[192:195], v[132:135]
	s_waitcnt lgkmcnt(0)
	v_mfma_f32_16x16x32_bf16 v[128:131], v[148:151], v[196:199], v[128:131]
	v_mfma_f32_16x16x32_bf16 v[124:127], v[152:155], v[168:171], v[124:127]
	v_mfma_f32_16x16x32_bf16 v[120:123], v[152:155], v[180:183], v[120:123]
	v_mfma_f32_16x16x32_bf16 v[116:119], v[152:155], v[192:195], v[116:119]
	v_mfma_f32_16x16x32_bf16 v[112:115], v[152:155], v[196:199], v[112:115]
	ds_read_b128 v[148:151], v0 offset:4096
	ds_read_b128 v[152:155], v0 offset:6144
	ds_read_b128 v[156:159], v0 offset:12288
	ds_read_b128 v[216:219], v0 offset:14336
	s_waitcnt lgkmcnt(3)
; template <int MI, bool SWAP, bool F8 = false>
; __device__ __forceinline__ void gemm_core(const bf16_t* __restrict__ A, int lda, const bf16_t* __restrict__ B, int ldb,
;                                           int K, char* smem, f32x4 (&acc)[MI][4]) {
;     ...
;   for (int kt = 0; kt < nk; ++kt) {
;     __syncthreads();
; #pragma unroll
;     for (int i = 0; i < MI; ++i) *(u32x4*)(smem + woff + i * 4096) = ra[i];
; #pragma unroll
;     for (int i = 0; i < 4; ++i) *(u32x4*)(smem + 32768 + woff + i * 4096) = rb[i];
;     __syncthreads();
;     if (kt + 1 < nk) {
; #pragma unroll
;       for (int i = 0; i < MI; ++i) ra[i] = *(const u32x4*)(ap + (size_t)(32 * i) * lda + (kt + 1) * 64);
; #pragma unroll
;       for (int i = 0; i < 4; ++i) rb[i] = *(const u32x4*)(bp + (size_t)(32 * i) * ldb + (kt + 1) * 64);
;     }
;     if (F8) {
;       const int c0 = (g ^ (li & 7)) << 4, c1 = ((4 + g) ^ (li & 7)) << 4;
;       i32x8 wf8[4];
; #pragma unroll
;       for (int j = 0; j < 4; ++j) {
;         const char* rp = smem + wrow + ((j & 1) * 16 + (j >> 1) * 64) * 128;
;         const u32x4 lo = *(const u32x4*)(rp + c0), hi = *(const u32x4*)(rp + c1);
;         wf8[j] = (i32x8){(int)lo.x, (int)lo.y, (int)lo.z, (int)lo.w, (int)hi.x, (int)hi.y, (int)hi.z, (int)hi.w};
;       }
; #pragma unroll
;       for (int i = 0; i < MI; ++i) {
;         const char* rp = smem + xrow + i * 2048;
;         const u32x4 lo = *(const u32x4*)(rp + c0), hi = *(const u32x4*)(rp + c1);
;         const i32x8 xf8 = {(int)lo.x, (int)lo.y, (int)lo.z, (int)lo.w, (int)hi.x, (int)hi.y, (int)hi.z, (int)hi.w};
; #pragma unroll
;         for (int j = 0; j < 4; ++j)
;           acc[i][j] = __builtin_amdgcn_mfma_scale_f32_16x16x128_f8f6f4(wf8[j], xf8, acc[i][j], 0, 0, 0, 0x77777777, 0, 0x7f7f7f7f);
;       }
;     } else {
; #pragma unroll
;     for (int kk = 0; kk < 2; ++kk) {
;       const int ch = ((kk * 4 + g) ^ (li & 7)) << 4;
;       bf16x8 xf[MI], wf[4];
; #pragma unroll
;       for (int j = 0; j < 4; ++j) wf[j] = *(const bf16x8*)(smem + wrow + ((j & 1) * 16 + (j >> 1) * 64) * 128 + ch);
; #pragma unroll
;       for (int i = 0; i < MI; ++i) xf[i] = *(const bf16x8*)(smem + xrow + i * 2048 + ch);
; #pragma unroll
;       for (int i = 0; i < MI; ++i)
; #pragma unroll
;         for (int j = 0; j < 4; ++j) {
	v_mfma_f32_16x16x32_bf16 v[108:111], v[148:151], v[168:171], v[108:111]
	v_mfma_f32_16x16x32_bf16 v[104:107], v[148:151], v[180:183], v[104:107]
	v_mfma_f32_16x16x32_bf16 v[100:103], v[148:151], v[192:195], v[100:103]
	v_mfma_f32_16x16x32_bf16 v[96:99], v[148:151], v[196:199], v[96:99]
	ds_read_b128 v[148:151], v0 offset:8192
	s_waitcnt lgkmcnt(3)
	v_mfma_f32_16x16x32_bf16 v[92:95], v[152:155], v[168:171], v[92:95]
	v_mfma_f32_16x16x32_bf16 v[88:91], v[152:155], v[180:183], v[88:91]
	v_mfma_f32_16x16x32_bf16 v[80:83], v[152:155], v[192:195], v[80:83]
	v_mfma_f32_16x16x32_bf16 v[72:75], v[152:155], v[196:199], v[72:75]
	ds_read_b128 v[152:155], v0 offset:10240
	s_waitcnt lgkmcnt(1)
	v_mfma_f32_16x16x32_bf16 v[64:67], v[148:151], v[168:171], v[64:67]
	v_mfma_f32_16x16x32_bf16 v[60:63], v[148:151], v[180:183], v[60:63]
	v_mfma_f32_16x16x32_bf16 v[52:55], v[148:151], v[192:195], v[52:55]
	v_mfma_f32_16x16x32_bf16 v[48:51], v[148:151], v[196:199], v[48:51]
	s_waitcnt lgkmcnt(0)
	v_mfma_f32_16x16x32_bf16 v[44:47], v[152:155], v[168:171], v[44:47]
	v_mfma_f32_16x16x32_bf16 v[40:43], v[152:155], v[180:183], v[40:43]
	v_mfma_f32_16x16x32_bf16 v[36:39], v[152:155], v[192:195], v[36:39]
	v_mfma_f32_16x16x32_bf16 v[32:35], v[152:155], v[196:199], v[32:35]
	v_mfma_f32_16x16x32_bf16 v[28:31], v[156:159], v[168:171], v[28:31]
	v_mfma_f32_16x16x32_bf16 v[24:27], v[156:159], v[180:183], v[24:27]
	v_mfma_f32_16x16x32_bf16 v[84:87], v[156:159], v[192:195], v[84:87]
	v_mfma_f32_16x16x32_bf16 v[76:79], v[156:159], v[196:199], v[76:79]
	v_mfma_f32_16x16x32_bf16 v[68:71], v[216:219], v[168:171], v[68:71]
	v_mfma_f32_16x16x32_bf16 v[56:59], v[216:219], v[180:183], v[56:59]
	v_mfma_f32_16x16x32_bf16 v[20:23], v[216:219], v[192:195], v[20:23]
	v_mfma_f32_16x16x32_bf16 v[144:147], v[216:219], v[196:199], v[144:147]
	s_add_u32 s8, s8, 0x80
	s_addc_u32 s9, s9, 0
	s_cmpk_lg_i32 s8, 0x780
	s_cbranch_scc1 .LBB0_313
	s_barrier
	s_setprio 3
	s_mov_b32 m0, s62
	s_nop 0
	global_load_lds_dwordx4 v252, s[56:57]
	s_add_u32 m0, s62, 0x1000
	s_nop 0
	global_load_lds_dwordx4 v253, s[56:57]
	s_add_u32 s56, s56, 0x20000
	s_addc_u32 s57, s57, 0
	s_add_u32 m0, s62, 0x2000
	s_nop 0
	global_load_lds_dwordx4 v252, s[56:57]
	s_add_u32 m0, s62, 0x3000
	s_nop 0
	global_load_lds_dwordx4 v253, s[56:57]
	s_add_u32 s56, s56, 0x20000
	s_addc_u32 s57, s57, 0
	s_add_u32 m0, s62, 0x4000
	s_nop 0
	global_load_lds_dwordx4 v252, s[56:57]
	s_add_u32 m0, s62, 0x5000
	s_nop 0
	global_load_lds_dwordx4 v253, s[56:57]
	s_add_u32 s56, s56, 0x20000
	s_addc_u32 s57, s57, 0
	s_add_u32 m0, s62, 0x6000
	s_nop 0
	global_load_lds_dwordx4 v252, s[56:57]
	s_add_u32 m0, s62, 0x7000
	s_nop 0
	global_load_lds_dwordx4 v253, s[56:57]
	s_sub_u32 s56, s56, 0x60000
	s_subb_u32 s57, s57, 0
	s_add_u32 m0, s62, 0x8000
	s_nop 0
	global_load_lds_dwordx4 v252, s[58:59]
	s_add_u32 m0, s62, 0x9000
	s_nop 0
	global_load_lds_dwordx4 v253, s[58:59]
	s_add_u32 s58, s58, 0x20000
	s_addc_u32 s59, s59, 0
	s_add_u32 m0, s62, 0xa000
	s_nop 0
	global_load_lds_dwordx4 v252, s[58:59]
	s_add_u32 m0, s62, 0xb000
	s_nop 0
	global_load_lds_dwordx4 v253, s[58:59]
	s_sub_u32 s58, s58, 0x20000
	s_subb_u32 s59, s59, 0
	s_waitcnt vmcnt(0)
	s_setprio 0
	s_barrier
	v_bfe_u32 v12, v208, 4, 1
	v_mul_u32_u24_e32 v12, 24, v12
	v_mov_b32_e32 v13, 0
	ds_read_b128 v[148:151], v215 offset:32768
	ds_read_b128 v[152:155], v215 offset:34816
	ds_read_b128 v[156:159], v215 offset:40960
	ds_read_b128 v[160:163], v215 offset:43008
	ds_read_b128 v[164:167], v213
	ds_read_b128 v[168:171], v213 offset:2048
	ds_read_b128 v[172:175], v213 offset:4096
	ds_read_b128 v[176:179], v213 offset:6144
	ds_read_b128 v[180:183], v213 offset:8192
	ds_read_b128 v[184:187], v213 offset:10240
	ds_read_b128 v[188:191], v213 offset:12288
	ds_read_b128 v[192:195], v213 offset:14336
	s_cmp_eq_u32 s42, 2
	s_mov_b32 s7, 0x6000000
	s_cselect_b32 s7, 0x2000000, s7
	s_waitcnt lgkmcnt(7)
	v_mfma_f32_16x16x32_bf16 v[140:143], v[164:167], v[148:151], v[140:143]
	s_add_u32 s8, s40, s7
	s_addc_u32 s9, s39, 0
	s_ashr_i32 s7, s6, 31
	v_mfma_f32_16x16x32_bf16 v[136:139], v[164:167], v[152:155], v[136:139]
	s_lshl_b64 s[6:7], s[6:7], 20
	s_add_u32 s6, s8, s6
	s_addc_u32 s7, s9, s7
	v_mfma_f32_16x16x32_bf16 v[132:135], v[164:167], v[156:159], v[132:135]
	s_lshl_b32 s8, s41, 1
	s_add_u32 s6, s6, s8
	s_addc_u32 s7, s7, 0
	v_mfma_f32_16x16x32_bf16 v[128:131], v[164:167], v[160:163], v[128:131]
	s_waitcnt lgkmcnt(6)
	v_mfma_f32_16x16x32_bf16 v[124:127], v[168:171], v[148:151], v[124:127]
	v_mfma_f32_16x16x32_bf16 v[120:123], v[168:171], v[152:155], v[120:123]
	v_mfma_f32_16x16x32_bf16 v[116:119], v[168:171], v[156:159], v[116:119]
	v_mfma_f32_16x16x32_bf16 v[112:115], v[168:171], v[160:163], v[112:115]
	s_waitcnt lgkmcnt(5)
	v_mfma_f32_16x16x32_bf16 v[108:111], v[172:175], v[148:151], v[108:111]
	v_mfma_f32_16x16x32_bf16 v[104:107], v[172:175], v[152:155], v[104:107]
	v_mfma_f32_16x16x32_bf16 v[100:103], v[172:175], v[156:159], v[100:103]
	v_mfma_f32_16x16x32_bf16 v[96:99], v[172:175], v[160:163], v[96:99]
	s_waitcnt lgkmcnt(4)
	v_mfma_f32_16x16x32_bf16 v[92:95], v[176:179], v[148:151], v[92:95]
	v_mfma_f32_16x16x32_bf16 v[88:91], v[176:179], v[152:155], v[88:91]
	v_mfma_f32_16x16x32_bf16 v[80:83], v[176:179], v[156:159], v[80:83]
	v_mfma_f32_16x16x32_bf16 v[72:75], v[176:179], v[160:163], v[72:75]
	s_waitcnt lgkmcnt(3)
	v_mfma_f32_16x16x32_bf16 v[64:67], v[180:183], v[148:151], v[64:67]
	v_mfma_f32_16x16x32_bf16 v[60:63], v[180:183], v[152:155], v[60:63]
	v_mfma_f32_16x16x32_bf16 v[52:55], v[180:183], v[156:159], v[52:55]
	v_mfma_f32_16x16x32_bf16 v[48:51], v[180:183], v[160:163], v[48:51]
	s_waitcnt lgkmcnt(2)
; template <int MI, bool SWAP, bool F8 = false>
; __device__ __forceinline__ void gemm_core(const bf16_t* __restrict__ A, int lda, const bf16_t* __restrict__ B, int ldb,
;                                           int K, char* smem, f32x4 (&acc)[MI][4]) {
;     ...
; #pragma unroll
;     for (int kk = 0; kk < 2; ++kk) {
;       const int ch = ((kk * 4 + g) ^ (li & 7)) << 4;
;       bf16x8 xf[MI], wf[4];
; #pragma unroll
;       for (int j = 0; j < 4; ++j) wf[j] = *(const bf16x8*)(smem + wrow + ((j & 1) * 16 + (j >> 1) * 64) * 128 + ch);
; #pragma unroll
;       for (int i = 0; i < MI; ++i) xf[i] = *(const bf16x8*)(smem + xrow + i * 2048 + ch);
; #pragma unroll
;       for (int i = 0; i < MI; ++i)
; #pragma unroll
;         for (int j = 0; j < 4; ++j) {
;           if (SWAP) acc[i][j] = __builtin_amdgcn_mfma_f32_16x16x32_bf16(xf[i], wf[j], acc[i][j], 0, 0, 0);
;           else acc[i][j] = __builtin_amdgcn_mfma_f32_16x16x32_bf16(wf[j], xf[i], acc[i][j], 0, 0, 0);
;         }
;     }
; __device__ void even_in_tile(const P& p, int li_even, int tm, int tn, char* smem) {
;     ...
; #pragma unroll
;     for (int i = 0; i < MI; ++i)
; #pragma unroll
;       for (int j = 0; j < 4; ++j) {
;         u32x2 v;
;         v.x = pk_bf16(acc[i][j][0], acc[i][j][1]);
;         v.y = pk_bf16(acc[i][j][2], acc[i][j][3]);
;         *(u32x2*)(dst + (size_t)NCOLS(j) * 4096 + s0 + MROWS(i)) = v;
;       }
	v_mfma_f32_16x16x32_bf16 v[44:47], v[184:187], v[148:151], v[44:47]
	v_mfma_f32_16x16x32_bf16 v[40:43], v[184:187], v[152:155], v[40:43]
	v_mfma_f32_16x16x32_bf16 v[36:39], v[184:187], v[156:159], v[36:39]
	v_mfma_f32_16x16x32_bf16 v[32:35], v[184:187], v[160:163], v[32:35]
	s_waitcnt lgkmcnt(1)
	v_mfma_f32_16x16x32_bf16 v[28:31], v[188:191], v[148:151], v[28:31]
	v_mfma_f32_16x16x32_bf16 v[24:27], v[188:191], v[152:155], v[24:27]
	v_mfma_f32_16x16x32_bf16 v[164:167], v[188:191], v[156:159], v[84:87]
	v_mfma_f32_16x16x32_bf16 v[168:171], v[188:191], v[160:163], v[76:79]
	s_waitcnt lgkmcnt(0)
	v_mfma_f32_16x16x32_bf16 v[148:151], v[192:195], v[148:151], v[68:71]
	v_mfma_f32_16x16x32_bf16 v[152:155], v[192:195], v[152:155], v[56:59]
	v_mfma_f32_16x16x32_bf16 v[20:23], v[192:195], v[156:159], v[20:23]
	v_mfma_f32_16x16x32_bf16 v[144:147], v[192:195], v[160:163], v[144:147]
	ds_read_b128 v[156:159], v207 offset:32768
	ds_read_b128 v[160:163], v207 offset:34816
	ds_read_b128 v[172:175], v207 offset:40960
	ds_read_b128 v[176:179], v207 offset:43008
	ds_read_b128 v[56:59], v0
	ds_read_b128 v[68:71], v0 offset:2048
	ds_read_b128 v[76:79], v0 offset:4096
	ds_read_b128 v[84:87], v0 offset:6144
	ds_read_b128 v[180:183], v0 offset:8192
	ds_read_b128 v[184:187], v0 offset:10240
	ds_read_b128 v[188:191], v0 offset:12288
	ds_read_b128 v[192:195], v0 offset:14336
	v_mov_b32_e32 v0, v208
	s_waitcnt lgkmcnt(7)
	v_mfma_f32_16x16x32_bf16 v[140:143], v[56:59], v[156:159], v[140:143]
	v_and_b32_e32 v2, 15, v0
	v_lshrrev_b32_e32 v3, 1, v0
	v_mfma_f32_16x16x32_bf16 v[196:199], v[56:59], v[160:163], v[136:139]
	s_nop 2
	v_and_or_b32 v136, v3, 32, v2
	v_and_b32_e32 v2, 0xffffff80, v0
	v_lshrrev_b32_e32 v0, 2, v0
	v_and_or_b32 v2, v0, 12, v2
	v_ashrrev_i32_e32 v3, 31, v2
	v_lshl_add_u64 v[2:3], v[2:3], 1, s[6:7]
	v_lshlrev_b32_e32 v0, 13, v136
	v_mfma_f32_16x16x32_bf16 v[200:203], v[56:59], v[172:175], v[132:135]
	v_cvt_pk_bf16_f32 v138, v140, v141
	v_cvt_pk_bf16_f32 v139, v142, v143
	v_lshl_add_u64 v[136:137], v[2:3], 0, v[0:1]
	v_mfma_f32_16x16x32_bf16 v[132:135], v[56:59], v[176:179], v[128:131]
	global_store_dwordx2 v[136:137], v[138:139], off
	v_or_b32_e32 v138, 0x20000, v0
	v_mov_b32_e32 v139, v1
	s_waitcnt lgkmcnt(6)
	v_mfma_f32_16x16x32_bf16 v[128:131], v[68:71], v[156:159], v[124:127]
	v_cvt_pk_bf16_f32 v140, v196, v197
	v_cvt_pk_bf16_f32 v141, v198, v199
	v_lshl_add_u64 v[142:143], v[2:3], 0, v[138:139]
	v_mfma_f32_16x16x32_bf16 v[124:127], v[68:71], v[160:163], v[120:123]
	global_store_dwordx2 v[142:143], v[140:141], off
	v_or_b32_e32 v140, 0x80000, v0
	v_or_b32_e32 v0, 0xa0000, v0
	v_mfma_f32_16x16x32_bf16 v[120:123], v[68:71], v[172:175], v[116:119]
	v_cvt_pk_bf16_f32 v132, v132, v133
	v_cvt_pk_bf16_f32 v133, v134, v135
	v_lshl_add_u64 v[134:135], v[2:3], 0, v[0:1]
	v_mfma_f32_16x16x32_bf16 v[116:119], v[68:71], v[176:179], v[112:115]
	global_store_dwordx2 v[134:135], v[132:133], off
	v_lshl_add_u64 v[132:133], v[2:3], 0, 32
	s_mov_b64 s[6:7], 0x60
	s_waitcnt lgkmcnt(5)
	v_mfma_f32_16x16x32_bf16 v[112:115], v[76:79], v[156:159], v[108:111]
	v_mov_b32_e32 v141, v1
	s_nop 1
	v_cvt_pk_bf16_f32 v116, v116, v117
	v_cvt_pk_bf16_f32 v117, v118, v119
	v_mfma_f32_16x16x32_bf16 v[108:111], v[76:79], v[160:163], v[104:107]
	v_lshl_add_u64 v[118:119], v[132:133], 0, v[0:1]
	global_store_dwordx2 v[118:119], v[116:117], off
	v_lshl_add_u64 v[116:117], v[2:3], 0, 64
	v_mfma_f32_16x16x32_bf16 v[104:107], v[76:79], v[172:175], v[100:103]
	v_cvt_pk_bf16_f32 v142, v200, v201
	v_cvt_pk_bf16_f32 v143, v202, v203
	v_cvt_pk_bf16_f32 v128, v128, v129
	v_mfma_f32_16x16x32_bf16 v[100:103], v[76:79], v[176:179], v[96:99]
	v_cvt_pk_bf16_f32 v129, v130, v131
	v_cvt_pk_bf16_f32 v124, v124, v125
	v_cvt_pk_bf16_f32 v125, v126, v127
	s_waitcnt lgkmcnt(4)
	v_mfma_f32_16x16x32_bf16 v[96:99], v[84:87], v[156:159], v[92:95]
	v_lshl_add_u64 v[126:127], v[132:133], 0, v[138:139]
	s_nop 1
	v_cvt_pk_bf16_f32 v100, v100, v101
	v_cvt_pk_bf16_f32 v101, v102, v103
	v_mfma_f32_16x16x32_bf16 v[92:95], v[84:87], v[160:163], v[88:91]
	v_lshl_add_u64 v[102:103], v[116:117], 0, v[0:1]
	global_store_dwordx2 v[102:103], v[100:101], off
	v_lshl_add_u64 v[100:101], v[2:3], 0, s[6:7]
	v_mfma_f32_16x16x32_bf16 v[88:91], v[84:87], v[172:175], v[80:83]
	s_mov_b64 s[6:7], 0x80
	v_cvt_pk_bf16_f32 v120, v120, v121
	v_cvt_pk_bf16_f32 v121, v122, v123
	v_mfma_f32_16x16x32_bf16 v[84:87], v[84:87], v[176:179], v[72:75]
	v_lshl_add_u64 v[122:123], v[132:133], 0, v[140:141]
	v_cvt_pk_bf16_f32 v112, v112, v113
	v_cvt_pk_bf16_f32 v113, v114, v115
	s_waitcnt lgkmcnt(3)
	v_mfma_f32_16x16x32_bf16 v[68:71], v[180:183], v[176:179], v[48:51]
	v_cvt_pk_bf16_f32 v108, v108, v109
	s_nop 1
	v_cvt_pk_bf16_f32 v84, v84, v85
	v_cvt_pk_bf16_f32 v85, v86, v87
	v_mfma_f32_16x16x32_bf16 v[72:75], v[180:183], v[172:175], v[52:55]
	v_lshl_add_u64 v[86:87], v[100:101], 0, v[0:1]
	global_store_dwordx2 v[86:87], v[84:85], off
	v_lshl_add_u64 v[84:85], v[2:3], 0, s[6:7]
	s_waitcnt lgkmcnt(2)
; __device__ void even_in_tile(const P& p, int li_even, int tm, int tn, char* smem) {
;     ...
; #pragma unroll
;     for (int i = 0; i < MI; ++i)
; #pragma unroll
;       for (int j = 0; j < 4; ++j) {
;         u32x2 v;
;         v.x = pk_bf16(acc[i][j][0], acc[i][j][1]);
;         v.y = pk_bf16(acc[i][j][2], acc[i][j][3]);
;         *(u32x2*)(dst + (size_t)NCOLS(j) * 4096 + s0 + MROWS(i)) = v;
;       }
;     return;
	v_mfma_f32_16x16x32_bf16 v[52:55], v[184:187], v[176:179], v[32:35]
	v_cvt_pk_bf16_f32 v68, v68, v69
	v_cvt_pk_bf16_f32 v69, v70, v71
	v_lshl_add_u64 v[70:71], v[84:85], 0, v[0:1]
	s_mov_b64 s[6:7], 0xa0
	v_mfma_f32_16x16x32_bf16 v[80:83], v[180:183], v[156:159], v[64:67]
	global_store_dwordx2 v[70:71], v[68:69], off
	v_lshl_add_u64 v[68:69], v[2:3], 0, s[6:7]
	s_nop 0
	v_cvt_pk_bf16_f32 v52, v52, v53
	v_mfma_f32_16x16x32_bf16 v[76:79], v[180:183], v[160:163], v[60:63]
	v_cvt_pk_bf16_f32 v53, v54, v55
	v_lshl_add_u64 v[54:55], v[68:69], 0, v[0:1]
	s_mov_b64 s[6:7], 0xc0
	v_mfma_f32_16x16x32_bf16 v[64:67], v[184:187], v[156:159], v[44:47]
	global_store_dwordx2 v[54:55], v[52:53], off
	v_lshl_add_u64 v[52:53], v[2:3], 0, s[6:7]
	s_mov_b64 s[6:7], 0xe0
	v_mfma_f32_16x16x32_bf16 v[60:63], v[184:187], v[160:163], v[40:43]
	v_cvt_pk_bf16_f32 v109, v110, v111
	v_lshl_add_u64 v[110:111], v[116:117], 0, v[138:139]
	v_cvt_pk_bf16_f32 v104, v104, v105
	v_mfma_f32_16x16x32_bf16 v[56:59], v[184:187], v[172:175], v[36:39]
	v_cvt_pk_bf16_f32 v105, v106, v107
	v_lshl_add_u64 v[106:107], v[116:117], 0, v[140:141]
	v_cvt_pk_bf16_f32 v96, v96, v97
	s_waitcnt lgkmcnt(1)
	v_mfma_f32_16x16x32_bf16 v[48:51], v[188:191], v[156:159], v[28:31]
	v_cvt_pk_bf16_f32 v97, v98, v99
	v_cvt_pk_bf16_f32 v92, v92, v93
	v_cvt_pk_bf16_f32 v93, v94, v95
	v_mfma_f32_16x16x32_bf16 v[44:47], v[188:191], v[160:163], v[24:27]
	v_lshl_add_u64 v[94:95], v[100:101], 0, v[138:139]
	v_cvt_pk_bf16_f32 v88, v88, v89
	v_cvt_pk_bf16_f32 v89, v90, v91
	v_mfma_f32_16x16x32_bf16 v[40:43], v[188:191], v[172:175], v[164:167]
	v_lshl_add_u64 v[90:91], v[100:101], 0, v[140:141]
	v_cvt_pk_bf16_f32 v80, v80, v81
	v_cvt_pk_bf16_f32 v81, v82, v83
	v_mfma_f32_16x16x32_bf16 v[36:39], v[188:191], v[176:179], v[168:171]
	v_cvt_pk_bf16_f32 v76, v76, v77
	v_cvt_pk_bf16_f32 v77, v78, v79
	v_lshl_add_u64 v[78:79], v[84:85], 0, v[138:139]
	s_waitcnt lgkmcnt(0)
	v_mfma_f32_16x16x32_bf16 v[32:35], v[192:195], v[156:159], v[148:151]
	v_cvt_pk_bf16_f32 v72, v72, v73
	v_cvt_pk_bf16_f32 v73, v74, v75
	v_lshl_add_u64 v[74:75], v[84:85], 0, v[140:141]
	v_mfma_f32_16x16x32_bf16 v[28:31], v[192:195], v[160:163], v[152:155]
	v_cvt_pk_bf16_f32 v64, v64, v65
	v_cvt_pk_bf16_f32 v65, v66, v67
	v_cvt_pk_bf16_f32 v60, v60, v61
	v_mfma_f32_16x16x32_bf16 v[24:27], v[192:195], v[172:175], v[20:23]
	v_cvt_pk_bf16_f32 v61, v62, v63
	v_lshl_add_u64 v[62:63], v[68:69], 0, v[138:139]
	v_cvt_pk_bf16_f32 v56, v56, v57
	v_mfma_f32_16x16x32_bf16 v[20:23], v[192:195], v[176:179], v[144:147]
	v_cvt_pk_bf16_f32 v57, v58, v59
	v_lshl_add_u64 v[58:59], v[68:69], 0, v[140:141]
	v_cvt_pk_bf16_f32 v48, v48, v49
	v_lshl_add_u64 v[144:145], v[2:3], 0, v[140:141]
	v_lshl_add_u64 v[2:3], v[2:3], 0, s[6:7]
	v_cvt_pk_bf16_f32 v49, v50, v51
	v_cvt_pk_bf16_f32 v44, v44, v45
	v_cvt_pk_bf16_f32 v45, v46, v47
	v_lshl_add_u64 v[46:47], v[52:53], 0, v[138:139]
	v_cvt_pk_bf16_f32 v40, v40, v41
	v_cvt_pk_bf16_f32 v41, v42, v43
	v_lshl_add_u64 v[42:43], v[52:53], 0, v[140:141]
	v_cvt_pk_bf16_f32 v36, v36, v37
	v_cvt_pk_bf16_f32 v37, v38, v39
	v_lshl_add_u64 v[38:39], v[52:53], 0, v[0:1]
	v_cvt_pk_bf16_f32 v32, v32, v33
	v_cvt_pk_bf16_f32 v33, v34, v35
	v_cvt_pk_bf16_f32 v28, v28, v29
	v_cvt_pk_bf16_f32 v29, v30, v31
	v_lshl_add_u64 v[30:31], v[2:3], 0, v[138:139]
	v_cvt_pk_bf16_f32 v24, v24, v25
	v_cvt_pk_bf16_f32 v25, v26, v27
	v_lshl_add_u64 v[26:27], v[2:3], 0, v[140:141]
	v_cvt_pk_bf16_f32 v20, v20, v21
	v_cvt_pk_bf16_f32 v21, v22, v23
	v_lshl_add_u64 v[2:3], v[2:3], 0, v[0:1]
	global_store_dwordx2 v[144:145], v[142:143], off
	global_store_dwordx2 v[136:137], v[128:129], off offset:32
	global_store_dwordx2 v[126:127], v[124:125], off
	global_store_dwordx2 v[122:123], v[120:121], off
	global_store_dwordx2 v[136:137], v[112:113], off offset:64
	global_store_dwordx2 v[110:111], v[108:109], off
	global_store_dwordx2 v[106:107], v[104:105], off
	global_store_dwordx2 v[136:137], v[96:97], off offset:96
	global_store_dwordx2 v[94:95], v[92:93], off
	global_store_dwordx2 v[90:91], v[88:89], off
	global_store_dwordx2 v[136:137], v[80:81], off offset:128
	global_store_dwordx2 v[78:79], v[76:77], off
	global_store_dwordx2 v[74:75], v[72:73], off
	global_store_dwordx2 v[136:137], v[64:65], off offset:160
	global_store_dwordx2 v[62:63], v[60:61], off
	global_store_dwordx2 v[58:59], v[56:57], off
	global_store_dwordx2 v[136:137], v[48:49], off offset:192
	global_store_dwordx2 v[46:47], v[44:45], off
	global_store_dwordx2 v[42:43], v[40:41], off
	global_store_dwordx2 v[38:39], v[36:37], off
	global_store_dwordx2 v[136:137], v[32:33], off offset:224
	global_store_dwordx2 v[30:31], v[28:29], off
	global_store_dwordx2 v[26:27], v[24:25], off
	global_store_dwordx2 v[2:3], v[20:21], off
	s_branch .LBB0_294

; template <int MI, bool SWAP, bool F8 = false>
; __device__ __forceinline__ void gemm_core(const bf16_t* __restrict__ A, int lda, const bf16_t* __restrict__ B, int ldb,
;                                           int K, char* smem, f32x4 (&acc)[MI][4]) {
;     ...
;   for (int kt = 0; kt < nk; ++kt) {
;     __syncthreads();
; #pragma unroll
;     for (int i = 0; i < MI; ++i) *(u32x4*)(smem + woff + i * 4096) = ra[i];
; #pragma unroll
;     for (int i = 0; i < 4; ++i) *(u32x4*)(smem + 32768 + woff + i * 4096) = rb[i];
;     __syncthreads();
;     if (kt + 1 < nk) {
; #pragma unroll
;       for (int i = 0; i < MI; ++i) ra[i] = *(const u32x4*)(ap + (size_t)(32 * i) * lda + (kt + 1) * 64);
; #pragma unroll
;       for (int i = 0; i < 4; ++i) rb[i] = *(const u32x4*)(bp + (size_t)(32 * i) * ldb + (kt + 1) * 64);
;     }
;     if (F8) {
;       const int c0 = (g ^ (li & 7)) << 4, c1 = ((4 + g) ^ (li & 7)) << 4;
;       i32x8 wf8[4];
; #pragma unroll
;       for (int j = 0; j < 4; ++j) {
;         const char* rp = smem + wrow + ((j & 1) * 16 + (j >> 1) * 64) * 128;
;         const u32x4 lo = *(const u32x4*)(rp + c0), hi = *(const u32x4*)(rp + c1);
;         wf8[j] = (i32x8){(int)lo.x, (int)lo.y, (int)lo.z, (int)lo.w, (int)hi.x, (int)hi.y, (int)hi.z, (int)hi.w};
;       }
; #pragma unroll
;       for (int i = 0; i < MI; ++i) {
;         const char* rp = smem + xrow + i * 2048;
;         const u32x4 lo = *(const u32x4*)(rp + c0), hi = *(const u32x4*)(rp + c1);
;         const i32x8 xf8 = {(int)lo.x, (int)lo.y, (int)lo.z, (int)lo.w, (int)hi.x, (int)hi.y, (int)hi.z, (int)hi.w};
; #pragma unroll
;         for (int j = 0; j < 4; ++j)
;           acc[i][j] = __builtin_amdgcn_mfma_scale_f32_16x16x128_f8f6f4(wf8[j], xf8, acc[i][j], 0, 0, 0, 0x77777777, 0, 0x7f7f7f7f);
;       }
;     } else {
; #pragma unroll
;     for (int kk = 0; kk < 2; ++kk) {
;       const int ch = ((kk * 4 + g) ^ (li & 7)) << 4;
;       bf16x8 xf[MI], wf[4];
; #pragma unroll
;       for (int j = 0; j < 4; ++j) wf[j] = *(const bf16x8*)(smem + wrow + ((j & 1) * 16 + (j >> 1) * 64) * 128 + ch);
; #pragma unroll
;       for (int i = 0; i < MI; ++i) xf[i] = *(const bf16x8*)(smem + xrow + i * 2048 + ch);
; #pragma unroll
;       for (int i = 0; i < MI; ++i)
; #pragma unroll
;         for (int j = 0; j < 4; ++j) {
.Lcch819_ret:
	s_add_u32 s63, s63, 1
	s_barrier
	v_add_u32_e32 v213, v202, v204
	ds_read_b128 v[148:151], v215 offset:32768
	ds_read_b128 v[152:155], v215 offset:34816
	ds_read_b128 v[156:159], v213
	ds_read_b128 v[160:163], v213 offset:2048
	ds_read_b128 v[164:167], v215 offset:40960
	ds_read_b128 v[168:171], v215 offset:43008
	s_waitcnt lgkmcnt(3)
	v_mfma_f32_16x16x32_bf16 v[140:143], v[148:151], v[156:159], v[140:143]
	v_add_u32_e32 v207, v203, v205
	v_add_u32_e32 v206, v202, v205
	v_mfma_f32_16x16x32_bf16 v[136:139], v[152:155], v[156:159], v[136:139]
	s_waitcnt lgkmcnt(1)
	v_mfma_f32_16x16x32_bf16 v[132:135], v[164:167], v[156:159], v[132:135]
	s_waitcnt lgkmcnt(0)
	v_mfma_f32_16x16x32_bf16 v[124:127], v[168:171], v[156:159], v[124:127]
	v_mfma_f32_16x16x32_bf16 v[108:111], v[148:151], v[160:163], v[108:111]
	v_mfma_f32_16x16x32_bf16 v[104:107], v[152:155], v[160:163], v[104:107]
	v_mfma_f32_16x16x32_bf16 v[96:99], v[164:167], v[160:163], v[96:99]
	v_mfma_f32_16x16x32_bf16 v[92:95], v[168:171], v[160:163], v[92:95]
	ds_read_b128 v[156:159], v213 offset:4096
	ds_read_b128 v[160:163], v213 offset:6144
	s_waitcnt lgkmcnt(1)
	v_mfma_f32_16x16x32_bf16 v[88:91], v[148:151], v[156:159], v[88:91]
	v_mfma_f32_16x16x32_bf16 v[84:87], v[152:155], v[156:159], v[84:87]
	v_mfma_f32_16x16x32_bf16 v[80:83], v[164:167], v[156:159], v[80:83]
	v_mfma_f32_16x16x32_bf16 v[60:63], v[168:171], v[156:159], v[60:63]
	s_waitcnt lgkmcnt(0)
	v_mfma_f32_16x16x32_bf16 v[56:59], v[148:151], v[160:163], v[56:59]
	v_mfma_f32_16x16x32_bf16 v[52:55], v[152:155], v[160:163], v[52:55]
	v_mfma_f32_16x16x32_bf16 v[48:51], v[164:167], v[160:163], v[48:51]
	v_mfma_f32_16x16x32_bf16 v[44:47], v[168:171], v[160:163], v[44:47]
	ds_read_b128 v[156:159], v213 offset:8192
	ds_read_b128 v[160:163], v213 offset:10240
	s_waitcnt lgkmcnt(1)
	v_mfma_f32_16x16x32_bf16 v[40:43], v[148:151], v[156:159], v[40:43]
	v_mfma_f32_16x16x32_bf16 v[36:39], v[152:155], v[156:159], v[36:39]
	v_mfma_f32_16x16x32_bf16 v[32:35], v[164:167], v[156:159], v[32:35]
	v_mfma_f32_16x16x32_bf16 v[28:31], v[168:171], v[156:159], v[28:31]
	s_waitcnt lgkmcnt(0)
	v_mfma_f32_16x16x32_bf16 v[24:27], v[148:151], v[160:163], v[24:27]
	v_mfma_f32_16x16x32_bf16 v[20:23], v[152:155], v[160:163], v[20:23]
	v_mfma_f32_16x16x32_bf16 v[68:71], v[164:167], v[160:163], v[68:71]
	v_mfma_f32_16x16x32_bf16 v[64:67], v[168:171], v[160:163], v[64:67]
	ds_read_b128 v[156:159], v213 offset:12288
	ds_read_b128 v[160:163], v213 offset:14336
	ds_read_b128 v[172:175], v207 offset:32768
	ds_read_b128 v[180:183], v207 offset:34816
	s_waitcnt lgkmcnt(3)
	v_mfma_f32_16x16x32_bf16 v[72:75], v[148:151], v[156:159], v[72:75]
	v_mfma_f32_16x16x32_bf16 v[76:79], v[152:155], v[156:159], v[76:79]
	v_mfma_f32_16x16x32_bf16 v[128:131], v[164:167], v[156:159], v[128:131]
	v_mfma_f32_16x16x32_bf16 v[120:123], v[168:171], v[156:159], v[120:123]
	s_waitcnt lgkmcnt(2)
	v_mfma_f32_16x16x32_bf16 v[116:119], v[148:151], v[160:163], v[116:119]
	v_mfma_f32_16x16x32_bf16 v[112:115], v[152:155], v[160:163], v[112:115]
	ds_read_b128 v[148:151], v206
	ds_read_b128 v[152:155], v206 offset:2048
	ds_read_b128 v[192:195], v207 offset:40960
	ds_read_b128 v[196:199], v207 offset:43008
	v_mfma_f32_16x16x32_bf16 v[100:103], v[164:167], v[160:163], v[100:103]
	v_mfma_f32_16x16x32_bf16 v[144:147], v[168:171], v[160:163], v[144:147]
	s_waitcnt lgkmcnt(3)
	v_mfma_f32_16x16x32_bf16 v[140:143], v[172:175], v[148:151], v[140:143]
	v_mfma_f32_16x16x32_bf16 v[136:139], v[180:183], v[148:151], v[136:139]
	s_waitcnt lgkmcnt(1)
	v_mfma_f32_16x16x32_bf16 v[132:135], v[192:195], v[148:151], v[132:135]
	s_waitcnt lgkmcnt(0)
	v_mfma_f32_16x16x32_bf16 v[124:127], v[196:199], v[148:151], v[124:127]
	v_mfma_f32_16x16x32_bf16 v[108:111], v[172:175], v[152:155], v[108:111]
	v_mfma_f32_16x16x32_bf16 v[104:107], v[180:183], v[152:155], v[104:107]
	v_mfma_f32_16x16x32_bf16 v[96:99], v[192:195], v[152:155], v[96:99]
	v_mfma_f32_16x16x32_bf16 v[92:95], v[196:199], v[152:155], v[92:95]
	ds_read_b128 v[148:151], v206 offset:4096
	ds_read_b128 v[152:155], v206 offset:6144
	s_waitcnt lgkmcnt(1)
	v_mfma_f32_16x16x32_bf16 v[88:91], v[172:175], v[148:151], v[88:91]
	ds_read_b128 v[156:159], v206 offset:12288
	ds_read_b128 v[216:219], v206 offset:14336
	v_mfma_f32_16x16x32_bf16 v[84:87], v[180:183], v[148:151], v[84:87]
	v_mfma_f32_16x16x32_bf16 v[80:83], v[192:195], v[148:151], v[80:83]
	v_mfma_f32_16x16x32_bf16 v[60:63], v[196:199], v[148:151], v[60:63]
	ds_read_b128 v[148:151], v206 offset:8192
	s_waitcnt lgkmcnt(3)
	v_mfma_f32_16x16x32_bf16 v[56:59], v[172:175], v[152:155], v[56:59]
	v_mfma_f32_16x16x32_bf16 v[52:55], v[180:183], v[152:155], v[52:55]
	v_mfma_f32_16x16x32_bf16 v[48:51], v[192:195], v[152:155], v[48:51]
	v_mfma_f32_16x16x32_bf16 v[44:47], v[196:199], v[152:155], v[44:47]
	ds_read_b128 v[152:155], v206 offset:10240
	s_waitcnt lgkmcnt(1)
	v_mfma_f32_16x16x32_bf16 v[40:43], v[172:175], v[148:151], v[40:43]
	v_mfma_f32_16x16x32_bf16 v[36:39], v[180:183], v[148:151], v[36:39]
	v_mfma_f32_16x16x32_bf16 v[32:35], v[192:195], v[148:151], v[32:35]
	v_mfma_f32_16x16x32_bf16 v[28:31], v[196:199], v[148:151], v[28:31]
	s_waitcnt lgkmcnt(0)
	v_mfma_f32_16x16x32_bf16 v[24:27], v[172:175], v[152:155], v[24:27]
	v_mfma_f32_16x16x32_bf16 v[20:23], v[180:183], v[152:155], v[20:23]
	v_mfma_f32_16x16x32_bf16 v[68:71], v[192:195], v[152:155], v[68:71]
	v_mfma_f32_16x16x32_bf16 v[64:67], v[196:199], v[152:155], v[64:67]
	v_mfma_f32_16x16x32_bf16 v[72:75], v[172:175], v[156:159], v[72:75]
	v_mfma_f32_16x16x32_bf16 v[76:79], v[180:183], v[156:159], v[76:79]
	v_mfma_f32_16x16x32_bf16 v[128:131], v[192:195], v[156:159], v[128:131]
	v_mfma_f32_16x16x32_bf16 v[120:123], v[196:199], v[156:159], v[120:123]
	v_mfma_f32_16x16x32_bf16 v[116:119], v[172:175], v[216:219], v[116:119]
	v_mfma_f32_16x16x32_bf16 v[112:115], v[180:183], v[216:219], v[112:115]
	v_mfma_f32_16x16x32_bf16 v[100:103], v[192:195], v[216:219], v[100:103]
	v_mfma_f32_16x16x32_bf16 v[144:147], v[196:199], v[216:219], v[144:147]
	s_add_u32 s6, s6, 0x80
	s_addc_u32 s7, s7, 0
	s_cmpk_lg_i32 s6, 0x780
	s_cbranch_scc1 .LBB0_819
; template <int MI, bool SWAP, bool F8 = false>
; __device__ __forceinline__ void gemm_core(const bf16_t* __restrict__ A, int lda, const bf16_t* __restrict__ B, int ldb,
;                                           int K, char* smem, f32x4 (&acc)[MI][4]) {
;     ...
;   for (int kt = 0; kt < nk; ++kt) {
;     __syncthreads();
; #pragma unroll
;     for (int i = 0; i < MI; ++i) *(u32x4*)(smem + woff + i * 4096) = ra[i];
; #pragma unroll
;     for (int i = 0; i < 4; ++i) *(u32x4*)(smem + 32768 + woff + i * 4096) = rb[i];
;     __syncthreads();
;     if (kt + 1 < nk) {
; #pragma unroll
;       for (int i = 0; i < MI; ++i) ra[i] = *(const u32x4*)(ap + (size_t)(32 * i) * lda + (kt + 1) * 64);
; #pragma unroll
;       for (int i = 0; i < 4; ++i) rb[i] = *(const u32x4*)(bp + (size_t)(32 * i) * ldb + (kt + 1) * 64);
;     }
;     if (F8) {
;       const int c0 = (g ^ (li & 7)) << 4, c1 = ((4 + g) ^ (li & 7)) << 4;
;       i32x8 wf8[4];
; #pragma unroll
;       for (int j = 0; j < 4; ++j) {
;         const char* rp = smem + wrow + ((j & 1) * 16 + (j >> 1) * 64) * 128;
;         const u32x4 lo = *(const u32x4*)(rp + c0), hi = *(const u32x4*)(rp + c1);
;         wf8[j] = (i32x8){(int)lo.x, (int)lo.y, (int)lo.z, (int)lo.w, (int)hi.x, (int)hi.y, (int)hi.z, (int)hi.w};
;       }
; #pragma unroll
;       for (int i = 0; i < MI; ++i) {
;         const char* rp = smem + xrow + i * 2048;
;         const u32x4 lo = *(const u32x4*)(rp + c0), hi = *(const u32x4*)(rp + c1);
;         const i32x8 xf8 = {(int)lo.x, (int)lo.y, (int)lo.z, (int)lo.w, (int)hi.x, (int)hi.y, (int)hi.z, (int)hi.w};
; #pragma unroll
;         for (int j = 0; j < 4; ++j)
;           acc[i][j] = __builtin_amdgcn_mfma_scale_f32_16x16x128_f8f6f4(wf8[j], xf8, acc[i][j], 0, 0, 0, 0x77777777, 0, 0x7f7f7f7f);
;       }
;     } else {
; #pragma unroll
;     for (int kk = 0; kk < 2; ++kk) {
;       const int ch = ((kk * 4 + g) ^ (li & 7)) << 4;
;       bf16x8 xf[MI], wf[4];
; #pragma unroll
;       for (int j = 0; j < 4; ++j) wf[j] = *(const bf16x8*)(smem + wrow + ((j & 1) * 16 + (j >> 1) * 64) * 128 + ch);
; #pragma unroll
;       for (int i = 0; i < MI; ++i) xf[i] = *(const bf16x8*)(smem + xrow + i * 2048 + ch);
; #pragma unroll
;       for (int i = 0; i < MI; ++i)
; #pragma unroll
;         for (int j = 0; j < 4; ++j) {
	s_barrier
	s_setprio 3
	s_mov_b32 m0, s62
	s_nop 0
	global_load_lds_dwordx4 v252, s[56:57]
	s_add_u32 m0, s62, 0x1000
	s_nop 0
	global_load_lds_dwordx4 v253, s[56:57]
	s_add_u32 s56, s56, 0x20000
	s_addc_u32 s57, s57, 0
	s_add_u32 m0, s62, 0x2000
	s_nop 0
	global_load_lds_dwordx4 v252, s[56:57]
	s_add_u32 m0, s62, 0x3000
	s_nop 0
	global_load_lds_dwordx4 v253, s[56:57]
	s_add_u32 s56, s56, 0x20000
	s_addc_u32 s57, s57, 0
	s_add_u32 m0, s62, 0x4000
	s_nop 0
	global_load_lds_dwordx4 v252, s[56:57]
	s_add_u32 m0, s62, 0x5000
	s_nop 0
	global_load_lds_dwordx4 v253, s[56:57]
	s_add_u32 s56, s56, 0x20000
	s_addc_u32 s57, s57, 0
	s_add_u32 m0, s62, 0x6000
	s_nop 0
	global_load_lds_dwordx4 v252, s[56:57]
	s_add_u32 m0, s62, 0x7000
	s_nop 0
	global_load_lds_dwordx4 v253, s[56:57]
	s_sub_u32 s56, s56, 0x60000
	s_subb_u32 s57, s57, 0
	s_add_u32 m0, s62, 0x8000
	s_nop 0
	global_load_lds_dwordx4 v252, s[58:59]
	s_add_u32 m0, s62, 0x9000
	s_nop 0
	global_load_lds_dwordx4 v253, s[58:59]
	s_add_u32 s58, s58, 0x20000
	s_addc_u32 s59, s59, 0
	s_add_u32 m0, s62, 0xa000
	s_nop 0
	global_load_lds_dwordx4 v252, s[58:59]
	s_add_u32 m0, s62, 0xb000
	s_nop 0
	global_load_lds_dwordx4 v253, s[58:59]
	s_sub_u32 s58, s58, 0x20000
	s_subb_u32 s59, s59, 0
	s_waitcnt vmcnt(0)
	s_setprio 0
	s_barrier
	ds_read_b128 v[148:151], v215 offset:32768
	ds_read_b128 v[152:155], v215 offset:34816
	ds_read_b128 v[156:159], v215 offset:40960
	ds_read_b128 v[160:163], v215 offset:43008
	ds_read_b128 v[164:167], v213
	ds_read_b128 v[168:171], v213 offset:2048
	ds_read_b128 v[172:175], v213 offset:4096
	ds_read_b128 v[176:179], v213 offset:6144
	ds_read_b128 v[180:183], v213 offset:8192
	ds_read_b128 v[184:187], v213 offset:10240
	ds_read_b128 v[188:191], v213 offset:12288
	ds_read_b128 v[192:195], v213 offset:14336
	s_waitcnt lgkmcnt(7)
	v_mfma_f32_16x16x32_bf16 v[132:135], v[156:159], v[164:167], v[132:135]
	s_lshl_b64 s[0:1], s[0:1], 2
	s_add_u32 s0, s16, s0
	s_addc_u32 s1, s17, s1
	v_mfma_f32_16x16x32_bf16 v[140:143], v[148:151], v[164:167], v[140:143]
	s_lshl_b32 s6, s22, 2
	s_add_u32 s0, s0, s6
	s_addc_u32 s1, s1, 0
	v_mfma_f32_16x16x32_bf16 v[136:139], v[152:155], v[164:167], v[136:139]
	s_add_i32 s21, s21, s78
	s_add_i32 s20, s20, s71
	s_add_i32 s19, s19, s76
	v_mfma_f32_16x16x32_bf16 v[124:127], v[160:163], v[164:167], v[124:127]
	s_cmpk_gt_i32 s21, 0x1ff
	s_waitcnt lgkmcnt(6)
	v_mfma_f32_16x16x32_bf16 v[108:111], v[148:151], v[168:171], v[108:111]
	v_mfma_f32_16x16x32_bf16 v[104:107], v[152:155], v[168:171], v[104:107]
	v_mfma_f32_16x16x32_bf16 v[96:99], v[156:159], v[168:171], v[96:99]
	v_mfma_f32_16x16x32_bf16 v[92:95], v[160:163], v[168:171], v[92:95]
	s_waitcnt lgkmcnt(5)
	v_mfma_f32_16x16x32_bf16 v[88:91], v[148:151], v[172:175], v[88:91]
	v_mfma_f32_16x16x32_bf16 v[84:87], v[152:155], v[172:175], v[84:87]
	v_mfma_f32_16x16x32_bf16 v[80:83], v[156:159], v[172:175], v[80:83]
	v_mfma_f32_16x16x32_bf16 v[60:63], v[160:163], v[172:175], v[60:63]
	s_waitcnt lgkmcnt(4)
	v_mfma_f32_16x16x32_bf16 v[56:59], v[148:151], v[176:179], v[56:59]
	v_mfma_f32_16x16x32_bf16 v[52:55], v[152:155], v[176:179], v[52:55]
	v_mfma_f32_16x16x32_bf16 v[48:51], v[156:159], v[176:179], v[48:51]
	v_mfma_f32_16x16x32_bf16 v[44:47], v[160:163], v[176:179], v[44:47]
	s_waitcnt lgkmcnt(3)
	v_mfma_f32_16x16x32_bf16 v[40:43], v[148:151], v[180:183], v[40:43]
	v_mfma_f32_16x16x32_bf16 v[36:39], v[152:155], v[180:183], v[36:39]
	v_mfma_f32_16x16x32_bf16 v[32:35], v[156:159], v[180:183], v[32:35]
	v_mfma_f32_16x16x32_bf16 v[28:31], v[160:163], v[180:183], v[28:31]
	s_waitcnt lgkmcnt(2)
	v_mfma_f32_16x16x32_bf16 v[24:27], v[148:151], v[184:187], v[24:27]
	v_mfma_f32_16x16x32_bf16 v[20:23], v[152:155], v[184:187], v[20:23]
	v_mfma_f32_16x16x32_bf16 v[164:167], v[156:159], v[184:187], v[68:71]
	v_mfma_f32_16x16x32_bf16 v[168:171], v[160:163], v[184:187], v[64:67]
	s_waitcnt lgkmcnt(1)
	v_mfma_f32_16x16x32_bf16 v[172:175], v[148:151], v[188:191], v[72:75]
	v_mfma_f32_16x16x32_bf16 v[176:179], v[152:155], v[188:191], v[76:79]
	v_mfma_f32_16x16x32_bf16 v[180:183], v[156:159], v[188:191], v[128:131]
	v_mfma_f32_16x16x32_bf16 v[184:187], v[160:163], v[188:191], v[120:123]
	s_waitcnt lgkmcnt(0)
	v_mfma_f32_16x16x32_bf16 v[148:151], v[148:151], v[192:195], v[116:119]
	v_mfma_f32_16x16x32_bf16 v[152:155], v[152:155], v[192:195], v[112:115]
	v_mfma_f32_16x16x32_bf16 v[156:159], v[156:159], v[192:195], v[100:103]
	v_mfma_f32_16x16x32_bf16 v[144:147], v[160:163], v[192:195], v[144:147]
	ds_read_b128 v[160:163], v207 offset:32768
	ds_read_b128 v[188:191], v207 offset:34816
	ds_read_b128 v[192:195], v207 offset:40960
	ds_read_b128 v[196:199], v207 offset:43008
	ds_read_b128 v[64:67], v206
	ds_read_b128 v[68:71], v206 offset:2048
	ds_read_b128 v[72:75], v206 offset:4096
	ds_read_b128 v[76:79], v206 offset:6144
	ds_read_b128 v[200:203], v206 offset:8192
	ds_read_b128 v[216:219], v206 offset:10240
	ds_read_b128 v[220:223], v206 offset:12288
	ds_read_b128 v[204:207], v206 offset:14336
	s_waitcnt lgkmcnt(7)
; template <int MI, bool SWAP, bool F8 = false>
; __device__ __forceinline__ void gemm_core(const bf16_t* __restrict__ A, int lda, const bf16_t* __restrict__ B, int ldb,
;                                           int K, char* smem, f32x4 (&acc)[MI][4]) {
;     ...
; #pragma unroll
;     for (int kk = 0; kk < 2; ++kk) {
;       const int ch = ((kk * 4 + g) ^ (li & 7)) << 4;
;       bf16x8 xf[MI], wf[4];
; #pragma unroll
;       for (int j = 0; j < 4; ++j) wf[j] = *(const bf16x8*)(smem + wrow + ((j & 1) * 16 + (j >> 1) * 64) * 128 + ch);
; #pragma unroll
;       for (int i = 0; i < MI; ++i) xf[i] = *(const bf16x8*)(smem + xrow + i * 2048 + ch);
; #pragma unroll
;       for (int i = 0; i < MI; ++i)
; #pragma unroll
;         for (int j = 0; j < 4; ++j) {
;           if (SWAP) acc[i][j] = __builtin_amdgcn_mfma_f32_16x16x32_bf16(xf[i], wf[j], acc[i][j], 0, 0, 0);
;           else acc[i][j] = __builtin_amdgcn_mfma_f32_16x16x32_bf16(wf[j], xf[i], acc[i][j], 0, 0, 0);
;         }
;     }
; template <bool ACCUM, int MI>
; __device__ void gemm_tile_f32(const bf16_t* A, int lda, const bf16_t* B, int ldb, int K, float* C, int ldc, char* smem) {
;     ...
; #pragma unroll
;   for (int i = 0; i < MI; ++i)
; #pragma unroll
;     for (int j = 0; j < 4; ++j) {
;       f32x4* cp = (f32x4*)(C + (size_t)MROW(i) * ldc + NCOL(j));
;       f32x4 v = acc[i][j];
;       if (ACCUM) v += *cp;
;       *cp = v;
;     }
	v_mfma_f32_16x16x32_bf16 v[224:227], v[192:195], v[64:67], v[132:135]
	v_mfma_f32_16x16x32_bf16 v[228:231], v[196:199], v[64:67], v[124:127]
	s_waitcnt lgkmcnt(6)
	v_mfma_f32_16x16x32_bf16 v[128:131], v[160:163], v[68:71], v[108:111]
	v_mfma_f32_16x16x32_bf16 v[124:127], v[188:191], v[68:71], v[104:107]
	s_waitcnt lgkmcnt(5)
	v_mfma_f32_16x16x32_bf16 v[112:115], v[160:163], v[72:75], v[88:91]
	v_mfma_f32_16x16x32_bf16 v[108:111], v[188:191], v[72:75], v[84:87]
	v_mfma_f32_16x16x32_bf16 v[104:107], v[192:195], v[72:75], v[80:83]
	v_mfma_f32_16x16x32_bf16 v[100:103], v[196:199], v[72:75], v[60:63]
	s_waitcnt lgkmcnt(3)
	v_mfma_f32_16x16x32_bf16 v[72:75], v[192:195], v[200:203], v[32:35]
	s_waitcnt lgkmcnt(0)
	v_mfma_f32_16x16x32_bf16 v[32:35], v[160:163], v[204:207], v[148:151]
	v_mfma_f32_16x16x32_bf16 v[60:63], v[188:191], v[216:219], v[20:23]
	v_mfma_f32_16x16x32_bf16 v[20:23], v[196:199], v[204:207], v[144:147]
	v_mfma_f32_16x16x32_bf16 v[140:143], v[160:163], v[64:67], v[140:143]
	v_mfma_f32_16x16x32_bf16 v[136:139], v[188:191], v[64:67], v[136:139]
	v_mfma_f32_16x16x32_bf16 v[120:123], v[192:195], v[68:71], v[96:99]
	v_mfma_f32_16x16x32_bf16 v[116:119], v[196:199], v[68:71], v[92:95]
	v_mfma_f32_16x16x32_bf16 v[96:99], v[160:163], v[76:79], v[56:59]
	v_mfma_f32_16x16x32_bf16 v[92:95], v[188:191], v[76:79], v[52:55]
	v_mfma_f32_16x16x32_bf16 v[88:91], v[192:195], v[76:79], v[48:51]
	v_mfma_f32_16x16x32_bf16 v[84:87], v[196:199], v[76:79], v[44:47]
	v_mfma_f32_16x16x32_bf16 v[80:83], v[160:163], v[200:203], v[40:43]
	v_mfma_f32_16x16x32_bf16 v[76:79], v[188:191], v[200:203], v[36:39]
	v_mfma_f32_16x16x32_bf16 v[68:71], v[196:199], v[200:203], v[28:31]
	v_mfma_f32_16x16x32_bf16 v[64:67], v[160:163], v[216:219], v[24:27]
	v_mfma_f32_16x16x32_bf16 v[56:59], v[192:195], v[216:219], v[164:167]
	v_mfma_f32_16x16x32_bf16 v[52:55], v[196:199], v[216:219], v[168:171]
	v_mfma_f32_16x16x32_bf16 v[48:51], v[160:163], v[220:223], v[172:175]
	v_mfma_f32_16x16x32_bf16 v[44:47], v[188:191], v[220:223], v[176:179]
	v_mfma_f32_16x16x32_bf16 v[40:43], v[192:195], v[220:223], v[180:183]
	v_mfma_f32_16x16x32_bf16 v[36:39], v[196:199], v[220:223], v[184:187]
	v_mfma_f32_16x16x32_bf16 v[28:31], v[188:191], v[204:207], v[152:155]
	v_mfma_f32_16x16x32_bf16 v[24:27], v[192:195], v[204:207], v[156:159]
	s_nop 7
	s_nop 7
	s_nop 7
	global_store_dwordx4 v237, v[140:143], s[98:99]
	global_store_dwordx4 v237, v[136:139], s[98:99] offset:64
	global_store_dwordx4 v237, v[224:227], s[98:99] offset:256
	global_store_dwordx4 v237, v[228:231], s[98:99] offset:320
	v_add_u32_e32 v237, 0x10000, v237
	global_store_dwordx4 v237, v[128:131], s[98:99]
	global_store_dwordx4 v237, v[124:127], s[98:99] offset:64
	global_store_dwordx4 v237, v[120:123], s[98:99] offset:256
	global_store_dwordx4 v237, v[116:119], s[98:99] offset:320
	v_add_u32_e32 v237, 0x10000, v237
	global_store_dwordx4 v237, v[112:115], s[98:99]
	global_store_dwordx4 v237, v[108:111], s[98:99] offset:64
	global_store_dwordx4 v237, v[104:107], s[98:99] offset:256
	global_store_dwordx4 v237, v[100:103], s[98:99] offset:320
	v_add_u32_e32 v237, 0x10000, v237
	global_store_dwordx4 v237, v[96:99], s[98:99]
	global_store_dwordx4 v237, v[92:95], s[98:99] offset:64
	global_store_dwordx4 v237, v[88:91], s[98:99] offset:256
	global_store_dwordx4 v237, v[84:87], s[98:99] offset:320
	v_add_u32_e32 v237, 0x10000, v237
	global_store_dwordx4 v237, v[80:83], s[98:99]
	global_store_dwordx4 v237, v[76:79], s[98:99] offset:64
	global_store_dwordx4 v237, v[72:75], s[98:99] offset:256
	global_store_dwordx4 v237, v[68:71], s[98:99] offset:320
	v_add_u32_e32 v237, 0x10000, v237
	global_store_dwordx4 v237, v[64:67], s[98:99]
	global_store_dwordx4 v237, v[60:63], s[98:99] offset:64
	global_store_dwordx4 v237, v[56:59], s[98:99] offset:256
	global_store_dwordx4 v237, v[52:55], s[98:99] offset:320
	v_add_u32_e32 v237, 0x10000, v237
	global_store_dwordx4 v237, v[48:51], s[98:99]
	global_store_dwordx4 v237, v[44:47], s[98:99] offset:64
	global_store_dwordx4 v237, v[40:43], s[98:99] offset:256
	global_store_dwordx4 v237, v[36:39], s[98:99] offset:320
	v_add_u32_e32 v237, 0x10000, v237
	global_store_dwordx4 v237, v[32:35], s[98:99]
	global_store_dwordx4 v237, v[28:31], s[98:99] offset:64
	global_store_dwordx4 v237, v[24:27], s[98:99] offset:256
	global_store_dwordx4 v237, v[20:23], s[98:99] offset:320
	s_cbranch_scc0 .LBB0_818

; template <int MI, bool SWAP, bool F8 = false>
; __device__ __forceinline__ void gemm_core(const bf16_t* __restrict__ A, int lda, const bf16_t* __restrict__ B, int ldb,
;                                           int K, char* smem, f32x4 (&acc)[MI][4]) {
;     ...
;   for (int kt = 0; kt < nk; ++kt) {
;     __syncthreads();
; #pragma unroll
;     for (int i = 0; i < MI; ++i) *(u32x4*)(smem + woff + i * 4096) = ra[i];
; #pragma unroll
;     for (int i = 0; i < 4; ++i) *(u32x4*)(smem + 32768 + woff + i * 4096) = rb[i];
;     __syncthreads();
;     if (kt + 1 < nk) {
; #pragma unroll
;       for (int i = 0; i < MI; ++i) ra[i] = *(const u32x4*)(ap + (size_t)(32 * i) * lda + (kt + 1) * 64);
; #pragma unroll
;       for (int i = 0; i < 4; ++i) rb[i] = *(const u32x4*)(bp + (size_t)(32 * i) * ldb + (kt + 1) * 64);
;     }
;     if (F8) {
;       const int c0 = (g ^ (li & 7)) << 4, c1 = ((4 + g) ^ (li & 7)) << 4;
;       i32x8 wf8[4];
; #pragma unroll
;       for (int j = 0; j < 4; ++j) {
;         const char* rp = smem + wrow + ((j & 1) * 16 + (j >> 1) * 64) * 128;
;         const u32x4 lo = *(const u32x4*)(rp + c0), hi = *(const u32x4*)(rp + c1);
;         wf8[j] = (i32x8){(int)lo.x, (int)lo.y, (int)lo.z, (int)lo.w, (int)hi.x, (int)hi.y, (int)hi.z, (int)hi.w};
;       }
; #pragma unroll
;       for (int i = 0; i < MI; ++i) {
;         const char* rp = smem + xrow + i * 2048;
;         const u32x4 lo = *(const u32x4*)(rp + c0), hi = *(const u32x4*)(rp + c1);
;         const i32x8 xf8 = {(int)lo.x, (int)lo.y, (int)lo.z, (int)lo.w, (int)hi.x, (int)hi.y, (int)hi.z, (int)hi.w};
; #pragma unroll
;         for (int j = 0; j < 4; ++j)
;           acc[i][j] = __builtin_amdgcn_mfma_scale_f32_16x16x128_f8f6f4(wf8[j], xf8, acc[i][j], 0, 0, 0, 0x77777777, 0, 0x7f7f7f7f);
;       }
.LBB0_944:
	v_add_u32_e32 v222, v215, v218
	v_add_u32_e32 v223, v215, v219
	s_barrier
	s_setprio 3
	s_mov_b32 m0, s62
	s_nop 0
	global_load_lds_dwordx4 v252, s[56:57]
	s_add_u32 m0, s62, 0x1000
	s_nop 0
	global_load_lds_dwordx4 v253, s[56:57]
	s_add_u32 s56, s56, 0x10000
	s_addc_u32 s57, s57, 0
	s_add_u32 m0, s62, 0x2000
	s_nop 0
	global_load_lds_dwordx4 v252, s[56:57]
	s_add_u32 m0, s62, 0x3000
	s_nop 0
	global_load_lds_dwordx4 v253, s[56:57]
	s_add_u32 s56, s56, 0x10000
	s_addc_u32 s57, s57, 0
	s_add_u32 m0, s62, 0x4000
	s_nop 0
	global_load_lds_dwordx4 v252, s[56:57]
	s_add_u32 m0, s62, 0x5000
	s_nop 0
	global_load_lds_dwordx4 v253, s[56:57]
	s_add_u32 s56, s56, 0x10000
	s_addc_u32 s57, s57, 0
	s_add_u32 m0, s62, 0x6000
	s_nop 0
	global_load_lds_dwordx4 v252, s[56:57]
	s_add_u32 m0, s62, 0x7000
	s_nop 0
	global_load_lds_dwordx4 v253, s[56:57]
	s_sub_u32 s56, s56, 0x30000
	s_subb_u32 s57, s57, 0
	s_add_u32 m0, s62, 0x8000
	s_nop 0
	global_load_lds_dwordx4 v252, s[58:59]
	s_add_u32 m0, s62, 0x9000
	s_nop 0
	global_load_lds_dwordx4 v253, s[58:59]
	s_add_u32 s58, s58, 0x10000
	s_addc_u32 s59, s59, 0
	s_add_u32 m0, s62, 0xa000
	s_nop 0
	global_load_lds_dwordx4 v252, s[58:59]
	s_add_u32 m0, s62, 0xb000
	s_nop 0
	global_load_lds_dwordx4 v253, s[58:59]
	s_sub_u32 s58, s58, 0x10000
	s_subb_u32 s59, s59, 0
	v_add_u32_e32 v252, 0x80, v252
	v_add_u32_e32 v253, 0x80, v253
	s_waitcnt vmcnt(0)
	s_setprio 0
	s_barrier
	v_add_u32_e32 v221, v213, v218
	v_add_u32_e32 v220, v213, v219
	ds_read_b128 v[44:47], v222 offset:32768
	ds_read_b128 v[48:51], v223 offset:32768
	ds_read_b128 v[180:183], v221
	ds_read_b128 v[184:187], v220
	ds_read_b128 v[20:23], v222 offset:34816
	ds_read_b128 v[24:27], v223 offset:34816
	ds_read_b128 v[188:191], v221 offset:2048
	ds_read_b128 v[192:195], v220 offset:2048
	ds_read_b128 v[32:35], v223 offset:40960
	ds_read_b128 v[28:31], v222 offset:40960
	ds_read_b128 v[36:39], v222 offset:43008
	ds_read_b128 v[40:43], v223 offset:43008
	s_waitcnt lgkmcnt(8)
	v_mfma_scale_f32_16x16x128_f8f6f4 v[176:179], v[44:51], v[180:187], v[176:179], v239, v238 op_sel_hi:[0,0,0]
	s_waitcnt lgkmcnt(6)
	v_mfma_scale_f32_16x16x128_f8f6f4 v[172:175], v[20:27], v[180:187], v[172:175], v239, v238 op_sel_hi:[0,0,0]
	s_waitcnt lgkmcnt(2)
	v_mfma_scale_f32_16x16x128_f8f6f4 v[168:171], v[28:35], v[180:187], v[168:171], v239, v238 op_sel_hi:[0,0,0]
	s_waitcnt lgkmcnt(0)
	v_mfma_scale_f32_16x16x128_f8f6f4 v[164:167], v[36:43], v[180:187], v[164:167], v239, v238 op_sel_hi:[0,0,0]
	v_mfma_scale_f32_16x16x128_f8f6f4 v[160:163], v[44:51], v[188:195], v[160:163], v239, v238 op_sel_hi:[0,0,0]
	v_mfma_scale_f32_16x16x128_f8f6f4 v[156:159], v[20:27], v[188:195], v[156:159], v239, v238 op_sel_hi:[0,0,0]
	v_mfma_scale_f32_16x16x128_f8f6f4 v[152:155], v[28:35], v[188:195], v[152:155], v239, v238 op_sel_hi:[0,0,0]
	v_mfma_scale_f32_16x16x128_f8f6f4 v[148:151], v[36:43], v[188:195], v[148:151], v239, v238 op_sel_hi:[0,0,0]
	ds_read_b128 v[184:187], v220 offset:4096
	ds_read_b128 v[180:183], v221 offset:4096
	ds_read_b128 v[188:191], v221 offset:6144
	ds_read_b128 v[192:195], v220 offset:6144
	s_waitcnt lgkmcnt(2)
	v_mfma_scale_f32_16x16x128_f8f6f4 v[144:147], v[44:51], v[180:187], v[144:147], v239, v238 op_sel_hi:[0,0,0]
	v_mfma_scale_f32_16x16x128_f8f6f4 v[140:143], v[20:27], v[180:187], v[140:143], v239, v238 op_sel_hi:[0,0,0]
	v_mfma_scale_f32_16x16x128_f8f6f4 v[136:139], v[28:35], v[180:187], v[136:139], v239, v238 op_sel_hi:[0,0,0]
	v_mfma_scale_f32_16x16x128_f8f6f4 v[132:135], v[36:43], v[180:187], v[132:135], v239, v238 op_sel_hi:[0,0,0]
	s_waitcnt lgkmcnt(0)
	v_mfma_scale_f32_16x16x128_f8f6f4 v[128:131], v[44:51], v[188:195], v[128:131], v239, v238 op_sel_hi:[0,0,0]
	v_mfma_scale_f32_16x16x128_f8f6f4 v[124:127], v[20:27], v[188:195], v[124:127], v239, v238 op_sel_hi:[0,0,0]
	v_mfma_scale_f32_16x16x128_f8f6f4 v[120:123], v[28:35], v[188:195], v[120:123], v239, v238 op_sel_hi:[0,0,0]
	v_mfma_scale_f32_16x16x128_f8f6f4 v[116:119], v[36:43], v[188:195], v[116:119], v239, v238 op_sel_hi:[0,0,0]
	ds_read_b128 v[184:187], v220 offset:8192
	ds_read_b128 v[180:183], v221 offset:8192
	ds_read_b128 v[188:191], v221 offset:10240
	ds_read_b128 v[192:195], v220 offset:10240
	s_waitcnt lgkmcnt(0)
	v_mfma_scale_f32_16x16x128_f8f6f4 v[96:99], v[44:51], v[188:195], v[96:99], v239, v238 op_sel_hi:[0,0,0]
	v_mfma_scale_f32_16x16x128_f8f6f4 v[92:95], v[20:27], v[188:195], v[92:95], v239, v238 op_sel_hi:[0,0,0]
	v_mfma_scale_f32_16x16x128_f8f6f4 v[88:91], v[28:35], v[188:195], v[88:91], v239, v238 op_sel_hi:[0,0,0]
	v_mfma_scale_f32_16x16x128_f8f6f4 v[84:87], v[36:43], v[188:195], v[84:87], v239, v238 op_sel_hi:[0,0,0]
	v_mfma_scale_f32_16x16x128_f8f6f4 v[112:115], v[44:51], v[180:187], v[112:115], v239, v238 op_sel_hi:[0,0,0]
	v_mfma_scale_f32_16x16x128_f8f6f4 v[108:111], v[20:27], v[180:187], v[108:111], v239, v238 op_sel_hi:[0,0,0]
	v_mfma_scale_f32_16x16x128_f8f6f4 v[104:107], v[28:35], v[180:187], v[104:107], v239, v238 op_sel_hi:[0,0,0]
	v_mfma_scale_f32_16x16x128_f8f6f4 v[100:103], v[36:43], v[180:187], v[100:103], v239, v238 op_sel_hi:[0,0,0]
	ds_read_b128 v[180:183], v221 offset:12288
	ds_read_b128 v[184:187], v220 offset:12288
	ds_read_b128 v[224:227], v221 offset:14336
	ds_read_b128 v[228:231], v220 offset:14336
	s_waitcnt lgkmcnt(2)
	v_mfma_scale_f32_16x16x128_f8f6f4 v[80:83], v[44:51], v[180:187], v[80:83], v239, v238 op_sel_hi:[0,0,0]
	v_mfma_scale_f32_16x16x128_f8f6f4 v[76:79], v[20:27], v[180:187], v[76:79], v239, v238 op_sel_hi:[0,0,0]
	v_mfma_scale_f32_16x16x128_f8f6f4 v[72:75], v[28:35], v[180:187], v[72:75], v239, v238 op_sel_hi:[0,0,0]
	v_mfma_scale_f32_16x16x128_f8f6f4 v[68:71], v[36:43], v[180:187], v[68:71], v239, v238 op_sel_hi:[0,0,0]
	s_waitcnt lgkmcnt(0)
	v_mfma_scale_f32_16x16x128_f8f6f4 v[64:67], v[44:51], v[224:231], v[64:67], v239, v238 op_sel_hi:[0,0,0]
	v_mfma_scale_f32_16x16x128_f8f6f4 v[60:63], v[20:27], v[224:231], v[60:63], v239, v238 op_sel_hi:[0,0,0]
	v_mfma_scale_f32_16x16x128_f8f6f4 v[56:59], v[28:35], v[224:231], v[56:59], v239, v238 op_sel_hi:[0,0,0]
	v_mfma_scale_f32_16x16x128_f8f6f4 v[52:55], v[36:43], v[224:231], v[52:55], v239, v238 op_sel_hi:[0,0,0]
	s_add_u32 s8, s8, 0x80
	s_addc_u32 s9, s9, 0
	s_cmpk_lg_i32 s8, 0x380
	s_cbranch_scc1 .LBB0_944
; template <int MI, bool SWAP, bool F8 = false>
; __device__ __forceinline__ void gemm_core(const bf16_t* __restrict__ A, int lda, const bf16_t* __restrict__ B, int ldb,
;                                           int K, char* smem, f32x4 (&acc)[MI][4]) {
;     ...
;     if (F8) {
;       const int c0 = (g ^ (li & 7)) << 4, c1 = ((4 + g) ^ (li & 7)) << 4;
;       i32x8 wf8[4];
; #pragma unroll
;       for (int j = 0; j < 4; ++j) {
;         const char* rp = smem + wrow + ((j & 1) * 16 + (j >> 1) * 64) * 128;
;         const u32x4 lo = *(const u32x4*)(rp + c0), hi = *(const u32x4*)(rp + c1);
;         wf8[j] = (i32x8){(int)lo.x, (int)lo.y, (int)lo.z, (int)lo.w, (int)hi.x, (int)hi.y, (int)hi.z, (int)hi.w};
;       }
; #pragma unroll
;       for (int i = 0; i < MI; ++i) {
;         const char* rp = smem + xrow + i * 2048;
;         const u32x4 lo = *(const u32x4*)(rp + c0), hi = *(const u32x4*)(rp + c1);
;         const i32x8 xf8 = {(int)lo.x, (int)lo.y, (int)lo.z, (int)lo.w, (int)hi.x, (int)hi.y, (int)hi.z, (int)hi.w};
; #pragma unroll
;         for (int j = 0; j < 4; ++j)
;           acc[i][j] = __builtin_amdgcn_mfma_scale_f32_16x16x128_f8f6f4(wf8[j], xf8, acc[i][j], 0, 0, 0, 0x77777777, 0, 0x7f7f7f7f);
;       }
	s_barrier
	s_setprio 3
	s_mov_b32 m0, s62
	s_nop 0
	global_load_lds_dwordx4 v252, s[56:57]
	s_add_u32 m0, s62, 0x1000
	s_nop 0
	global_load_lds_dwordx4 v253, s[56:57]
	s_add_u32 s56, s56, 0x10000
	s_addc_u32 s57, s57, 0
	s_add_u32 m0, s62, 0x2000
	s_nop 0
	global_load_lds_dwordx4 v252, s[56:57]
	s_add_u32 m0, s62, 0x3000
	s_nop 0
	global_load_lds_dwordx4 v253, s[56:57]
	s_add_u32 s56, s56, 0x10000
	s_addc_u32 s57, s57, 0
	s_add_u32 m0, s62, 0x4000
	s_nop 0
	global_load_lds_dwordx4 v252, s[56:57]
	s_add_u32 m0, s62, 0x5000
	s_nop 0
	global_load_lds_dwordx4 v253, s[56:57]
	s_add_u32 s56, s56, 0x10000
	s_addc_u32 s57, s57, 0
	s_add_u32 m0, s62, 0x6000
	s_nop 0
	global_load_lds_dwordx4 v252, s[56:57]
	s_add_u32 m0, s62, 0x7000
	s_nop 0
	global_load_lds_dwordx4 v253, s[56:57]
	s_sub_u32 s56, s56, 0x30000
	s_subb_u32 s57, s57, 0
	s_add_u32 m0, s62, 0x8000
	s_nop 0
	global_load_lds_dwordx4 v252, s[58:59]
	s_add_u32 m0, s62, 0x9000
	s_nop 0
	global_load_lds_dwordx4 v253, s[58:59]
	s_add_u32 s58, s58, 0x10000
	s_addc_u32 s59, s59, 0
	s_add_u32 m0, s62, 0xa000
	s_nop 0
	global_load_lds_dwordx4 v252, s[58:59]
	s_add_u32 m0, s62, 0xb000
	s_nop 0
	global_load_lds_dwordx4 v253, s[58:59]
	s_sub_u32 s58, s58, 0x10000
	s_subb_u32 s59, s59, 0
	s_waitcnt vmcnt(0)
	s_setprio 0
	s_barrier
	v_bfe_u32 v12, v208, 4, 1
	v_mul_u32_u24_e32 v12, 24, v12
	v_mov_b32_e32 v13, 0
	ds_read_b128 v[20:23], v222 offset:32768
	ds_read_b128 v[24:27], v223 offset:32768
	ds_read_b128 v[28:31], v222 offset:34816
	ds_read_b128 v[32:35], v223 offset:34816
	ds_read_b128 v[36:39], v222 offset:40960
	ds_read_b128 v[40:43], v223 offset:40960
	ds_read_b128 v[44:47], v222 offset:43008
	ds_read_b128 v[48:51], v223 offset:43008
	ds_read_b128 v[180:183], v221
	ds_read_b128 v[184:187], v220
	s_waitcnt lgkmcnt(0)
	v_mfma_scale_f32_16x16x128_f8f6f4 v[176:179], v[20:27], v[180:187], v[176:179], v239, v238 op_sel_hi:[0,0,0]
	s_lshl_b64 s[6:7], s[6:7], 20
	s_add_u32 s6, s42, s6
	s_addc_u32 s7, s43, s7
	s_lshl_b32 s8, s19, 1
	s_add_u32 s6, s6, s8
	s_addc_u32 s7, s7, 0
	s_add_i32 s18, s18, s78
	v_mfma_scale_f32_16x16x128_f8f6f4 v[172:175], v[28:35], v[180:187], v[172:175], v239, v238 op_sel_hi:[0,0,0]
	s_add_i32 s15, s15, s71
	s_add_i32 s14, s14, s76
	s_cmpk_gt_i32 s18, 0x3ff
	v_mfma_scale_f32_16x16x128_f8f6f4 v[168:171], v[36:43], v[180:187], v[168:171], v239, v238 op_sel_hi:[0,0,0]
	v_mfma_scale_f32_16x16x128_f8f6f4 v[164:167], v[44:51], v[180:187], v[164:167], v239, v238 op_sel_hi:[0,0,0]
	ds_read_b128 v[180:183], v221 offset:2048
	ds_read_b128 v[184:187], v220 offset:2048
	s_waitcnt lgkmcnt(0)
	v_mfma_scale_f32_16x16x128_f8f6f4 v[160:163], v[20:27], v[180:187], v[160:163], v239, v238 op_sel_hi:[0,0,0]
	v_mfma_scale_f32_16x16x128_f8f6f4 v[156:159], v[28:35], v[180:187], v[156:159], v239, v238 op_sel_hi:[0,0,0]
	v_mfma_scale_f32_16x16x128_f8f6f4 v[152:155], v[36:43], v[180:187], v[152:155], v239, v238 op_sel_hi:[0,0,0]
	v_mfma_scale_f32_16x16x128_f8f6f4 v[148:151], v[44:51], v[180:187], v[148:151], v239, v238 op_sel_hi:[0,0,0]
	ds_read_b128 v[180:183], v221 offset:4096
	ds_read_b128 v[184:187], v220 offset:4096
	s_waitcnt lgkmcnt(0)
	v_mfma_scale_f32_16x16x128_f8f6f4 v[144:147], v[20:27], v[180:187], v[144:147], v239, v238 op_sel_hi:[0,0,0]
	v_mfma_scale_f32_16x16x128_f8f6f4 v[140:143], v[28:35], v[180:187], v[140:143], v239, v238 op_sel_hi:[0,0,0]
	v_mfma_scale_f32_16x16x128_f8f6f4 v[136:139], v[36:43], v[180:187], v[136:139], v239, v238 op_sel_hi:[0,0,0]
	v_mfma_scale_f32_16x16x128_f8f6f4 v[132:135], v[44:51], v[180:187], v[132:135], v239, v238 op_sel_hi:[0,0,0]
	ds_read_b128 v[180:183], v221 offset:6144
	ds_read_b128 v[184:187], v220 offset:6144
	s_waitcnt lgkmcnt(0)
	v_mfma_scale_f32_16x16x128_f8f6f4 v[128:131], v[20:27], v[180:187], v[128:131], v239, v238 op_sel_hi:[0,0,0]
	v_mfma_scale_f32_16x16x128_f8f6f4 v[124:127], v[28:35], v[180:187], v[124:127], v239, v238 op_sel_hi:[0,0,0]
	v_mfma_scale_f32_16x16x128_f8f6f4 v[120:123], v[36:43], v[180:187], v[120:123], v239, v238 op_sel_hi:[0,0,0]
	v_mfma_scale_f32_16x16x128_f8f6f4 v[116:119], v[44:51], v[180:187], v[116:119], v239, v238 op_sel_hi:[0,0,0]
	ds_read_b128 v[180:183], v221 offset:8192
	ds_read_b128 v[184:187], v220 offset:8192
	s_waitcnt lgkmcnt(0)
	v_mfma_scale_f32_16x16x128_f8f6f4 v[112:115], v[20:27], v[180:187], v[112:115], v239, v238 op_sel_hi:[0,0,0]
	v_mfma_scale_f32_16x16x128_f8f6f4 v[108:111], v[28:35], v[180:187], v[108:111], v239, v238 op_sel_hi:[0,0,0]
	v_mfma_scale_f32_16x16x128_f8f6f4 v[104:107], v[36:43], v[180:187], v[104:107], v239, v238 op_sel_hi:[0,0,0]
	v_mfma_scale_f32_16x16x128_f8f6f4 v[100:103], v[44:51], v[180:187], v[100:103], v239, v238 op_sel_hi:[0,0,0]
	ds_read_b128 v[180:183], v221 offset:10240
	ds_read_b128 v[184:187], v220 offset:10240
	s_waitcnt lgkmcnt(0)
	v_mfma_scale_f32_16x16x128_f8f6f4 v[96:99], v[20:27], v[180:187], v[96:99], v239, v238 op_sel_hi:[0,0,0]
	v_mfma_scale_f32_16x16x128_f8f6f4 v[92:95], v[28:35], v[180:187], v[92:95], v239, v238 op_sel_hi:[0,0,0]
	v_mfma_scale_f32_16x16x128_f8f6f4 v[88:91], v[36:43], v[180:187], v[88:91], v239, v238 op_sel_hi:[0,0,0]
	v_mfma_scale_f32_16x16x128_f8f6f4 v[84:87], v[44:51], v[180:187], v[84:87], v239, v238 op_sel_hi:[0,0,0]
	ds_read_b128 v[180:183], v221 offset:12288
	ds_read_b128 v[184:187], v220 offset:12288
	s_waitcnt lgkmcnt(0)
	v_mfma_scale_f32_16x16x128_f8f6f4 v[80:83], v[20:27], v[180:187], v[80:83], v239, v238 op_sel_hi:[0,0,0]
	v_mfma_scale_f32_16x16x128_f8f6f4 v[76:79], v[28:35], v[180:187], v[76:79], v239, v238 op_sel_hi:[0,0,0]
	v_mfma_scale_f32_16x16x128_f8f6f4 v[72:75], v[36:43], v[180:187], v[72:75], v239, v238 op_sel_hi:[0,0,0]
	v_mfma_scale_f32_16x16x128_f8f6f4 v[68:71], v[44:51], v[180:187], v[68:71], v239, v238 op_sel_hi:[0,0,0]
	ds_read_b128 v[180:183], v221 offset:14336
	ds_read_b128 v[184:187], v220 offset:14336
	s_waitcnt lgkmcnt(0)
; template <int MI, bool F8 = false>
; __device__ void gemm_tile_bf16(const bf16_t* A, int lda, const bf16_t* B, int ldb, int K, bf16_t* C, int ldc, char* smem) {
;     ...
; #pragma unroll
;   for (int i = 0; i < MI; ++i)
; #pragma unroll
;     for (int j = 0; j < 4; ++j) {
;       u32x2 v;
;       v.x = pk_bf16(acc[i][j][0], acc[i][j][1]);
;       v.y = pk_bf16(acc[i][j][2], acc[i][j][3]);
;       *(u32x2*)(C + (size_t)MROW(i) * ldc + NCOL(j)) = v;
;     }
	v_mfma_scale_f32_16x16x128_f8f6f4 v[64:67], v[20:27], v[180:187], v[64:67], v239, v238 op_sel_hi:[0,0,0]
	v_mfma_scale_f32_16x16x128_f8f6f4 v[24:27], v[36:43], v[180:187], v[56:59], v239, v238 op_sel_hi:[0,0,0]
	v_mov_b32_e32 v36, v208
	s_nop 0
	v_lshrrev_b32_e32 v0, 1, v36
	v_and_b32_e32 v2, 0xffffff8f, v36
	v_and_b32_e32 v0, 32, v0
	v_lshrrev_b32_e32 v3, 2, v36
	v_and_or_b32 v0, v3, 12, v0
	v_ashrrev_i32_e32 v3, 31, v2
	v_mfma_scale_f32_16x16x128_f8f6f4 v[28:31], v[28:35], v[180:187], v[60:63], v239, v238 op_sel_hi:[0,0,0]
	v_lshlrev_b64 v[32:33], 12, v[2:3]
	v_lshl_add_u64 v[32:33], s[6:7], 0, v[32:33]
	v_lshlrev_b32_e32 v0, 1, v0
	v_cvt_pk_bf16_f32 v4, v176, v177
	v_cvt_pk_bf16_f32 v5, v178, v179
	v_lshl_add_u64 v[32:33], v[32:33], 0, v[0:1]
	v_cvt_pk_bf16_f32 v6, v172, v173
	v_cvt_pk_bf16_f32 v7, v174, v175
	s_nop 1
	v_permlane16_swap_b32_e32 v4, v6
	v_permlane16_swap_b32_e32 v5, v7
	v_lshl_add_u64 v[14:15], v[32:33], 0, v[12:13]
	global_store_dwordx4 v[14:15], v[4:7], off
	v_cvt_pk_bf16_f32 v8, v168, v169
	v_cvt_pk_bf16_f32 v9, v170, v171
	v_cvt_pk_bf16_f32 v10, v164, v165
	v_cvt_pk_bf16_f32 v11, v166, v167
	s_nop 1
	v_permlane16_swap_b32_e32 v8, v10
	v_permlane16_swap_b32_e32 v9, v11
	v_lshl_add_u64 v[14:15], v[32:33], 0, v[12:13]
	global_store_dwordx4 v[14:15], v[8:11], off offset:128
	v_or_b32_e32 v32, 16, v2
	v_ashrrev_i32_e32 v33, 31, v32
	v_lshlrev_b64 v[32:33], 12, v[32:33]
	v_lshl_add_u64 v[32:33], s[6:7], 0, v[32:33]
	v_cvt_pk_bf16_f32 v4, v160, v161
	v_cvt_pk_bf16_f32 v5, v162, v163
	v_lshl_add_u64 v[32:33], v[32:33], 0, v[0:1]
	v_cvt_pk_bf16_f32 v6, v156, v157
	v_cvt_pk_bf16_f32 v7, v158, v159
	s_nop 1
	v_permlane16_swap_b32_e32 v4, v6
	v_permlane16_swap_b32_e32 v5, v7
	v_lshl_add_u64 v[14:15], v[32:33], 0, v[12:13]
	global_store_dwordx4 v[14:15], v[4:7], off
	v_cvt_pk_bf16_f32 v8, v152, v153
	v_cvt_pk_bf16_f32 v9, v154, v155
	v_cvt_pk_bf16_f32 v10, v148, v149
	v_cvt_pk_bf16_f32 v11, v150, v151
	s_nop 1
	v_permlane16_swap_b32_e32 v8, v10
	v_permlane16_swap_b32_e32 v9, v11
	v_lshl_add_u64 v[14:15], v[32:33], 0, v[12:13]
	global_store_dwordx4 v[14:15], v[8:11], off offset:128
	v_or_b32_e32 v32, 32, v2
	v_ashrrev_i32_e32 v33, 31, v32
	v_lshlrev_b64 v[32:33], 12, v[32:33]
	v_lshl_add_u64 v[32:33], s[6:7], 0, v[32:33]
	v_cvt_pk_bf16_f32 v4, v144, v145
	v_cvt_pk_bf16_f32 v5, v146, v147
	v_lshl_add_u64 v[32:33], v[32:33], 0, v[0:1]
	v_cvt_pk_bf16_f32 v6, v140, v141
	v_cvt_pk_bf16_f32 v7, v142, v143
	s_nop 1
	v_permlane16_swap_b32_e32 v4, v6
	v_permlane16_swap_b32_e32 v5, v7
	v_lshl_add_u64 v[14:15], v[32:33], 0, v[12:13]
	global_store_dwordx4 v[14:15], v[4:7], off
	v_cvt_pk_bf16_f32 v8, v136, v137
	v_cvt_pk_bf16_f32 v9, v138, v139
	v_cvt_pk_bf16_f32 v10, v132, v133
	v_cvt_pk_bf16_f32 v11, v134, v135
	s_nop 1
	v_permlane16_swap_b32_e32 v8, v10
	v_permlane16_swap_b32_e32 v9, v11
	v_lshl_add_u64 v[14:15], v[32:33], 0, v[12:13]
	global_store_dwordx4 v[14:15], v[8:11], off offset:128
	v_or_b32_e32 v32, 48, v2
	v_ashrrev_i32_e32 v33, 31, v32
	v_lshlrev_b64 v[32:33], 12, v[32:33]
	v_lshl_add_u64 v[32:33], s[6:7], 0, v[32:33]
	v_cvt_pk_bf16_f32 v4, v128, v129
	v_cvt_pk_bf16_f32 v5, v130, v131
	v_lshl_add_u64 v[32:33], v[32:33], 0, v[0:1]
	v_cvt_pk_bf16_f32 v6, v124, v125
	v_cvt_pk_bf16_f32 v7, v126, v127
	s_nop 1
	v_permlane16_swap_b32_e32 v4, v6
	v_permlane16_swap_b32_e32 v5, v7
	v_lshl_add_u64 v[14:15], v[32:33], 0, v[12:13]
	global_store_dwordx4 v[14:15], v[4:7], off
	v_cvt_pk_bf16_f32 v8, v120, v121
	v_cvt_pk_bf16_f32 v9, v122, v123
	v_cvt_pk_bf16_f32 v10, v116, v117
	v_cvt_pk_bf16_f32 v11, v118, v119
	s_nop 1
	v_permlane16_swap_b32_e32 v8, v10
; template <int MI, bool F8 = false>
; __device__ void gemm_tile_bf16(const bf16_t* A, int lda, const bf16_t* B, int ldb, int K, bf16_t* C, int ldc, char* smem) {
;     ...
; #pragma unroll
;   for (int i = 0; i < MI; ++i)
; #pragma unroll
;     for (int j = 0; j < 4; ++j) {
;       u32x2 v;
;       v.x = pk_bf16(acc[i][j][0], acc[i][j][1]);
;       v.y = pk_bf16(acc[i][j][2], acc[i][j][3]);
;       *(u32x2*)(C + (size_t)MROW(i) * ldc + NCOL(j)) = v;
;     }
	v_permlane16_swap_b32_e32 v9, v11
	v_lshl_add_u64 v[14:15], v[32:33], 0, v[12:13]
	global_store_dwordx4 v[14:15], v[8:11], off offset:128
	v_or_b32_e32 v32, 64, v2
	v_ashrrev_i32_e32 v33, 31, v32
	v_lshlrev_b64 v[32:33], 12, v[32:33]
	v_lshl_add_u64 v[32:33], s[6:7], 0, v[32:33]
	v_cvt_pk_bf16_f32 v4, v112, v113
	v_cvt_pk_bf16_f32 v5, v114, v115
	v_lshl_add_u64 v[32:33], v[32:33], 0, v[0:1]
	v_cvt_pk_bf16_f32 v6, v108, v109
	v_cvt_pk_bf16_f32 v7, v110, v111
	s_nop 1
	v_permlane16_swap_b32_e32 v4, v6
	v_permlane16_swap_b32_e32 v5, v7
	v_lshl_add_u64 v[14:15], v[32:33], 0, v[12:13]
	global_store_dwordx4 v[14:15], v[4:7], off
	v_cvt_pk_bf16_f32 v8, v104, v105
	v_cvt_pk_bf16_f32 v9, v106, v107
	v_cvt_pk_bf16_f32 v10, v100, v101
	v_cvt_pk_bf16_f32 v11, v102, v103
	s_nop 1
	v_permlane16_swap_b32_e32 v8, v10
	v_permlane16_swap_b32_e32 v9, v11
	v_lshl_add_u64 v[14:15], v[32:33], 0, v[12:13]
	global_store_dwordx4 v[14:15], v[8:11], off offset:128
	v_or_b32_e32 v32, 0x50, v2
	v_ashrrev_i32_e32 v33, 31, v32
	v_lshlrev_b64 v[32:33], 12, v[32:33]
	v_lshl_add_u64 v[32:33], s[6:7], 0, v[32:33]
	v_cvt_pk_bf16_f32 v4, v96, v97
	v_cvt_pk_bf16_f32 v5, v98, v99
	v_lshl_add_u64 v[32:33], v[32:33], 0, v[0:1]
	v_or_b32_e32 v2, 0x60, v2
	v_cvt_pk_bf16_f32 v6, v92, v93
	v_cvt_pk_bf16_f32 v7, v94, v95
	v_ashrrev_i32_e32 v3, 31, v2
	s_nop 1
	v_permlane16_swap_b32_e32 v4, v6
	v_permlane16_swap_b32_e32 v5, v7
	v_lshl_add_u64 v[14:15], v[32:33], 0, v[12:13]
	global_store_dwordx4 v[14:15], v[4:7], off
	v_cvt_pk_bf16_f32 v8, v88, v89
	v_cvt_pk_bf16_f32 v9, v90, v91
	v_lshlrev_b64 v[2:3], 12, v[2:3]
	v_cvt_pk_bf16_f32 v10, v84, v85
	v_cvt_pk_bf16_f32 v11, v86, v87
	v_lshl_add_u64 v[2:3], s[6:7], 0, v[2:3]
	v_mfma_scale_f32_16x16x128_f8f6f4 v[20:23], v[44:51], v[180:187], v[52:55], v239, v238 op_sel_hi:[0,0,0]
	s_nop 1
	v_permlane16_swap_b32_e32 v8, v10
	v_permlane16_swap_b32_e32 v9, v11
	v_lshl_add_u64 v[14:15], v[32:33], 0, v[12:13]
	global_store_dwordx4 v[14:15], v[8:11], off offset:128
	v_cvt_pk_bf16_f32 v4, v80, v81
	v_cvt_pk_bf16_f32 v5, v82, v83
	v_lshl_add_u64 v[2:3], v[2:3], 0, v[0:1]
	v_cvt_pk_bf16_f32 v6, v76, v77
	v_cvt_pk_bf16_f32 v7, v78, v79
	s_nop 1
	v_permlane16_swap_b32_e32 v4, v6
	v_permlane16_swap_b32_e32 v5, v7
	v_lshl_add_u64 v[14:15], v[2:3], 0, v[12:13]
	global_store_dwordx4 v[14:15], v[4:7], off
	v_cvt_pk_bf16_f32 v8, v72, v73
	v_cvt_pk_bf16_f32 v9, v74, v75
	v_cvt_pk_bf16_f32 v10, v68, v69
	v_cvt_pk_bf16_f32 v11, v70, v71
	s_nop 1
	v_permlane16_swap_b32_e32 v8, v10
	v_permlane16_swap_b32_e32 v9, v11
	v_lshl_add_u64 v[14:15], v[2:3], 0, v[12:13]
	global_store_dwordx4 v[14:15], v[8:11], off offset:128
	v_or_b32_e32 v2, 0x70, v36
	v_ashrrev_i32_e32 v3, 31, v2
	v_lshlrev_b64 v[2:3], 12, v[2:3]
	v_lshl_add_u64 v[2:3], s[6:7], 0, v[2:3]
	v_cvt_pk_bf16_f32 v32, v64, v65
	v_cvt_pk_bf16_f32 v33, v66, v67
	v_lshl_add_u64 v[2:3], v[2:3], 0, v[0:1]
	v_cvt_pk_bf16_f32 v28, v28, v29
	v_cvt_pk_bf16_f32 v29, v30, v31
	v_cvt_pk_bf16_f32 v24, v24, v25
	v_cvt_pk_bf16_f32 v25, v26, v27
	v_cvt_pk_bf16_f32 v20, v20, v21
	v_cvt_pk_bf16_f32 v21, v22, v23
	v_mov_b64_e32 v[4:5], v[32:33]
	v_mov_b64_e32 v[6:7], v[28:29]
	s_nop 1
	v_permlane16_swap_b32_e32 v4, v6
	v_permlane16_swap_b32_e32 v5, v7
	v_lshl_add_u64 v[14:15], v[2:3], 0, v[12:13]
	global_store_dwordx4 v[14:15], v[4:7], off
	v_mov_b64_e32 v[8:9], v[24:25]
	v_mov_b64_e32 v[10:11], v[20:21]
	s_nop 1
	v_permlane16_swap_b32_e32 v8, v10
	v_permlane16_swap_b32_e32 v9, v11
	v_lshl_add_u64 v[14:15], v[2:3], 0, v[12:13]
	global_store_dwordx4 v[14:15], v[8:11], off offset:128
	s_cbranch_scc0 .LBB0_943
